# hout+pool sample rows also LDS-staged; ConvFFN epilogue G stores: address+data pulled through ds_bpermute so each lane quad writes one row (same bytes to same addresses)
# speedup vs baseline: 1.0843x; 1.0157x over previous
; #define LAS __attribute__((address_space(3)))
; __global__ void __launch_bounds__(512, 2) fwd_megakernel(Args a_unused) {
;     extern __shared__ __attribute__((aligned(16))) unsigned char lds_raw[];
;     LAS unsigned char* lds = (LAS unsigned char*)lds_raw;
;     const int G = gridDim.x, bx = blockIdx.x;
;     volatile LAS unsigned* xst = (volatile LAS unsigned*)(lds + LDS_BYTES - 64);
;     if (threadIdx.x < 2) xst[threadIdx.x] = 0u;
;     __syncthreads();
;     XcdBarrier xbar;
;     {   KAP a0 = (KAP)__builtin_amdgcn_kernarg_segment_ptr();
;         if (a0->ph_lo == 0x7fffffff) cg::this_grid().sync();
;         xbar = xcd_barrier_post((unsigned*)a0->ws, xst); }
_Z14fwd_megakernel4Args:
	s_load_dword s56, s[0:1], 0xb0
	s_mov_b64 s[16:17], s[0:1]
	s_add_u32 s0, s16, 0xb0
	s_addc_u32 s1, s17, 0
	v_and_b32_e32 v208, 0x3ff, v0
	v_and_b32_e32 v244, 63, v208
	v_and_b32_e32 v245, 3, v244
	v_lshrrev_b32_e32 v244, 2, v244
	v_lshl_add_u32 v244, v245, 4, v244
	v_lshlrev_b32_e32 v244, 2, v244
	v_writelane_b32 v235, s0, 0
	v_cmp_gt_u32_e32 vcc, 2, v208
	s_nop 0
	v_writelane_b32 v235, s1, 1
	s_and_saveexec_b64 s[4:5], vcc
	v_lshl_add_u32 v1, v208, 2, 0
	v_add_u32_e32 v1, 0x23fc0, v1
	v_mov_b32_e32 v2, 0
	ds_write_b32 v1, v2
	s_or_b64 exec, exec, s[4:5]
	s_waitcnt lgkmcnt(0)
	s_barrier
	s_load_dword s0, s[16:17], 0xa8
	s_waitcnt lgkmcnt(0)
	s_cmp_lg_u32 s0, 0x7fffffff
	s_cbranch_scc1 .LBB0_14
	v_lshrrev_b32_e32 v1, 20, v0
	v_lshrrev_b32_e32 v0, 10, v0
	v_or_b32_e32 v0, v0, v1
	s_movk_i32 s0, 0x3ff
	v_and_or_b32 v0, v0, s0, v208
	v_cmp_eq_u32_e32 vcc, 0, v0
	s_barrier
	s_and_saveexec_b64 s[4:5], vcc
	s_cbranch_execz .LBB0_13
	v_readlane_b32 s0, v235, 0
	v_readlane_b32 s1, v235, 1
	buffer_wbl2 sc1
	s_load_dwordx2 s[6:7], s[0:1], 0x58
	s_mov_b64 s[8:9], exec
	v_mbcnt_lo_u32_b32 v0, s8, 0
	v_mbcnt_hi_u32_b32 v0, s9, v0
	v_cmp_eq_u32_e32 vcc, 0, v0
	s_waitcnt lgkmcnt(0)
	s_load_dword s0, s[6:7], 0x28
	s_and_saveexec_b64 s[10:11], vcc
	s_cbranch_execz .LBB0_6
	s_bcnt1_i32_b64 s1, s[8:9]
	v_mov_b32_e32 v1, 0
	v_mov_b32_e32 v2, s1
	global_atomic_add v1, v1, v2, s[6:7] offset:32 sc0

; #define LAS __attribute__((address_space(3)))
; template <class F>
; __device__ __forceinline__ void small_gemm_ks(LAS unsigned char* lds, const bf16_t* A, int lda, const bf16_t* Bt, int ldb, int K, int N, int a_grp_cols, int bx, int G, int tid, const F& f) {
;     const int lane = tid & 63, w = __builtin_amdgcn_readfirstlane(tid >> 6), c = lane & 15, g = lane >> 4, kh = w >> 2, wq = w & 3, wm = wq >> 1, wn = wq & 1;
;     const int ntn = N / 64, ntiles = (MS / 32) * ntn, KH = K / 2;
;     for (int t = bx; t < ntiles; t += G) {
;         const int row0 = MP + (t / ntn) * 32 + wm * 16, n0 = (t % ntn) * 64 + wn * 32;
;         const bf16_t* ap = A + (size_t)(row0 + c) * lda + (n0 >> 8) * a_grp_cols + kh * KH + 8 * g;
;         const bf16_t* bp = Bt + (size_t)(n0 + c) * ldb + kh * KH + 8 * g;
.LBB0_345:
	s_or_b64 exec, exec, s[6:7]
	v_readlane_b32 s0, v235, 5
	s_waitcnt vmcnt(0)
	v_mov_b32_e32 v28, v208
	v_readlane_b32 s1, v235, 6
	s_waitcnt lgkmcnt(0)
	s_barrier
	s_load_dwordx2 s[4:5], s[0:1], 0xa0
	s_load_dwordx2 s[12:13], s[0:1], 0x50
	v_and_b32_e32 v29, 15, v28
	s_waitcnt lgkmcnt(0)
	s_add_u32 s14, s4, 0x9900000
	s_addc_u32 s15, s5, 0
	s_add_u32 s0, s4, 0x100000
	s_addc_u32 s1, s5, 0
	s_add_u32 s16, s4, 0x5700000
	s_addc_u32 s17, s5, 0
	s_cmpk_lt_i32 s2, 0x100
	v_readfirstlane_b32 s4, v28
	s_cselect_b64 s[90:91], -1, 0
	s_cmpk_gt_i32 s2, 0xff
	s_cbranch_scc1 .LBB0_368
	v_readfirstlane_b32 s68, v208
	v_and_b32_e32 v86, 63, v208
	s_nop 3
	s_lshr_b32 s68, s68, 6
	v_lshrrev_b32_e32 v87, 3, v86
	v_and_b32_e32 v88, 7, v86
	v_and_b32_e32 v94, 6, v87
	v_xor_b32_e32 v88, v88, v94
	s_mov_b32 s69, 2048
	v_mul_lo_u32 v90, v87, s69
	v_lshl_add_u32 v90, v88, 4, v90
	v_mov_b32_e32 v91, 0
	s_mov_b32 s69, 512
	v_mul_lo_u32 v92, v87, s69
	v_lshl_add_u32 v92, v88, 4, v92
	v_mov_b32_e32 v93, 0
	v_and_b32_e32 v87, 15, v86
	v_lshrrev_b32_e32 v88, 4, v86
	v_lshrrev_b32_e32 v89, 3, v87
	v_lshlrev_b32_e32 v89, 10, v89
	v_and_b32_e32 v94, 6, v87
	v_xor_b32_e32 v94, v88, v94
	v_lshl_add_u32 v89, v94, 4, v89
	v_and_b32_e32 v94, 7, v87
	v_lshl_add_u32 v89, v94, 7, v89
	s_lshr_b32 s70, s68, 2
	s_bfe_u32 s71, s68, 0x10001
	s_and_b32 s72, s68, 1
	s_lshl_b32 s73, s70, 12
	s_lshl_b32 s74, s71, 11
	s_add_i32 s73, s73, s74
	s_lshl_b32 s74, s70, 13
	s_lshl_b32 s75, s72, 12
	s_add_i32 s74, s74, s75
	s_add_i32 s74, s74, 0x2000
	v_add_u32_e32 v96, s73, v89
	v_add_u32_e32 v101, s74, v89
	v_add_u32_e32 v97, s73, v89
	v_add_u32_e32 v102, s74, v89
	v_add_u32_e32 v98, s73, v89
	v_add_u32_e32 v103, s74, v89
	v_add_u32_e32 v97, 24576, v97
	v_add_u32_e32 v102, 24576, v102
	v_add_u32_e32 v98, 49152, v98
	v_add_u32_e32 v103, 49152, v103
	v_xor_b32_e32 v188, 64, v96
	v_xor_b32_e32 v193, 64, v101
	v_xor_b32_e32 v189, 64, v97
	v_xor_b32_e32 v194, 64, v102
	v_xor_b32_e32 v190, 64, v98
	v_xor_b32_e32 v195, 64, v103
	s_lshl_b32 s75, s71, 4
	v_lshl_add_u32 v106, v88, 2, s75
	v_lshlrev_b32_e32 v106, 11, v106
	s_lshl_b32 s75, s72, 5
	v_add_u32_e32 v107, s75, v87
	v_lshl_add_u32 v106, v107, 1, v106
	v_lshlrev_b32_e32 v108, 2, v107
	v_mov_b32_e32 v107, 0
	s_and_b32 s75, s68, 3
	s_lshl_b32 s75, s75, 11
	v_lshl_add_u32 v109, v86, 4, s75
	s_lshl_b32 s76, s68, 10
	s_lshl_b32 s77, s68, 11
	s_add_i32 s77, s77, 0x2000
	s_mov_b32 s78, 0x80
	s_mov_b32 s79, 0
	s_and_b32 s80, s68, 3
	v_readlane_b32 s92, v235, 5
	v_readlane_b32 s93, v235, 6
	s_nop 3
	s_load_dwordx2 s[92:93], s[92:93], 0x50
	s_mov_b32 s81, s2
; #define LAS __attribute__((address_space(3)))
; #define LDS_SYNC() do { asm volatile("s_waitcnt lgkmcnt(0)" ::: "memory"); __builtin_amdgcn_s_barrier(); asm volatile("" ::: "memory"); } while (0)
; template <class F>
; __device__ __forceinline__ void small_gemm_ks(LAS unsigned char* lds, const bf16_t* A, int lda, const bf16_t* Bt, int ldb, int K, int N, int a_grp_cols, int bx, int G, int tid, const F& f) {
;     ...
;     for (int t = bx; t < ntiles; t += G) {
;         const int row0 = MP + (t / ntn) * 32 + wm * 16, n0 = (t % ntn) * 64 + wn * 32;
;         const bf16_t* ap = A + (size_t)(row0 + c) * lda + (n0 >> 8) * a_grp_cols + kh * KH + 8 * g;
;         const bf16_t* bp = Bt + (size_t)(n0 + c) * ldb + kh * KH + 8 * g;
;         f32x4 acc[2] = {(f32x4){0.f, 0.f, 0.f, 0.f}, (f32x4){0.f, 0.f, 0.f, 0.f}};
; #pragma unroll 8
;         for (int k0 = 0; k0 < KH; k0 += 32) { const bf16x8 av = *(const bf16x8*)(ap + k0);
; #pragma unroll
;             for (int nt = 0; nt < 2; ++nt) { const bf16x8 bv = *(const bf16x8*)(bp + (size_t)nt * 16 * ldb + k0); acc[nt] = __builtin_amdgcn_mfma_f32_16x16x32_bf16(av, bv, acc[nt], 0, 0, 0); } }
;         if (kh == 1) { *(LAS f32x4*)(lds + ((wq * 2 + 0) * 64 + lane) * 16) = acc[0]; *(LAS f32x4*)(lds + ((wq * 2 + 1) * 64 + lane) * 16) = acc[1]; }
;         LDS_SYNC();
;         if (kh == 0) {
; #pragma unroll
;             for (int nt = 0; nt < 2; ++nt) { const f32x4 o = acc[nt] + *(const LAS f32x4*)(lds + ((wq * 2 + nt) * 64 + lane) * 16);
; #pragma unroll
;                 for (int j = 0; j < 4; ++j) f(row0 + 4 * g + j, n0 + 16 * nt + c, o[j]); }
;         }
;         LDS_SYNC();
;     }
; }
.Lsg_pool_tile:
	s_lshr_b32 s82, s81, 4
	s_and_b32 s83, s81, 15
	s_lshl_b32 s82, s82, 5
	s_add_i32 s82, s82, 0x4000
	s_lshl_b32 s83, s83, 6
	s_lshl_b32 s59, s80, 3
	s_add_i32 s59, s59, s82
	s_mul_i32 s60, s59, 2048
	s_mul_hi_u32 s61, s59, 2048
	s_mul_i32 s62, s70, 256
	s_add_u32 s60, s60, s62
	s_addc_u32 s61, s61, 0
	s_lshr_b32 s62, s83, 8
	s_lshl_b32 s62, s62, 9
	s_add_u32 s60, s60, s62
	s_addc_u32 s61, s61, 0
	s_add_u32 s60, s60, s54
	s_addc_u32 s61, s61, s55
	s_add_u32 s60, s60, 0x9900000
	s_addc_u32 s61, s61, 0
	v_lshl_add_u64 v[110:111], s[60:61], 0, v[90:91]
	s_lshl_b32 s59, s80, 4
	s_add_i32 s59, s59, s83
	s_mul_i32 s60, s59, 512
	s_mul_i32 s62, s70, 256
	s_add_u32 s60, s60, s62
	s_add_u32 s60, s60, s54
	s_addc_u32 s61, s55, 0
	s_add_u32 s60, s60, 0x100000
	s_addc_u32 s61, s61, 0
	v_lshl_add_u64 v[112:113], s[60:61], 0, v[92:93]
	s_add_u32 s60, s60, 4096
	s_addc_u32 s61, s61, 0
	v_lshl_add_u64 v[114:115], s[60:61], 0, v[92:93]
	s_waitcnt vmcnt(0)
	s_lshl_b32 s59, s83, 2
	v_add_u32_e32 v116, s59, v108
	s_waitcnt lgkmcnt(0)
	global_load_dword v117, v116, s[92:93]
	global_load_dword v118, v116, s[92:93] offset:64
	v_mov_b32_e32 v120, 0
	v_mov_b32_e32 v121, 0
	v_mov_b32_e32 v122, 0
	v_mov_b32_e32 v123, 0
	v_mov_b32_e32 v124, 0
	v_mov_b32_e32 v125, 0
	v_mov_b32_e32 v126, 0
	v_mov_b32_e32 v127, 0
	s_add_i32 m0, s76, 0
	s_nop 0
	global_load_lds_dwordx4 v[110:111], off
	v_lshl_add_u64 v[110:111], v[110:111], 0, s[78:79]
	s_add_i32 m0, s77, 0
	s_nop 0
	global_load_lds_dwordx4 v[112:113], off
	v_lshl_add_u64 v[112:113], v[112:113], 0, s[78:79]
	s_add_i32 m0, s77, 1024
	s_nop 0
	global_load_lds_dwordx4 v[114:115], off
	v_lshl_add_u64 v[114:115], v[114:115], 0, s[78:79]
	s_add_i32 m0, s76, 24576
	s_nop 0
	global_load_lds_dwordx4 v[110:111], off
	v_lshl_add_u64 v[110:111], v[110:111], 0, s[78:79]
	s_add_i32 m0, s77, 24576
	s_nop 0
	global_load_lds_dwordx4 v[112:113], off
	v_lshl_add_u64 v[112:113], v[112:113], 0, s[78:79]
	s_add_i32 m0, s77, 25600
	s_nop 0
	global_load_lds_dwordx4 v[114:115], off
	v_lshl_add_u64 v[114:115], v[114:115], 0, s[78:79]
	s_waitcnt vmcnt(3)
	s_barrier
	ds_read_b128 v[128:131], v96
	ds_read_b128 v[136:139], v101 offset:0
	ds_read_b128 v[144:147], v101 offset:2048
	ds_read_b128 v[132:135], v188
	ds_read_b128 v[140:143], v193 offset:0
	ds_read_b128 v[148:151], v193 offset:2048
	s_waitcnt lgkmcnt(3)
	v_mfma_f32_16x16x32_bf16 v[120:123], v[128:131], v[136:139], v[120:123]
	v_mfma_f32_16x16x32_bf16 v[124:127], v[128:131], v[144:147], v[124:127]
	s_waitcnt lgkmcnt(0)
	v_mfma_f32_16x16x32_bf16 v[120:123], v[132:135], v[140:143], v[120:123]
	v_mfma_f32_16x16x32_bf16 v[124:127], v[132:135], v[148:151], v[124:127]
	s_waitcnt vmcnt(0)
	s_barrier
	ds_read_b128 v[152:155], v97
	ds_read_b128 v[160:163], v102 offset:0
	ds_read_b128 v[168:171], v102 offset:2048
	ds_read_b128 v[156:159], v189
	ds_read_b128 v[164:167], v194 offset:0
	ds_read_b128 v[172:175], v194 offset:2048
	s_waitcnt lgkmcnt(3)
	v_mfma_f32_16x16x32_bf16 v[120:123], v[152:155], v[160:163], v[120:123]
	v_mfma_f32_16x16x32_bf16 v[124:127], v[152:155], v[168:171], v[124:127]
	s_waitcnt lgkmcnt(0)
	v_mfma_f32_16x16x32_bf16 v[120:123], v[156:159], v[164:167], v[120:123]
	v_mfma_f32_16x16x32_bf16 v[124:127], v[156:159], v[172:175], v[124:127]
	s_barrier
	s_lshl_b32 s59, s82, 11
	s_lshl_b32 s62, s83, 1
	s_add_i32 s59, s59, s62
	s_add_u32 s60, s54, s59
	s_addc_u32 s61, s55, 0
	s_add_u32 s60, s60, 0x5700000
	s_addc_u32 s61, s61, 0
	v_lshl_add_u64 v[176:177], s[60:61], 0, v[106:107]
	s_mov_b32 s62, 0x1000
	s_mov_b32 s63, 0
	v_lshl_add_u64 v[178:179], v[176:177], 0, s[62:63]
	s_cmp_eq_u32 s70, 0
	s_cbranch_scc1 .Lsg_pool_lo
	s_nop 4
	ds_write_b128 v109, v[120:123]
	ds_write_b128 v109, v[124:127] offset:1024
	s_waitcnt lgkmcnt(0)
	s_barrier
	s_branch .Lsg_pool_done
.Lsg_pool_lo:
	s_barrier
	ds_read_b128 v[180:183], v109
	ds_read_b128 v[184:187], v109 offset:1024
	s_waitcnt vmcnt(0)
	s_waitcnt lgkmcnt(0)
	v_add_f32_e32 v120, v120, v180
	v_add_f32_e32 v121, v121, v181
	v_add_f32_e32 v122, v122, v182
	v_add_f32_e32 v123, v123, v183
	v_add_f32_e32 v124, v124, v184
	v_add_f32_e32 v125, v125, v185
	v_add_f32_e32 v126, v126, v186
	v_add_f32_e32 v127, v127, v187
	v_mul_f32_e32 v120, v120, v117
	v_mul_f32_e32 v121, v121, v117
	v_mul_f32_e32 v122, v122, v117
	v_mul_f32_e32 v123, v123, v117
	v_mul_f32_e32 v124, v124, v118
	v_mul_f32_e32 v125, v125, v118
	v_mul_f32_e32 v126, v126, v118
	v_mul_f32_e32 v127, v127, v118
	v_cvt_pk_bf16_f32 v120, v120, v120
	v_cvt_pk_bf16_f32 v121, v121, v121
	v_cvt_pk_bf16_f32 v122, v122, v122
	v_cvt_pk_bf16_f32 v123, v123, v123
	v_cvt_pk_bf16_f32 v124, v124, v124
	v_cvt_pk_bf16_f32 v125, v125, v125
	v_cvt_pk_bf16_f32 v126, v126, v126
	v_cvt_pk_bf16_f32 v127, v127, v127
	global_store_short v[176:177], v120, off offset:0
	global_store_short v[176:177], v121, off offset:2048
	global_store_short v[178:179], v122, off offset:0
	global_store_short v[178:179], v123, off offset:2048
	global_store_short v[176:177], v124, off offset:32
	global_store_short v[176:177], v125, off offset:2080
	global_store_short v[178:179], v126, off offset:32
	global_store_short v[178:179], v127, off offset:2080
.Lsg_pool_done:
	s_waitcnt lgkmcnt(0)
	s_barrier
	s_add_i32 s81, s81, s56
	s_cmpk_lt_i32 s81, 0x100
	s_cbranch_scc1 .Lsg_pool_tile
.LBB0_368:
	v_cndmask_b32_e64 v0, 0, 1, s[90:91]
	v_cmp_ne_u32_e64 s[88:89], 1, v0
	s_andn2_b64 vcc, exec, s[90:91]
	v_readfirstlane_b32 s8, v28
	s_cbranch_vccnz .LBB0_374
	s_ashr_i32 s3, s2, 31
	s_lshr_b32 s3, s3, 29
	s_add_i32 s3, s2, s3
	s_and_b32 s4, s3, -8
	s_sub_i32 s4, s2, s4
	s_cmp_gt_i32 s4, -1
	s_cbranch_scc0 .LBB0_371
	s_lshl_b32 s5, s4, 5
	s_cbranch_execz .LBB0_372
	s_branch .LBB0_373

; __device__ __forceinline__ unsigned pk2(float lo, float hi) { const f32x2 v = {lo, hi}; const bf16x2_t b = __builtin_convertvector(v, bf16x2_t); return __builtin_bit_cast(unsigned, b); }
; template <int N> __device__ __forceinline__ float dpp_ror(float v) { const int i = __builtin_bit_cast(int, v); return __builtin_bit_cast(float, __builtin_amdgcn_update_dpp(i, i, 0x120 + N, 0xF, 0xF, false)); }
;     __device__ __forceinline__ void operator()(const f32x4 (&acc)[2][2][4][2], const pg8::Unit& u, int wr, int wc, int fr, int fq, PG8_LAS unsigned char* xl) const {
;     ...
;                     for (int bj = 0; bj < 2; ++bj) {
;                         const f32x4 cur = acc[ai][bj][m][n]; f32x4 p1, p2;
;                         if (!sample) { const f32x4 prv = (m == 0) ? hb[bj] : acc[ai][bj][m == 0 ? 0 : m - 1][n];
; #pragma unroll
;                             for (int j = 0; j < 4; ++j) { const float s1 = fr == 15 ? prv[j] : cur[j], s2 = fr >= 14 ? prv[j] : cur[j]; p1[j] = dpp_ror<1>(s1); p2[j] = dpp_ror<2>(s2); }
;                         } else { const int t = fr & 3, b = (row - MP) >> 2;
; #pragma unroll
;                             for (int j = 0; j < 4; ++j) { p1[j] = dpp_ror<1>(cur[j]); p2[j] = dpp_ror<2>(cur[j]); }
;                             const f32x4 c1 = *(const f32x4*)(ctx_s + (size_t)(b * 2 + 1) * FF2 + bj * FF + jc0 + 4 * n), c0 = *(const f32x4*)(ctx_s + (size_t)(b * 2) * FF2 + bj * FF + jc0 + 4 * n);
; #pragma unroll
;                             for (int j = 0; j < 4; ++j) { p2[j] = t == 0 ? c0[j] : (t == 1 ? c1[j] : p2[j]); p1[j] = t == 0 ? c1[j] : p1[j]; }
;                         }
;                         cc[bj] = bb[bj] + w0[bj] * p2 + w1[bj] * p1 + w2[bj] * cur;
;                     }
;                     const f32x4 gv = gelu_mul4(cc[0], cc[1]);
;                     u32x2 w; w.x = pk2(gv[0], gv[1]); w.y = pk2(gv[2], gv[3]);
;                     *(u32x2*)(G + (size_t)row * FF + jc0 + 4 * n) = w;
;                     if (!sample && ai == 0 && wr == 0 && m == 0 && fr < 2 && (pm & 7) != 0) {
; #pragma unroll
;                         for (int bj = 0; bj < 2; ++bj) *(f32x4*)(PH + (size_t)(pm * 2 + fr) * FF2 + bj * FF + jc0 + 4 * n) = cc[bj];
.LBB0_565:
	s_and_b32 s73, s42, 7
	s_waitcnt vmcnt(0)
	v_pk_fma_f32 v[160:161], v[114:115], v[170:171], v[118:119]
	v_pk_fma_f32 v[162:163], v[112:113], v[168:169], v[116:117]
	s_cmp_lg_u32 s73, 0
	v_pk_fma_f32 v[160:161], v[110:111], v[166:167], v[160:161]
	v_pk_fma_f32 v[164:165], v[108:109], v[164:165], v[162:163]
	s_cselect_b64 s[6:7], -1, 0
	s_lshl_b32 s87, s42, 1
	v_pk_fma_f32 v[162:163], v[158:159], v[98:99], v[160:161]
	v_pk_fma_f32 v[160:161], v[156:157], v[96:97], v[164:165]
	v_add_u32_e32 v164, s87, v211
	v_mad_i64_i32 v[168:169], s[34:35], v164, s36, 0
	v_pk_fma_f32 v[164:165], v[106:107], v[178:179], v[122:123]
	v_pk_fma_f32 v[166:167], v[104:105], v[176:177], v[120:121]
	v_pk_fma_f32 v[164:165], v[102:103], v[174:175], v[164:165]
	v_pk_fma_f32 v[170:171], v[100:101], v[172:173], v[166:167]
	v_pk_mul_f32 v[166:167], v[162:163], v[162:163]
	v_pk_mul_f32 v[172:173], v[160:161], v[160:161]
	v_mov_b64_e32 v[174:175], s[82:83]
	v_pk_fma_f32 v[166:167], v[166:167], s[84:85], v[174:175] op_sel_hi:[1,0,0]
	v_pk_fma_f32 v[172:173], v[172:173], s[84:85], v[174:175] op_sel_hi:[1,0,0]
	v_pk_mul_f32 v[166:167], v[162:163], v[166:167]
	v_pk_mul_f32 v[172:173], v[160:161], v[172:173]
	v_exp_f32_e32 v174, v166
	v_exp_f32_e32 v172, v172
	v_exp_f32_e32 v175, v167
	v_exp_f32_e32 v173, v173
	v_pk_fma_f32 v[166:167], v[154:155], v[94:95], v[164:165]
	v_pk_fma_f32 v[164:165], v[152:153], v[92:93], v[170:171]
	v_pk_add_f32 v[170:171], v[174:175], 1.0 op_sel_hi:[1,0]
	v_pk_add_f32 v[172:173], v[172:173], 1.0 op_sel_hi:[1,0]
	v_rcp_f32_e32 v170, v170
	v_rcp_f32_e32 v172, v172
	v_rcp_f32_e32 v171, v171
	v_rcp_f32_e32 v173, v173
	v_pk_mul_f32 v[174:175], v[162:163], v[166:167]
	v_pk_mul_f32 v[176:177], v[160:161], v[164:165]
	v_pk_mul_f32 v[170:171], v[174:175], v[170:171]
	v_pk_mul_f32 v[172:173], v[176:177], v[172:173]
	v_lshl_add_u64 v[168:169], s[50:51], 0, v[168:169]
	v_cvt_pk_bf16_f32 v172, v172, v173
	v_cvt_pk_bf16_f32 v173, v170, v171
	v_mov_b64_e32 v[170:171], s[46:47]
	v_mad_i64_i32 v[170:171], s[34:35], v225, s37, v[170:171]
	s_and_b64 s[34:35], s[66:67], s[96:97]
	s_xor_b64 s[34:35], s[34:35], -1
	s_nor_b64 s[34:35], s[34:35], s[18:19]
	v_lshl_add_u64 v[178:179], v[196:197], 1, v[170:171]
	s_and_b64 s[6:7], s[6:7], s[34:35]
	v_lshl_add_u64 v[176:177], v[196:197], 2, v[168:169]
	ds_bpermute_b32 v236, v244, v178
	ds_bpermute_b32 v237, v244, v179
	ds_bpermute_b32 v238, v244, v172
	ds_bpermute_b32 v239, v244, v173
	s_waitcnt lgkmcnt(0)
	global_store_dwordx2 v[236:237], v[238:239], off
	s_and_saveexec_b64 s[34:35], s[6:7]
	s_cbranch_execz .LBB0_567
	global_store_dwordx4 v[176:177], v[160:163], off
	s_nop 1
	v_add_co_u32_e32 v160, vcc, 0x2000, v176
	s_nop 1
	v_addc_co_u32_e32 v161, vcc, 0, v177, vcc
	global_store_dwordx4 v[160:161], v[164:167], off offset:3072

; __device__ __forceinline__ unsigned pk2(float lo, float hi) { const f32x2 v = {lo, hi}; const bf16x2_t b = __builtin_convertvector(v, bf16x2_t); return __builtin_bit_cast(unsigned, b); }
;     __device__ __forceinline__ void operator()(const f32x4 (&acc)[2][2][4][2], const pg8::Unit& u, int wr, int wc, int fr, int fq, PG8_LAS unsigned char* xl) const {
;     ...
;                     for (int bj = 0; bj < 2; ++bj) {
;                         const f32x4 cur = acc[ai][bj][m][n]; f32x4 p1, p2;
;                         if (!sample) { const f32x4 prv = (m == 0) ? hb[bj] : acc[ai][bj][m == 0 ? 0 : m - 1][n];
; #pragma unroll
;                             for (int j = 0; j < 4; ++j) { const float s1 = fr == 15 ? prv[j] : cur[j], s2 = fr >= 14 ? prv[j] : cur[j]; p1[j] = dpp_ror<1>(s1); p2[j] = dpp_ror<2>(s2); }
;                         } else { const int t = fr & 3, b = (row - MP) >> 2;
; #pragma unroll
;                             for (int j = 0; j < 4; ++j) { p1[j] = dpp_ror<1>(cur[j]); p2[j] = dpp_ror<2>(cur[j]); }
;                             const f32x4 c1 = *(const f32x4*)(ctx_s + (size_t)(b * 2 + 1) * FF2 + bj * FF + jc0 + 4 * n), c0 = *(const f32x4*)(ctx_s + (size_t)(b * 2) * FF2 + bj * FF + jc0 + 4 * n);
; #pragma unroll
;                             for (int j = 0; j < 4; ++j) { p2[j] = t == 0 ? c0[j] : (t == 1 ? c1[j] : p2[j]); p1[j] = t == 0 ? c1[j] : p1[j]; }
;                         }
;                         cc[bj] = bb[bj] + w0[bj] * p2 + w1[bj] * p1 + w2[bj] * cur;
;                     }
;                     const f32x4 gv = gelu_mul4(cc[0], cc[1]);
;                     u32x2 w; w.x = pk2(gv[0], gv[1]); w.y = pk2(gv[2], gv[3]);
;                     *(u32x2*)(G + (size_t)row * FF + jc0 + 4 * n) = w;
;                     if (!sample && ai == 0 && wr == 0 && m == 0 && fr < 2 && (pm & 7) != 0) {
; #pragma unroll
;                         for (int bj = 0; bj < 2; ++bj) *(f32x4*)(PH + (size_t)(pm * 2 + fr) * FF2 + bj * FF + jc0 + 4 * n) = cc[bj];
;                     }
;                     if (sample && (fr & 3) >= 2) { const int b = (row - MP) >> 2, t = fr & 3;
; #pragma unroll
;                         for (int bj = 0; bj < 2; ++bj) *(f32x4*)(nf_s + (size_t)(b * 2 + t - 2) * FF2 + bj * FF + jc0 + 4 * n) = acc[ai][bj][m][n];
.LBB0_577:
	v_pk_fma_f32 v[152:153], v[114:115], v[166:167], v[118:119]
	v_pk_fma_f32 v[154:155], v[112:113], v[164:165], v[116:117]
	v_pk_fma_f32 v[152:153], v[110:111], v[162:163], v[152:153]
	v_pk_fma_f32 v[154:155], v[108:109], v[160:161], v[154:155]
	v_pk_fma_f32 v[152:153], v[150:151], v[98:99], v[152:153]
	v_pk_fma_f32 v[154:155], v[148:149], v[96:97], v[154:155]
	v_pk_fma_f32 v[160:161], v[106:107], v[170:171], v[122:123]
	v_pk_fma_f32 v[162:163], v[104:105], v[168:169], v[120:121]
	v_pk_fma_f32 v[158:159], v[102:103], v[158:159], v[160:161]
	v_pk_fma_f32 v[156:157], v[100:101], v[156:157], v[162:163]
	v_pk_mul_f32 v[160:161], v[152:153], v[152:153]
	v_pk_mul_f32 v[162:163], v[154:155], v[154:155]
	v_mov_b64_e32 v[164:165], s[82:83]
	v_pk_fma_f32 v[160:161], v[160:161], s[84:85], v[164:165] op_sel_hi:[1,0,0]
	v_pk_fma_f32 v[162:163], v[162:163], s[84:85], v[164:165] op_sel_hi:[1,0,0]
	v_pk_mul_f32 v[160:161], v[152:153], v[160:161]
	v_pk_mul_f32 v[162:163], v[154:155], v[162:163]
	v_exp_f32_e32 v160, v160
	v_exp_f32_e32 v162, v162
	v_exp_f32_e32 v161, v161
	v_exp_f32_e32 v163, v163
	v_pk_fma_f32 v[158:159], v[146:147], v[94:95], v[158:159]
	v_pk_fma_f32 v[156:157], v[144:145], v[92:93], v[156:157]
	v_pk_add_f32 v[160:161], v[160:161], 1.0 op_sel_hi:[1,0]
	v_pk_add_f32 v[162:163], v[162:163], 1.0 op_sel_hi:[1,0]
	v_rcp_f32_e32 v160, v160
	v_rcp_f32_e32 v162, v162
	v_rcp_f32_e32 v161, v161
	v_rcp_f32_e32 v163, v163
	v_pk_mul_f32 v[152:153], v[152:153], v[158:159]
	v_pk_mul_f32 v[154:155], v[154:155], v[156:157]
	v_pk_mul_f32 v[152:153], v[152:153], v[160:161]
	v_pk_mul_f32 v[154:155], v[154:155], v[162:163]
	v_or_b32_e32 v166, 16, v225
	v_cvt_pk_bf16_f32 v154, v154, v155
	v_cvt_pk_bf16_f32 v155, v152, v153
	v_mov_b64_e32 v[152:153], s[46:47]
	v_mad_i64_i32 v[152:153], s[78:79], v166, s37, v[152:153]
	v_lshl_add_u64 v[168:169], v[196:197], 1, v[152:153]
	v_add_u32_e32 v170, v226, v215
	ds_bpermute_b32 v236, v244, v168
	ds_bpermute_b32 v237, v244, v169
	ds_bpermute_b32 v238, v244, v154
	ds_bpermute_b32 v239, v244, v155
	s_waitcnt lgkmcnt(0)
	global_store_dwordx2 v[236:237], v[238:239], off
	s_and_saveexec_b64 s[78:79], s[34:35]
	s_cbranch_execz .LBB0_579
	v_mov_b64_e32 v[152:153], s[24:25]
	v_mad_i64_i32 v[152:153], vcc, v170, s36, v[152:153]
	v_lshl_add_u64 v[152:153], v[196:197], 2, v[152:153]
	global_store_dwordx4 v[152:153], v[148:151], off
	v_add_co_u32_e32 v152, vcc, 0x2000, v152
	s_nop 1
	v_addc_co_u32_e32 v153, vcc, 0, v153, vcc
	global_store_dwordx4 v[152:153], v[144:147], off offset:3072

; __device__ __forceinline__ unsigned pk2(float lo, float hi) { const f32x2 v = {lo, hi}; const bf16x2_t b = __builtin_convertvector(v, bf16x2_t); return __builtin_bit_cast(unsigned, b); }
;     __device__ __forceinline__ void operator()(const f32x4 (&acc)[2][2][4][2], const pg8::Unit& u, int wr, int wc, int fr, int fq, PG8_LAS unsigned char* xl) const {
;     ...
;                     for (int bj = 0; bj < 2; ++bj) {
;                         const f32x4 cur = acc[ai][bj][m][n]; f32x4 p1, p2;
;                         if (!sample) { const f32x4 prv = (m == 0) ? hb[bj] : acc[ai][bj][m == 0 ? 0 : m - 1][n];
; #pragma unroll
;                             for (int j = 0; j < 4; ++j) { const float s1 = fr == 15 ? prv[j] : cur[j], s2 = fr >= 14 ? prv[j] : cur[j]; p1[j] = dpp_ror<1>(s1); p2[j] = dpp_ror<2>(s2); }
;                         } else { const int t = fr & 3, b = (row - MP) >> 2;
; #pragma unroll
;                             for (int j = 0; j < 4; ++j) { p1[j] = dpp_ror<1>(cur[j]); p2[j] = dpp_ror<2>(cur[j]); }
;                             const f32x4 c1 = *(const f32x4*)(ctx_s + (size_t)(b * 2 + 1) * FF2 + bj * FF + jc0 + 4 * n), c0 = *(const f32x4*)(ctx_s + (size_t)(b * 2) * FF2 + bj * FF + jc0 + 4 * n);
; #pragma unroll
;                             for (int j = 0; j < 4; ++j) { p2[j] = t == 0 ? c0[j] : (t == 1 ? c1[j] : p2[j]); p1[j] = t == 0 ? c1[j] : p1[j]; }
;                         }
;                         cc[bj] = bb[bj] + w0[bj] * p2 + w1[bj] * p1 + w2[bj] * cur;
;                     }
;                     const f32x4 gv = gelu_mul4(cc[0], cc[1]);
;                     u32x2 w; w.x = pk2(gv[0], gv[1]); w.y = pk2(gv[2], gv[3]);
;                     *(u32x2*)(G + (size_t)row * FF + jc0 + 4 * n) = w;
;                     if (!sample && ai == 0 && wr == 0 && m == 0 && fr < 2 && (pm & 7) != 0) {
; #pragma unroll
;                         for (int bj = 0; bj < 2; ++bj) *(f32x4*)(PH + (size_t)(pm * 2 + fr) * FF2 + bj * FF + jc0 + 4 * n) = cc[bj];
;                     }
;                     if (sample && (fr & 3) >= 2) { const int b = (row - MP) >> 2, t = fr & 3;
; #pragma unroll
;                         for (int bj = 0; bj < 2; ++bj) *(f32x4*)(nf_s + (size_t)(b * 2 + t - 2) * FF2 + bj * FF + jc0 + 4 * n) = acc[ai][bj][m][n];
.LBB0_587:
	v_pk_fma_f32 v[144:145], v[114:115], v[158:159], v[118:119]
	v_pk_fma_f32 v[146:147], v[112:113], v[156:157], v[116:117]
	v_pk_fma_f32 v[144:145], v[110:111], v[154:155], v[144:145]
	v_pk_fma_f32 v[146:147], v[108:109], v[152:153], v[146:147]
	v_pk_fma_f32 v[144:145], v[142:143], v[98:99], v[144:145]
	v_pk_fma_f32 v[146:147], v[140:141], v[96:97], v[146:147]
	v_pk_fma_f32 v[152:153], v[106:107], v[162:163], v[122:123]
	v_pk_fma_f32 v[154:155], v[104:105], v[160:161], v[120:121]
	v_pk_fma_f32 v[150:151], v[102:103], v[150:151], v[152:153]
	v_pk_fma_f32 v[148:149], v[100:101], v[148:149], v[154:155]
	v_pk_mul_f32 v[152:153], v[144:145], v[144:145]
	v_pk_mul_f32 v[154:155], v[146:147], v[146:147]
	v_mov_b64_e32 v[156:157], s[82:83]
	v_pk_fma_f32 v[152:153], v[152:153], s[84:85], v[156:157] op_sel_hi:[1,0,0]
	v_pk_fma_f32 v[154:155], v[154:155], s[84:85], v[156:157] op_sel_hi:[1,0,0]
	v_pk_mul_f32 v[152:153], v[144:145], v[152:153]
	v_pk_mul_f32 v[154:155], v[146:147], v[154:155]
	v_exp_f32_e32 v152, v152
	v_exp_f32_e32 v154, v154
	v_exp_f32_e32 v153, v153
	v_exp_f32_e32 v155, v155
	v_pk_fma_f32 v[150:151], v[138:139], v[94:95], v[150:151]
	v_pk_fma_f32 v[148:149], v[136:137], v[92:93], v[148:149]
	v_pk_add_f32 v[152:153], v[152:153], 1.0 op_sel_hi:[1,0]
	v_pk_add_f32 v[154:155], v[154:155], 1.0 op_sel_hi:[1,0]
	v_rcp_f32_e32 v152, v152
	v_rcp_f32_e32 v154, v154
	v_rcp_f32_e32 v153, v153
	v_rcp_f32_e32 v155, v155
	v_pk_mul_f32 v[144:145], v[144:145], v[150:151]
	v_pk_mul_f32 v[146:147], v[146:147], v[148:149]
	v_pk_mul_f32 v[144:145], v[144:145], v[152:153]
	v_pk_mul_f32 v[146:147], v[146:147], v[154:155]
	v_or_b32_e32 v158, 32, v225
	v_cvt_pk_bf16_f32 v146, v146, v147
	v_cvt_pk_bf16_f32 v147, v144, v145
	v_mov_b64_e32 v[144:145], s[46:47]
	v_mad_i64_i32 v[144:145], s[78:79], v158, s37, v[144:145]
	v_lshl_add_u64 v[160:161], v[196:197], 1, v[144:145]
	v_add_u32_e32 v162, v171, v215
	ds_bpermute_b32 v236, v244, v160
	ds_bpermute_b32 v237, v244, v161
	ds_bpermute_b32 v238, v244, v146
	ds_bpermute_b32 v239, v244, v147
	s_waitcnt lgkmcnt(0)
	global_store_dwordx2 v[236:237], v[238:239], off
	s_and_saveexec_b64 s[78:79], s[34:35]
	s_cbranch_execz .LBB0_589
	v_mov_b64_e32 v[144:145], s[24:25]
	v_mad_i64_i32 v[144:145], vcc, v162, s36, v[144:145]
	v_lshl_add_u64 v[144:145], v[196:197], 2, v[144:145]
	global_store_dwordx4 v[144:145], v[140:143], off
	v_add_co_u32_e32 v144, vcc, 0x2000, v144
	s_nop 1
	v_addc_co_u32_e32 v145, vcc, 0, v145, vcc
	global_store_dwordx4 v[144:145], v[136:139], off offset:3072

; __device__ __forceinline__ unsigned pk2(float lo, float hi) { const f32x2 v = {lo, hi}; const bf16x2_t b = __builtin_convertvector(v, bf16x2_t); return __builtin_bit_cast(unsigned, b); }
;     __device__ __forceinline__ void operator()(const f32x4 (&acc)[2][2][4][2], const pg8::Unit& u, int wr, int wc, int fr, int fq, PG8_LAS unsigned char* xl) const {
;     ...
;                     for (int bj = 0; bj < 2; ++bj) {
;                         const f32x4 cur = acc[ai][bj][m][n]; f32x4 p1, p2;
;                         if (!sample) { const f32x4 prv = (m == 0) ? hb[bj] : acc[ai][bj][m == 0 ? 0 : m - 1][n];
; #pragma unroll
;                             for (int j = 0; j < 4; ++j) { const float s1 = fr == 15 ? prv[j] : cur[j], s2 = fr >= 14 ? prv[j] : cur[j]; p1[j] = dpp_ror<1>(s1); p2[j] = dpp_ror<2>(s2); }
;                         } else { const int t = fr & 3, b = (row - MP) >> 2;
; #pragma unroll
;                             for (int j = 0; j < 4; ++j) { p1[j] = dpp_ror<1>(cur[j]); p2[j] = dpp_ror<2>(cur[j]); }
;                             const f32x4 c1 = *(const f32x4*)(ctx_s + (size_t)(b * 2 + 1) * FF2 + bj * FF + jc0 + 4 * n), c0 = *(const f32x4*)(ctx_s + (size_t)(b * 2) * FF2 + bj * FF + jc0 + 4 * n);
; #pragma unroll
;                             for (int j = 0; j < 4; ++j) { p2[j] = t == 0 ? c0[j] : (t == 1 ? c1[j] : p2[j]); p1[j] = t == 0 ? c1[j] : p1[j]; }
;                         }
;                         cc[bj] = bb[bj] + w0[bj] * p2 + w1[bj] * p1 + w2[bj] * cur;
;                     }
;                     const f32x4 gv = gelu_mul4(cc[0], cc[1]);
;                     u32x2 w; w.x = pk2(gv[0], gv[1]); w.y = pk2(gv[2], gv[3]);
;                     *(u32x2*)(G + (size_t)row * FF + jc0 + 4 * n) = w;
;                     if (!sample && ai == 0 && wr == 0 && m == 0 && fr < 2 && (pm & 7) != 0) {
; #pragma unroll
;                         for (int bj = 0; bj < 2; ++bj) *(f32x4*)(PH + (size_t)(pm * 2 + fr) * FF2 + bj * FF + jc0 + 4 * n) = cc[bj];
;                     }
;                     if (sample && (fr & 3) >= 2) { const int b = (row - MP) >> 2, t = fr & 3;
; #pragma unroll
;                         for (int bj = 0; bj < 2; ++bj) *(f32x4*)(nf_s + (size_t)(b * 2 + t - 2) * FF2 + bj * FF + jc0 + 4 * n) = acc[ai][bj][m][n];
.LBB0_597:
	v_pk_fma_f32 v[136:137], v[114:115], v[150:151], v[118:119]
	v_pk_fma_f32 v[138:139], v[112:113], v[148:149], v[116:117]
	v_pk_fma_f32 v[136:137], v[110:111], v[146:147], v[136:137]
	v_pk_fma_f32 v[138:139], v[108:109], v[144:145], v[138:139]
	v_pk_fma_f32 v[136:137], v[134:135], v[98:99], v[136:137]
	v_pk_fma_f32 v[138:139], v[132:133], v[96:97], v[138:139]
	v_pk_fma_f32 v[144:145], v[106:107], v[154:155], v[122:123]
	v_pk_fma_f32 v[146:147], v[104:105], v[152:153], v[120:121]
	v_pk_fma_f32 v[142:143], v[102:103], v[142:143], v[144:145]
	v_pk_fma_f32 v[140:141], v[100:101], v[140:141], v[146:147]
	v_pk_mul_f32 v[144:145], v[136:137], v[136:137]
	v_pk_mul_f32 v[146:147], v[138:139], v[138:139]
	v_mov_b64_e32 v[148:149], s[82:83]
	v_pk_fma_f32 v[144:145], v[144:145], s[84:85], v[148:149] op_sel_hi:[1,0,0]
	v_pk_fma_f32 v[146:147], v[146:147], s[84:85], v[148:149] op_sel_hi:[1,0,0]
	v_pk_mul_f32 v[144:145], v[136:137], v[144:145]
	v_pk_mul_f32 v[146:147], v[138:139], v[146:147]
	v_exp_f32_e32 v144, v144
	v_exp_f32_e32 v146, v146
	v_exp_f32_e32 v145, v145
	v_exp_f32_e32 v147, v147
	v_pk_fma_f32 v[142:143], v[130:131], v[94:95], v[142:143]
	v_pk_fma_f32 v[140:141], v[128:129], v[92:93], v[140:141]
	v_pk_add_f32 v[144:145], v[144:145], 1.0 op_sel_hi:[1,0]
	v_pk_add_f32 v[146:147], v[146:147], 1.0 op_sel_hi:[1,0]
	v_rcp_f32_e32 v144, v144
	v_rcp_f32_e32 v146, v146
	v_rcp_f32_e32 v145, v145
	v_rcp_f32_e32 v147, v147
	v_pk_mul_f32 v[136:137], v[136:137], v[142:143]
	v_pk_mul_f32 v[138:139], v[138:139], v[140:141]
	v_pk_mul_f32 v[136:137], v[136:137], v[144:145]
	v_pk_mul_f32 v[138:139], v[138:139], v[146:147]
	v_or_b32_e32 v150, 48, v225
	v_cvt_pk_bf16_f32 v138, v138, v139
	v_cvt_pk_bf16_f32 v139, v136, v137
	v_mov_b64_e32 v[136:137], s[46:47]
	v_mad_i64_i32 v[136:137], s[78:79], v150, s37, v[136:137]
	v_lshl_add_u64 v[152:153], v[196:197], 1, v[136:137]
	v_add_u32_e32 v154, v163, v215
	ds_bpermute_b32 v236, v244, v152
	ds_bpermute_b32 v237, v244, v153
	ds_bpermute_b32 v238, v244, v138
	ds_bpermute_b32 v239, v244, v139
	s_waitcnt lgkmcnt(0)
	global_store_dwordx2 v[236:237], v[238:239], off
	s_and_saveexec_b64 s[78:79], s[34:35]
	s_cbranch_execz .LBB0_599
	v_mov_b64_e32 v[136:137], s[24:25]
	v_mad_i64_i32 v[136:137], vcc, v154, s36, v[136:137]
	v_lshl_add_u64 v[136:137], v[196:197], 2, v[136:137]
	global_store_dwordx4 v[136:137], v[132:135], off
	s_nop 1
	v_add_co_u32_e32 v132, vcc, 0x2000, v136
	s_nop 1
	v_addc_co_u32_e32 v133, vcc, 0, v137, vcc
	global_store_dwordx4 v[132:133], v[128:131], off offset:3072

; __device__ __forceinline__ unsigned pk2(float lo, float hi) { const f32x2 v = {lo, hi}; const bf16x2_t b = __builtin_convertvector(v, bf16x2_t); return __builtin_bit_cast(unsigned, b); }
;     __device__ __forceinline__ void operator()(const f32x4 (&acc)[2][2][4][2], const pg8::Unit& u, int wr, int wc, int fr, int fq, PG8_LAS unsigned char* xl) const {
;     ...
;                     for (int bj = 0; bj < 2; ++bj) {
;                         const f32x4 cur = acc[ai][bj][m][n]; f32x4 p1, p2;
;                         if (!sample) { const f32x4 prv = (m == 0) ? hb[bj] : acc[ai][bj][m == 0 ? 0 : m - 1][n];
; #pragma unroll
;                             for (int j = 0; j < 4; ++j) { const float s1 = fr == 15 ? prv[j] : cur[j], s2 = fr >= 14 ? prv[j] : cur[j]; p1[j] = dpp_ror<1>(s1); p2[j] = dpp_ror<2>(s2); }
;                         } else { const int t = fr & 3, b = (row - MP) >> 2;
; #pragma unroll
;                             for (int j = 0; j < 4; ++j) { p1[j] = dpp_ror<1>(cur[j]); p2[j] = dpp_ror<2>(cur[j]); }
;                             const f32x4 c1 = *(const f32x4*)(ctx_s + (size_t)(b * 2 + 1) * FF2 + bj * FF + jc0 + 4 * n), c0 = *(const f32x4*)(ctx_s + (size_t)(b * 2) * FF2 + bj * FF + jc0 + 4 * n);
; #pragma unroll
;                             for (int j = 0; j < 4; ++j) { p2[j] = t == 0 ? c0[j] : (t == 1 ? c1[j] : p2[j]); p1[j] = t == 0 ? c1[j] : p1[j]; }
;                         }
;                         cc[bj] = bb[bj] + w0[bj] * p2 + w1[bj] * p1 + w2[bj] * cur;
;                     }
;                     const f32x4 gv = gelu_mul4(cc[0], cc[1]);
;                     u32x2 w; w.x = pk2(gv[0], gv[1]); w.y = pk2(gv[2], gv[3]);
;                     *(u32x2*)(G + (size_t)row * FF + jc0 + 4 * n) = w;
;                     if (!sample && ai == 0 && wr == 0 && m == 0 && fr < 2 && (pm & 7) != 0) {
; #pragma unroll
;                         for (int bj = 0; bj < 2; ++bj) *(f32x4*)(PH + (size_t)(pm * 2 + fr) * FF2 + bj * FF + jc0 + 4 * n) = cc[bj];
;                     }
;                     if (sample && (fr & 3) >= 2) { const int b = (row - MP) >> 2, t = fr & 3;
; #pragma unroll
;                         for (int bj = 0; bj < 2; ++bj) *(f32x4*)(nf_s + (size_t)(b * 2 + t - 2) * FF2 + bj * FF + jc0 + 4 * n) = acc[ai][bj][m][n];
.LBB0_609:
	s_waitcnt lgkmcnt(0)
	v_pk_fma_f32 v[128:129], v[114:115], v[138:139], v[118:119]
	v_pk_fma_f32 v[130:131], v[112:113], v[136:137], v[116:117]
	v_pk_fma_f32 v[128:129], v[110:111], v[134:135], v[128:129]
	v_pk_fma_f32 v[130:131], v[108:109], v[132:133], v[130:131]
	v_pk_fma_f32 v[128:129], v[126:127], v[98:99], v[128:129]
	v_pk_fma_f32 v[130:131], v[124:125], v[96:97], v[130:131]
	v_pk_fma_f32 v[134:135], v[104:105], v[144:145], v[120:121]
	v_pk_mul_f32 v[136:137], v[128:129], v[128:129]
	v_pk_fma_f32 v[134:135], v[100:101], v[140:141], v[134:135]
	v_pk_mul_f32 v[138:139], v[130:131], v[130:131]
	v_mov_b64_e32 v[140:141], s[82:83]
	v_pk_fma_f32 v[136:137], v[136:137], s[84:85], v[140:141] op_sel_hi:[1,0,0]
	v_pk_fma_f32 v[138:139], v[138:139], s[84:85], v[140:141] op_sel_hi:[1,0,0]
	v_pk_mul_f32 v[136:137], v[128:129], v[136:137]
	v_pk_mul_f32 v[138:139], v[130:131], v[138:139]
	v_exp_f32_e32 v136, v136
	v_exp_f32_e32 v138, v138
	v_exp_f32_e32 v137, v137
	v_exp_f32_e32 v139, v139
	v_pk_fma_f32 v[132:133], v[106:107], v[146:147], v[122:123]
	v_pk_fma_f32 v[134:135], v[88:89], v[92:93], v[134:135]
	v_pk_add_f32 v[136:137], v[136:137], 1.0 op_sel_hi:[1,0]
	v_pk_add_f32 v[138:139], v[138:139], 1.0 op_sel_hi:[1,0]
	v_rcp_f32_e32 v136, v136
	v_rcp_f32_e32 v138, v138
	v_rcp_f32_e32 v137, v137
	v_rcp_f32_e32 v139, v139
	v_pk_fma_f32 v[132:133], v[102:103], v[142:143], v[132:133]
	v_pk_mul_f32 v[130:131], v[130:131], v[134:135]
	v_pk_fma_f32 v[132:133], v[90:91], v[94:95], v[132:133]
	v_pk_mul_f32 v[130:131], v[130:131], v[138:139]
	v_pk_mul_f32 v[128:129], v[128:129], v[132:133]
	v_add_u32_e32 v163, 0x80, v225
	v_pk_mul_f32 v[128:129], v[128:129], v[136:137]
	v_cvt_pk_bf16_f32 v130, v130, v131
	v_cvt_pk_bf16_f32 v131, v128, v129
	v_mov_b64_e32 v[128:129], s[46:47]
	v_mad_i64_i32 v[128:129], s[78:79], v163, s37, v[128:129]
	v_lshl_add_u64 v[144:145], v[196:197], 1, v[128:129]
	v_add_u32_e32 v146, v155, v215
	ds_bpermute_b32 v236, v244, v144
	ds_bpermute_b32 v237, v244, v145
	ds_bpermute_b32 v238, v244, v130
	ds_bpermute_b32 v239, v244, v131
	s_waitcnt lgkmcnt(0)
	global_store_dwordx2 v[236:237], v[238:239], off
	s_and_saveexec_b64 s[78:79], s[34:35]
	s_cbranch_execz .LBB0_611
	v_mov_b64_e32 v[128:129], s[24:25]
	v_mad_i64_i32 v[128:129], vcc, v146, s36, v[128:129]
	v_lshl_add_u64 v[128:129], v[196:197], 2, v[128:129]
	global_store_dwordx4 v[128:129], v[124:127], off
	v_add_co_u32_e32 v128, vcc, 0x2000, v128
	s_nop 1
	v_addc_co_u32_e32 v129, vcc, 0, v129, vcc
	global_store_dwordx4 v[128:129], v[88:91], off offset:3072

; __device__ __forceinline__ unsigned pk2(float lo, float hi) { const f32x2 v = {lo, hi}; const bf16x2_t b = __builtin_convertvector(v, bf16x2_t); return __builtin_bit_cast(unsigned, b); }
;     __device__ __forceinline__ void operator()(const f32x4 (&acc)[2][2][4][2], const pg8::Unit& u, int wr, int wc, int fr, int fq, PG8_LAS unsigned char* xl) const {
;     ...
;                     for (int bj = 0; bj < 2; ++bj) {
;                         const f32x4 cur = acc[ai][bj][m][n]; f32x4 p1, p2;
;                         if (!sample) { const f32x4 prv = (m == 0) ? hb[bj] : acc[ai][bj][m == 0 ? 0 : m - 1][n];
; #pragma unroll
;                             for (int j = 0; j < 4; ++j) { const float s1 = fr == 15 ? prv[j] : cur[j], s2 = fr >= 14 ? prv[j] : cur[j]; p1[j] = dpp_ror<1>(s1); p2[j] = dpp_ror<2>(s2); }
;                         } else { const int t = fr & 3, b = (row - MP) >> 2;
; #pragma unroll
;                             for (int j = 0; j < 4; ++j) { p1[j] = dpp_ror<1>(cur[j]); p2[j] = dpp_ror<2>(cur[j]); }
;                             const f32x4 c1 = *(const f32x4*)(ctx_s + (size_t)(b * 2 + 1) * FF2 + bj * FF + jc0 + 4 * n), c0 = *(const f32x4*)(ctx_s + (size_t)(b * 2) * FF2 + bj * FF + jc0 + 4 * n);
; #pragma unroll
;                             for (int j = 0; j < 4; ++j) { p2[j] = t == 0 ? c0[j] : (t == 1 ? c1[j] : p2[j]); p1[j] = t == 0 ? c1[j] : p1[j]; }
;                         }
;                         cc[bj] = bb[bj] + w0[bj] * p2 + w1[bj] * p1 + w2[bj] * cur;
;                     }
;                     const f32x4 gv = gelu_mul4(cc[0], cc[1]);
;                     u32x2 w; w.x = pk2(gv[0], gv[1]); w.y = pk2(gv[2], gv[3]);
;                     *(u32x2*)(G + (size_t)row * FF + jc0 + 4 * n) = w;
;                     if (!sample && ai == 0 && wr == 0 && m == 0 && fr < 2 && (pm & 7) != 0) {
; #pragma unroll
;                         for (int bj = 0; bj < 2; ++bj) *(f32x4*)(PH + (size_t)(pm * 2 + fr) * FF2 + bj * FF + jc0 + 4 * n) = cc[bj];
;                     }
;                     if (sample && (fr & 3) >= 2) { const int b = (row - MP) >> 2, t = fr & 3;
; #pragma unroll
;                         for (int bj = 0; bj < 2; ++bj) *(f32x4*)(nf_s + (size_t)(b * 2 + t - 2) * FF2 + bj * FF + jc0 + 4 * n) = acc[ai][bj][m][n];
.LBB0_619:
	v_pk_fma_f32 v[88:89], v[114:115], v[134:135], v[118:119]
	v_pk_fma_f32 v[90:91], v[112:113], v[132:133], v[116:117]
	v_pk_fma_f32 v[88:89], v[110:111], v[130:131], v[88:89]
	v_pk_fma_f32 v[90:91], v[108:109], v[128:129], v[90:91]
	v_pk_fma_f32 v[88:89], v[86:87], v[98:99], v[88:89]
	v_pk_fma_f32 v[90:91], v[84:85], v[96:97], v[90:91]
	v_pk_fma_f32 v[128:129], v[106:107], v[138:139], v[122:123]
	v_pk_fma_f32 v[130:131], v[104:105], v[136:137], v[120:121]
	v_pk_fma_f32 v[126:127], v[102:103], v[126:127], v[128:129]
	v_pk_fma_f32 v[124:125], v[100:101], v[124:125], v[130:131]
	v_pk_mul_f32 v[128:129], v[88:89], v[88:89]
	v_pk_mul_f32 v[130:131], v[90:91], v[90:91]
	v_mov_b64_e32 v[132:133], s[82:83]
	v_pk_fma_f32 v[128:129], v[128:129], s[84:85], v[132:133] op_sel_hi:[1,0,0]
	v_pk_fma_f32 v[130:131], v[130:131], s[84:85], v[132:133] op_sel_hi:[1,0,0]
	v_pk_mul_f32 v[128:129], v[88:89], v[128:129]
	v_pk_mul_f32 v[130:131], v[90:91], v[130:131]
	v_exp_f32_e32 v128, v128
	v_exp_f32_e32 v130, v130
	v_exp_f32_e32 v129, v129
	v_exp_f32_e32 v131, v131
	v_pk_fma_f32 v[126:127], v[82:83], v[94:95], v[126:127]
	v_pk_fma_f32 v[124:125], v[80:81], v[92:93], v[124:125]
	v_pk_add_f32 v[128:129], v[128:129], 1.0 op_sel_hi:[1,0]
	v_pk_add_f32 v[130:131], v[130:131], 1.0 op_sel_hi:[1,0]
	v_rcp_f32_e32 v128, v128
	v_rcp_f32_e32 v130, v130
	v_rcp_f32_e32 v129, v129
	v_rcp_f32_e32 v131, v131
	v_pk_mul_f32 v[88:89], v[88:89], v[126:127]
	v_pk_mul_f32 v[90:91], v[90:91], v[124:125]
	v_pk_mul_f32 v[88:89], v[88:89], v[128:129]
	v_pk_mul_f32 v[90:91], v[90:91], v[130:131]
	v_add_u32_e32 v134, 0x90, v225
	v_cvt_pk_bf16_f32 v90, v90, v91
	v_cvt_pk_bf16_f32 v91, v88, v89
	v_mov_b64_e32 v[88:89], s[46:47]
	v_mad_i64_i32 v[88:89], s[78:79], v134, s37, v[88:89]
	v_lshl_add_u64 v[136:137], v[196:197], 1, v[88:89]
	v_add_u32_e32 v138, v147, v215
	ds_bpermute_b32 v236, v244, v136
	ds_bpermute_b32 v237, v244, v137
	ds_bpermute_b32 v238, v244, v90
	ds_bpermute_b32 v239, v244, v91
	s_waitcnt lgkmcnt(0)
	global_store_dwordx2 v[236:237], v[238:239], off
	s_and_saveexec_b64 s[78:79], s[34:35]
	s_cbranch_execz .LBB0_621
	v_mov_b64_e32 v[88:89], s[24:25]
	v_mad_i64_i32 v[88:89], vcc, v138, s36, v[88:89]
	v_lshl_add_u64 v[88:89], v[196:197], 2, v[88:89]
	global_store_dwordx4 v[88:89], v[84:87], off
	v_add_co_u32_e32 v88, vcc, 0x2000, v88
	s_nop 1
	v_addc_co_u32_e32 v89, vcc, 0, v89, vcc
	global_store_dwordx4 v[88:89], v[80:83], off offset:3072

; __device__ __forceinline__ unsigned pk2(float lo, float hi) { const f32x2 v = {lo, hi}; const bf16x2_t b = __builtin_convertvector(v, bf16x2_t); return __builtin_bit_cast(unsigned, b); }
;     __device__ __forceinline__ void operator()(const f32x4 (&acc)[2][2][4][2], const pg8::Unit& u, int wr, int wc, int fr, int fq, PG8_LAS unsigned char* xl) const {
;     ...
;                     for (int bj = 0; bj < 2; ++bj) {
;                         const f32x4 cur = acc[ai][bj][m][n]; f32x4 p1, p2;
;                         if (!sample) { const f32x4 prv = (m == 0) ? hb[bj] : acc[ai][bj][m == 0 ? 0 : m - 1][n];
; #pragma unroll
;                             for (int j = 0; j < 4; ++j) { const float s1 = fr == 15 ? prv[j] : cur[j], s2 = fr >= 14 ? prv[j] : cur[j]; p1[j] = dpp_ror<1>(s1); p2[j] = dpp_ror<2>(s2); }
;                         } else { const int t = fr & 3, b = (row - MP) >> 2;
; #pragma unroll
;                             for (int j = 0; j < 4; ++j) { p1[j] = dpp_ror<1>(cur[j]); p2[j] = dpp_ror<2>(cur[j]); }
;                             const f32x4 c1 = *(const f32x4*)(ctx_s + (size_t)(b * 2 + 1) * FF2 + bj * FF + jc0 + 4 * n), c0 = *(const f32x4*)(ctx_s + (size_t)(b * 2) * FF2 + bj * FF + jc0 + 4 * n);
; #pragma unroll
;                             for (int j = 0; j < 4; ++j) { p2[j] = t == 0 ? c0[j] : (t == 1 ? c1[j] : p2[j]); p1[j] = t == 0 ? c1[j] : p1[j]; }
;                         }
;                         cc[bj] = bb[bj] + w0[bj] * p2 + w1[bj] * p1 + w2[bj] * cur;
;                     }
;                     const f32x4 gv = gelu_mul4(cc[0], cc[1]);
;                     u32x2 w; w.x = pk2(gv[0], gv[1]); w.y = pk2(gv[2], gv[3]);
;                     *(u32x2*)(G + (size_t)row * FF + jc0 + 4 * n) = w;
;                     if (!sample && ai == 0 && wr == 0 && m == 0 && fr < 2 && (pm & 7) != 0) {
; #pragma unroll
;                         for (int bj = 0; bj < 2; ++bj) *(f32x4*)(PH + (size_t)(pm * 2 + fr) * FF2 + bj * FF + jc0 + 4 * n) = cc[bj];
;                     }
;                     if (sample && (fr & 3) >= 2) { const int b = (row - MP) >> 2, t = fr & 3;
; #pragma unroll
;                         for (int bj = 0; bj < 2; ++bj) *(f32x4*)(nf_s + (size_t)(b * 2 + t - 2) * FF2 + bj * FF + jc0 + 4 * n) = acc[ai][bj][m][n];
.LBB0_629:
	v_pk_fma_f32 v[80:81], v[114:115], v[126:127], v[118:119]
	v_pk_fma_f32 v[82:83], v[112:113], v[124:125], v[116:117]
	v_pk_fma_f32 v[80:81], v[110:111], v[90:91], v[80:81]
	v_pk_fma_f32 v[82:83], v[108:109], v[88:89], v[82:83]
	v_pk_fma_f32 v[80:81], v[78:79], v[98:99], v[80:81]
	v_pk_fma_f32 v[82:83], v[76:77], v[96:97], v[82:83]
	v_pk_fma_f32 v[88:89], v[106:107], v[130:131], v[122:123]
	v_pk_fma_f32 v[90:91], v[104:105], v[128:129], v[120:121]
	v_pk_fma_f32 v[86:87], v[102:103], v[86:87], v[88:89]
	v_pk_fma_f32 v[84:85], v[100:101], v[84:85], v[90:91]
	v_pk_mul_f32 v[88:89], v[80:81], v[80:81]
	v_pk_mul_f32 v[90:91], v[82:83], v[82:83]
	v_mov_b64_e32 v[124:125], s[82:83]
	v_pk_fma_f32 v[88:89], v[88:89], s[84:85], v[124:125] op_sel_hi:[1,0,0]
	v_pk_fma_f32 v[90:91], v[90:91], s[84:85], v[124:125] op_sel_hi:[1,0,0]
	v_pk_mul_f32 v[88:89], v[80:81], v[88:89]
	v_pk_mul_f32 v[90:91], v[82:83], v[90:91]
	v_exp_f32_e32 v88, v88
	v_exp_f32_e32 v90, v90
	v_exp_f32_e32 v89, v89
	v_exp_f32_e32 v91, v91
	v_pk_fma_f32 v[86:87], v[74:75], v[94:95], v[86:87]
	v_pk_fma_f32 v[84:85], v[72:73], v[92:93], v[84:85]
	v_pk_add_f32 v[88:89], v[88:89], 1.0 op_sel_hi:[1,0]
	v_pk_add_f32 v[90:91], v[90:91], 1.0 op_sel_hi:[1,0]
	v_rcp_f32_e32 v88, v88
	v_rcp_f32_e32 v90, v90
	v_rcp_f32_e32 v89, v89
	v_rcp_f32_e32 v91, v91
	v_pk_mul_f32 v[80:81], v[80:81], v[86:87]
	v_pk_mul_f32 v[82:83], v[82:83], v[84:85]
	v_pk_mul_f32 v[80:81], v[80:81], v[88:89]
	v_pk_mul_f32 v[82:83], v[82:83], v[90:91]
	v_add_u32_e32 v126, 0xa0, v225
	v_cvt_pk_bf16_f32 v82, v82, v83
	v_cvt_pk_bf16_f32 v83, v80, v81
	v_mov_b64_e32 v[80:81], s[46:47]
	v_mad_i64_i32 v[80:81], s[78:79], v126, s37, v[80:81]
	v_lshl_add_u64 v[128:129], v[196:197], 1, v[80:81]
	v_add_u32_e32 v139, v139, v215
	ds_bpermute_b32 v236, v244, v128
	ds_bpermute_b32 v237, v244, v129
	ds_bpermute_b32 v238, v244, v82
	ds_bpermute_b32 v239, v244, v83
	s_waitcnt lgkmcnt(0)
	global_store_dwordx2 v[236:237], v[238:239], off
	s_and_saveexec_b64 s[78:79], s[34:35]
	s_cbranch_execz .LBB0_631
	v_mov_b64_e32 v[80:81], s[24:25]
	v_mad_i64_i32 v[80:81], vcc, v139, s36, v[80:81]
	v_lshl_add_u64 v[80:81], v[196:197], 2, v[80:81]
	global_store_dwordx4 v[80:81], v[76:79], off
	v_add_co_u32_e32 v80, vcc, 0x2000, v80
	s_nop 1
	v_addc_co_u32_e32 v81, vcc, 0, v81, vcc
	global_store_dwordx4 v[80:81], v[72:75], off offset:3072

; __device__ __forceinline__ unsigned pk2(float lo, float hi) { const f32x2 v = {lo, hi}; const bf16x2_t b = __builtin_convertvector(v, bf16x2_t); return __builtin_bit_cast(unsigned, b); }
;     __device__ __forceinline__ void operator()(const f32x4 (&acc)[2][2][4][2], const pg8::Unit& u, int wr, int wc, int fr, int fq, PG8_LAS unsigned char* xl) const {
;     ...
;                     for (int bj = 0; bj < 2; ++bj) {
;                         const f32x4 cur = acc[ai][bj][m][n]; f32x4 p1, p2;
;                         if (!sample) { const f32x4 prv = (m == 0) ? hb[bj] : acc[ai][bj][m == 0 ? 0 : m - 1][n];
; #pragma unroll
;                             for (int j = 0; j < 4; ++j) { const float s1 = fr == 15 ? prv[j] : cur[j], s2 = fr >= 14 ? prv[j] : cur[j]; p1[j] = dpp_ror<1>(s1); p2[j] = dpp_ror<2>(s2); }
;                         } else { const int t = fr & 3, b = (row - MP) >> 2;
; #pragma unroll
;                             for (int j = 0; j < 4; ++j) { p1[j] = dpp_ror<1>(cur[j]); p2[j] = dpp_ror<2>(cur[j]); }
;                             const f32x4 c1 = *(const f32x4*)(ctx_s + (size_t)(b * 2 + 1) * FF2 + bj * FF + jc0 + 4 * n), c0 = *(const f32x4*)(ctx_s + (size_t)(b * 2) * FF2 + bj * FF + jc0 + 4 * n);
; #pragma unroll
;                             for (int j = 0; j < 4; ++j) { p2[j] = t == 0 ? c0[j] : (t == 1 ? c1[j] : p2[j]); p1[j] = t == 0 ? c1[j] : p1[j]; }
;                         }
;                         cc[bj] = bb[bj] + w0[bj] * p2 + w1[bj] * p1 + w2[bj] * cur;
;                     }
;                     const f32x4 gv = gelu_mul4(cc[0], cc[1]);
;                     u32x2 w; w.x = pk2(gv[0], gv[1]); w.y = pk2(gv[2], gv[3]);
;                     *(u32x2*)(G + (size_t)row * FF + jc0 + 4 * n) = w;
;                     if (!sample && ai == 0 && wr == 0 && m == 0 && fr < 2 && (pm & 7) != 0) {
; #pragma unroll
;                         for (int bj = 0; bj < 2; ++bj) *(f32x4*)(PH + (size_t)(pm * 2 + fr) * FF2 + bj * FF + jc0 + 4 * n) = cc[bj];
;                     }
;                     if (sample && (fr & 3) >= 2) { const int b = (row - MP) >> 2, t = fr & 3;
; #pragma unroll
;                         for (int bj = 0; bj < 2; ++bj) *(f32x4*)(nf_s + (size_t)(b * 2 + t - 2) * FF2 + bj * FF + jc0 + 4 * n) = acc[ai][bj][m][n];
.LBB0_639:
	v_pk_fma_f32 v[72:73], v[114:115], v[86:87], v[118:119]
	v_pk_fma_f32 v[74:75], v[112:113], v[84:85], v[116:117]
	v_pk_fma_f32 v[72:73], v[110:111], v[82:83], v[72:73]
	v_pk_fma_f32 v[74:75], v[108:109], v[80:81], v[74:75]
	v_pk_fma_f32 v[72:73], v[14:15], v[98:99], v[72:73]
	v_pk_fma_f32 v[74:75], v[12:13], v[96:97], v[74:75]
	v_pk_fma_f32 v[80:81], v[106:107], v[90:91], v[122:123]
	v_pk_fma_f32 v[82:83], v[104:105], v[88:89], v[120:121]
	v_pk_fma_f32 v[78:79], v[102:103], v[78:79], v[80:81]
	v_pk_fma_f32 v[76:77], v[100:101], v[76:77], v[82:83]
	v_pk_mul_f32 v[80:81], v[72:73], v[72:73]
	v_pk_mul_f32 v[82:83], v[74:75], v[74:75]
	v_mov_b64_e32 v[84:85], s[82:83]
	v_pk_fma_f32 v[80:81], v[80:81], s[84:85], v[84:85] op_sel_hi:[1,0,0]
	v_pk_fma_f32 v[82:83], v[82:83], s[84:85], v[84:85] op_sel_hi:[1,0,0]
	v_pk_mul_f32 v[80:81], v[72:73], v[80:81]
	v_pk_mul_f32 v[82:83], v[74:75], v[82:83]
	v_exp_f32_e32 v80, v80
	v_exp_f32_e32 v82, v82
	v_exp_f32_e32 v81, v81
	v_exp_f32_e32 v83, v83
	v_pk_fma_f32 v[78:79], v[6:7], v[94:95], v[78:79]
	v_pk_fma_f32 v[76:77], v[4:5], v[92:93], v[76:77]
	v_pk_add_f32 v[80:81], v[80:81], 1.0 op_sel_hi:[1,0]
	v_pk_add_f32 v[82:83], v[82:83], 1.0 op_sel_hi:[1,0]
	v_rcp_f32_e32 v80, v80
	v_rcp_f32_e32 v82, v82
	v_rcp_f32_e32 v81, v81
	v_rcp_f32_e32 v83, v83
	v_pk_mul_f32 v[72:73], v[72:73], v[78:79]
	v_pk_mul_f32 v[74:75], v[74:75], v[76:77]
	v_pk_mul_f32 v[72:73], v[72:73], v[80:81]
	v_pk_mul_f32 v[74:75], v[74:75], v[82:83]
	v_add_u32_e32 v86, 0xb0, v225
	v_cvt_pk_bf16_f32 v74, v74, v75
	v_cvt_pk_bf16_f32 v75, v72, v73
	v_mov_b64_e32 v[72:73], s[46:47]
	v_mad_i64_i32 v[72:73], s[78:79], v86, s37, v[72:73]
	v_lshl_add_u64 v[130:131], v[196:197], 1, v[72:73]
	v_add_u32_e32 v147, v147, v215
	ds_bpermute_b32 v236, v244, v130
	ds_bpermute_b32 v237, v244, v131
	ds_bpermute_b32 v238, v244, v74
	ds_bpermute_b32 v239, v244, v75
	s_waitcnt lgkmcnt(0)
	global_store_dwordx2 v[236:237], v[238:239], off
	s_and_saveexec_b64 s[78:79], s[34:35]
	s_cbranch_execz .LBB0_641
	v_mov_b64_e32 v[72:73], s[24:25]
	v_mad_i64_i32 v[72:73], vcc, v147, s36, v[72:73]
	v_lshl_add_u64 v[72:73], v[196:197], 2, v[72:73]
	global_store_dwordx4 v[72:73], v[12:15], off
	v_add_co_u32_e32 v72, vcc, 0x2000, v72
	s_nop 1
	v_addc_co_u32_e32 v73, vcc, 0, v73, vcc
	global_store_dwordx4 v[72:73], v[4:7], off offset:3072

; __device__ __forceinline__ unsigned pk2(float lo, float hi) { const f32x2 v = {lo, hi}; const bf16x2_t b = __builtin_convertvector(v, bf16x2_t); return __builtin_bit_cast(unsigned, b); }
; template <int N> __device__ __forceinline__ float dpp_ror(float v) { const int i = __builtin_bit_cast(int, v); return __builtin_bit_cast(float, __builtin_amdgcn_update_dpp(i, i, 0x120 + N, 0xF, 0xF, false)); }
;     __device__ __forceinline__ void operator()(const f32x4 (&acc)[2][2][4][2], const pg8::Unit& u, int wr, int wc, int fr, int fq, PG8_LAS unsigned char* xl) const {
;     ...
;                     for (int bj = 0; bj < 2; ++bj) {
;                         const f32x4 cur = acc[ai][bj][m][n]; f32x4 p1, p2;
;                         if (!sample) { const f32x4 prv = (m == 0) ? hb[bj] : acc[ai][bj][m == 0 ? 0 : m - 1][n];
; #pragma unroll
;                             for (int j = 0; j < 4; ++j) { const float s1 = fr == 15 ? prv[j] : cur[j], s2 = fr >= 14 ? prv[j] : cur[j]; p1[j] = dpp_ror<1>(s1); p2[j] = dpp_ror<2>(s2); }
;                         } else { const int t = fr & 3, b = (row - MP) >> 2;
; #pragma unroll
;                             for (int j = 0; j < 4; ++j) { p1[j] = dpp_ror<1>(cur[j]); p2[j] = dpp_ror<2>(cur[j]); }
;                             const f32x4 c1 = *(const f32x4*)(ctx_s + (size_t)(b * 2 + 1) * FF2 + bj * FF + jc0 + 4 * n), c0 = *(const f32x4*)(ctx_s + (size_t)(b * 2) * FF2 + bj * FF + jc0 + 4 * n);
; #pragma unroll
;                             for (int j = 0; j < 4; ++j) { p2[j] = t == 0 ? c0[j] : (t == 1 ? c1[j] : p2[j]); p1[j] = t == 0 ? c1[j] : p1[j]; }
;                         }
;                         cc[bj] = bb[bj] + w0[bj] * p2 + w1[bj] * p1 + w2[bj] * cur;
;                     }
;                     const f32x4 gv = gelu_mul4(cc[0], cc[1]);
;                     u32x2 w; w.x = pk2(gv[0], gv[1]); w.y = pk2(gv[2], gv[3]);
;                     *(u32x2*)(G + (size_t)row * FF + jc0 + 4 * n) = w;
;                     if (!sample && ai == 0 && wr == 0 && m == 0 && fr < 2 && (pm & 7) != 0) {
; #pragma unroll
;                         for (int bj = 0; bj < 2; ++bj) *(f32x4*)(PH + (size_t)(pm * 2 + fr) * FF2 + bj * FF + jc0 + 4 * n) = cc[bj];
.LBB0_651:
	s_waitcnt vmcnt(4) lgkmcnt(0)
	v_pk_fma_f32 v[104:105], v[94:95], v[114:115], v[102:103]
	v_pk_fma_f32 v[106:107], v[92:93], v[112:113], v[100:101]
	v_pk_fma_f32 v[104:105], v[90:91], v[110:111], v[104:105]
	v_pk_fma_f32 v[108:109], v[88:89], v[108:109], v[106:107]
	v_pk_fma_f32 v[106:107], v[70:71], v[82:83], v[104:105]
	v_pk_fma_f32 v[104:105], v[68:69], v[80:81], v[108:109]
	s_waitcnt vmcnt(0)
	v_pk_fma_f32 v[110:111], v[84:85], v[120:121], v[96:97]
	v_pk_mul_f32 v[114:115], v[104:105], v[104:105]
	v_pk_fma_f32 v[112:113], v[76:77], v[116:117], v[110:111]
	v_pk_mul_f32 v[110:111], v[106:107], v[106:107]
	v_mov_b64_e32 v[116:117], s[82:83]
	v_pk_fma_f32 v[110:111], v[110:111], s[84:85], v[116:117] op_sel_hi:[1,0,0]
	v_pk_fma_f32 v[114:115], v[114:115], s[84:85], v[116:117] op_sel_hi:[1,0,0]
	v_pk_mul_f32 v[110:111], v[106:107], v[110:111]
	v_pk_mul_f32 v[114:115], v[104:105], v[114:115]
	v_exp_f32_e32 v116, v110
	v_exp_f32_e32 v114, v114
	v_exp_f32_e32 v117, v111
	v_exp_f32_e32 v115, v115
	v_pk_fma_f32 v[108:109], v[86:87], v[122:123], v[98:99]
	v_pk_add_f32 v[114:115], v[114:115], 1.0 op_sel_hi:[1,0]
	v_pk_fma_f32 v[108:109], v[78:79], v[118:119], v[108:109]
	v_rcp_f32_e32 v114, v114
	v_pk_fma_f32 v[110:111], v[66:67], v[74:75], v[108:109]
	v_pk_fma_f32 v[108:109], v[64:65], v[72:73], v[112:113]
	v_pk_add_f32 v[112:113], v[116:117], 1.0 op_sel_hi:[1,0]
	v_rcp_f32_e32 v115, v115
	v_rcp_f32_e32 v112, v112
	v_rcp_f32_e32 v113, v113
	v_pk_mul_f32 v[116:117], v[106:107], v[110:111]
	v_pk_mul_f32 v[118:119], v[104:105], v[108:109]
	v_pk_mul_f32 v[112:113], v[116:117], v[112:113]
	v_pk_mul_f32 v[114:115], v[118:119], v[114:115]
	s_nop 0
	v_cvt_pk_bf16_f32 v114, v114, v115
	v_cvt_pk_bf16_f32 v115, v112, v113
	ds_bpermute_b32 v236, v244, v178
	ds_bpermute_b32 v237, v244, v179
	ds_bpermute_b32 v238, v244, v114
	ds_bpermute_b32 v239, v244, v115
	s_waitcnt lgkmcnt(0)
	global_store_dwordx2 v[236:237], v[238:239], off offset:8
	s_and_saveexec_b64 s[58:59], s[6:7]
	s_cbranch_execz .LBB0_653
	global_store_dwordx4 v[176:177], v[104:107], off offset:16
	s_nop 1
	v_add_co_u32_e32 v104, vcc, 0x2000, v176
	s_nop 1
	v_addc_co_u32_e32 v105, vcc, 0, v177, vcc
	global_store_dwordx4 v[104:105], v[108:111], off offset:3088
	s_or_b64 exec, exec, s[58:59]
	s_and_saveexec_b64 s[6:7], s[34:35]
	s_cbranch_execz .LBB0_655
	s_branch .LBB0_654

; __device__ __forceinline__ unsigned pk2(float lo, float hi) { const f32x2 v = {lo, hi}; const bf16x2_t b = __builtin_convertvector(v, bf16x2_t); return __builtin_bit_cast(unsigned, b); }
;     __device__ __forceinline__ void operator()(const f32x4 (&acc)[2][2][4][2], const pg8::Unit& u, int wr, int wc, int fr, int fq, PG8_LAS unsigned char* xl) const {
;     ...
;                     for (int bj = 0; bj < 2; ++bj) {
;                         const f32x4 cur = acc[ai][bj][m][n]; f32x4 p1, p2;
;                         if (!sample) { const f32x4 prv = (m == 0) ? hb[bj] : acc[ai][bj][m == 0 ? 0 : m - 1][n];
; #pragma unroll
;                             for (int j = 0; j < 4; ++j) { const float s1 = fr == 15 ? prv[j] : cur[j], s2 = fr >= 14 ? prv[j] : cur[j]; p1[j] = dpp_ror<1>(s1); p2[j] = dpp_ror<2>(s2); }
;                         } else { const int t = fr & 3, b = (row - MP) >> 2;
; #pragma unroll
;                             for (int j = 0; j < 4; ++j) { p1[j] = dpp_ror<1>(cur[j]); p2[j] = dpp_ror<2>(cur[j]); }
;                             const f32x4 c1 = *(const f32x4*)(ctx_s + (size_t)(b * 2 + 1) * FF2 + bj * FF + jc0 + 4 * n), c0 = *(const f32x4*)(ctx_s + (size_t)(b * 2) * FF2 + bj * FF + jc0 + 4 * n);
; #pragma unroll
;                             for (int j = 0; j < 4; ++j) { p2[j] = t == 0 ? c0[j] : (t == 1 ? c1[j] : p2[j]); p1[j] = t == 0 ? c1[j] : p1[j]; }
;                         }
;                         cc[bj] = bb[bj] + w0[bj] * p2 + w1[bj] * p1 + w2[bj] * cur;
;                     }
;                     const f32x4 gv = gelu_mul4(cc[0], cc[1]);
;                     u32x2 w; w.x = pk2(gv[0], gv[1]); w.y = pk2(gv[2], gv[3]);
;                     *(u32x2*)(G + (size_t)row * FF + jc0 + 4 * n) = w;
;                     if (!sample && ai == 0 && wr == 0 && m == 0 && fr < 2 && (pm & 7) != 0) {
; #pragma unroll
;                         for (int bj = 0; bj < 2; ++bj) *(f32x4*)(PH + (size_t)(pm * 2 + fr) * FF2 + bj * FF + jc0 + 4 * n) = cc[bj];
;                     }
;                     if (sample && (fr & 3) >= 2) { const int b = (row - MP) >> 2, t = fr & 3;
; #pragma unroll
;                         for (int bj = 0; bj < 2; ++bj) *(f32x4*)(nf_s + (size_t)(b * 2 + t - 2) * FF2 + bj * FF + jc0 + 4 * n) = acc[ai][bj][m][n];
.LBB0_663:
	v_pk_fma_f32 v[64:65], v[94:95], v[110:111], v[102:103]
	v_pk_fma_f32 v[66:67], v[92:93], v[108:109], v[100:101]
	v_pk_fma_f32 v[64:65], v[90:91], v[106:107], v[64:65]
	v_pk_fma_f32 v[66:67], v[88:89], v[104:105], v[66:67]
	v_pk_fma_f32 v[64:65], v[62:63], v[82:83], v[64:65]
	v_pk_fma_f32 v[66:67], v[60:61], v[80:81], v[66:67]
	v_pk_fma_f32 v[104:105], v[86:87], v[114:115], v[98:99]
	v_pk_fma_f32 v[106:107], v[84:85], v[112:113], v[96:97]
	v_pk_fma_f32 v[70:71], v[78:79], v[70:71], v[104:105]
	v_pk_fma_f32 v[68:69], v[76:77], v[68:69], v[106:107]
	v_pk_mul_f32 v[104:105], v[64:65], v[64:65]
	v_pk_mul_f32 v[106:107], v[66:67], v[66:67]
	v_mov_b64_e32 v[108:109], s[82:83]
	v_pk_fma_f32 v[104:105], v[104:105], s[84:85], v[108:109] op_sel_hi:[1,0,0]
	v_pk_fma_f32 v[106:107], v[106:107], s[84:85], v[108:109] op_sel_hi:[1,0,0]
	v_pk_mul_f32 v[104:105], v[64:65], v[104:105]
	v_pk_mul_f32 v[106:107], v[66:67], v[106:107]
	v_exp_f32_e32 v104, v104
	v_exp_f32_e32 v106, v106
	v_exp_f32_e32 v105, v105
	v_exp_f32_e32 v107, v107
	v_pk_fma_f32 v[70:71], v[58:59], v[74:75], v[70:71]
	v_pk_fma_f32 v[68:69], v[56:57], v[72:73], v[68:69]
	v_pk_add_f32 v[104:105], v[104:105], 1.0 op_sel_hi:[1,0]
	v_pk_add_f32 v[106:107], v[106:107], 1.0 op_sel_hi:[1,0]
	v_rcp_f32_e32 v104, v104
	v_rcp_f32_e32 v106, v106
	v_rcp_f32_e32 v105, v105
	v_rcp_f32_e32 v107, v107
	v_pk_mul_f32 v[64:65], v[64:65], v[70:71]
	v_pk_mul_f32 v[66:67], v[66:67], v[68:69]
	v_pk_mul_f32 v[64:65], v[64:65], v[104:105]
	v_pk_mul_f32 v[66:67], v[66:67], v[106:107]
	s_nop 0
	v_cvt_pk_bf16_f32 v66, v66, v67
	v_cvt_pk_bf16_f32 v67, v64, v65
	ds_bpermute_b32 v236, v244, v168
	ds_bpermute_b32 v237, v244, v169
	ds_bpermute_b32 v238, v244, v66
	ds_bpermute_b32 v239, v244, v67
	s_waitcnt lgkmcnt(0)
	global_store_dwordx2 v[236:237], v[238:239], off offset:8
	s_and_saveexec_b64 s[6:7], s[34:35]
	s_cbranch_execz .LBB0_665
	v_mov_b64_e32 v[64:65], s[24:25]
	v_mad_i64_i32 v[64:65], s[58:59], v170, s36, v[64:65]
	v_lshl_add_u64 v[64:65], v[196:197], 2, v[64:65]
	global_store_dwordx4 v[64:65], v[60:63], off offset:16
	v_add_co_u32_e32 v64, vcc, 0x2000, v64
	s_nop 1
	v_addc_co_u32_e32 v65, vcc, 0, v65, vcc
	global_store_dwordx4 v[64:65], v[56:59], off offset:3088

; __device__ __forceinline__ unsigned pk2(float lo, float hi) { const f32x2 v = {lo, hi}; const bf16x2_t b = __builtin_convertvector(v, bf16x2_t); return __builtin_bit_cast(unsigned, b); }
;     __device__ __forceinline__ void operator()(const f32x4 (&acc)[2][2][4][2], const pg8::Unit& u, int wr, int wc, int fr, int fq, PG8_LAS unsigned char* xl) const {
;     ...
;                     for (int bj = 0; bj < 2; ++bj) {
;                         const f32x4 cur = acc[ai][bj][m][n]; f32x4 p1, p2;
;                         if (!sample) { const f32x4 prv = (m == 0) ? hb[bj] : acc[ai][bj][m == 0 ? 0 : m - 1][n];
; #pragma unroll
;                             for (int j = 0; j < 4; ++j) { const float s1 = fr == 15 ? prv[j] : cur[j], s2 = fr >= 14 ? prv[j] : cur[j]; p1[j] = dpp_ror<1>(s1); p2[j] = dpp_ror<2>(s2); }
;                         } else { const int t = fr & 3, b = (row - MP) >> 2;
; #pragma unroll
;                             for (int j = 0; j < 4; ++j) { p1[j] = dpp_ror<1>(cur[j]); p2[j] = dpp_ror<2>(cur[j]); }
;                             const f32x4 c1 = *(const f32x4*)(ctx_s + (size_t)(b * 2 + 1) * FF2 + bj * FF + jc0 + 4 * n), c0 = *(const f32x4*)(ctx_s + (size_t)(b * 2) * FF2 + bj * FF + jc0 + 4 * n);
; #pragma unroll
;                             for (int j = 0; j < 4; ++j) { p2[j] = t == 0 ? c0[j] : (t == 1 ? c1[j] : p2[j]); p1[j] = t == 0 ? c1[j] : p1[j]; }
;                         }
;                         cc[bj] = bb[bj] + w0[bj] * p2 + w1[bj] * p1 + w2[bj] * cur;
;                     }
;                     const f32x4 gv = gelu_mul4(cc[0], cc[1]);
;                     u32x2 w; w.x = pk2(gv[0], gv[1]); w.y = pk2(gv[2], gv[3]);
;                     *(u32x2*)(G + (size_t)row * FF + jc0 + 4 * n) = w;
;                     if (!sample && ai == 0 && wr == 0 && m == 0 && fr < 2 && (pm & 7) != 0) {
; #pragma unroll
;                         for (int bj = 0; bj < 2; ++bj) *(f32x4*)(PH + (size_t)(pm * 2 + fr) * FF2 + bj * FF + jc0 + 4 * n) = cc[bj];
;                     }
;                     if (sample && (fr & 3) >= 2) { const int b = (row - MP) >> 2, t = fr & 3;
; #pragma unroll
;                         for (int bj = 0; bj < 2; ++bj) *(f32x4*)(nf_s + (size_t)(b * 2 + t - 2) * FF2 + bj * FF + jc0 + 4 * n) = acc[ai][bj][m][n];
.LBB0_673:
	v_pk_fma_f32 v[56:57], v[94:95], v[70:71], v[102:103]
	v_pk_fma_f32 v[58:59], v[92:93], v[68:69], v[100:101]
	v_pk_fma_f32 v[56:57], v[90:91], v[66:67], v[56:57]
	v_pk_fma_f32 v[58:59], v[88:89], v[64:65], v[58:59]
	v_pk_fma_f32 v[56:57], v[54:55], v[82:83], v[56:57]
	v_pk_fma_f32 v[58:59], v[52:53], v[80:81], v[58:59]
	v_pk_fma_f32 v[64:65], v[86:87], v[106:107], v[98:99]
	v_pk_fma_f32 v[66:67], v[84:85], v[104:105], v[96:97]
	v_pk_fma_f32 v[62:63], v[78:79], v[62:63], v[64:65]
	v_pk_fma_f32 v[60:61], v[76:77], v[60:61], v[66:67]
	v_pk_mul_f32 v[64:65], v[56:57], v[56:57]
	v_pk_mul_f32 v[66:67], v[58:59], v[58:59]
	v_mov_b64_e32 v[68:69], s[82:83]
	v_pk_fma_f32 v[64:65], v[64:65], s[84:85], v[68:69] op_sel_hi:[1,0,0]
	v_pk_fma_f32 v[66:67], v[66:67], s[84:85], v[68:69] op_sel_hi:[1,0,0]
	v_pk_mul_f32 v[64:65], v[56:57], v[64:65]
	v_pk_mul_f32 v[66:67], v[58:59], v[66:67]
	v_exp_f32_e32 v64, v64
	v_exp_f32_e32 v66, v66
	v_exp_f32_e32 v65, v65
	v_exp_f32_e32 v67, v67
	v_pk_fma_f32 v[62:63], v[50:51], v[74:75], v[62:63]
	v_pk_fma_f32 v[60:61], v[48:49], v[72:73], v[60:61]
	v_pk_add_f32 v[64:65], v[64:65], 1.0 op_sel_hi:[1,0]
	v_pk_add_f32 v[66:67], v[66:67], 1.0 op_sel_hi:[1,0]
	v_rcp_f32_e32 v64, v64
	v_rcp_f32_e32 v66, v66
	v_rcp_f32_e32 v65, v65
	v_rcp_f32_e32 v67, v67
	v_pk_mul_f32 v[56:57], v[56:57], v[62:63]
	v_pk_mul_f32 v[58:59], v[58:59], v[60:61]
	v_pk_mul_f32 v[56:57], v[56:57], v[64:65]
	v_pk_mul_f32 v[58:59], v[58:59], v[66:67]
	s_nop 0
	v_cvt_pk_bf16_f32 v58, v58, v59
	v_cvt_pk_bf16_f32 v59, v56, v57
	ds_bpermute_b32 v236, v244, v160
	ds_bpermute_b32 v237, v244, v161
	ds_bpermute_b32 v238, v244, v58
	ds_bpermute_b32 v239, v244, v59
	s_waitcnt lgkmcnt(0)
	global_store_dwordx2 v[236:237], v[238:239], off offset:8
	s_and_saveexec_b64 s[6:7], s[34:35]
	s_cbranch_execz .LBB0_675
	v_mov_b64_e32 v[56:57], s[24:25]
	v_mad_i64_i32 v[56:57], s[58:59], v162, s36, v[56:57]
	v_lshl_add_u64 v[56:57], v[196:197], 2, v[56:57]
	global_store_dwordx4 v[56:57], v[52:55], off offset:16
	v_add_co_u32_e32 v56, vcc, 0x2000, v56
	s_nop 1
	v_addc_co_u32_e32 v57, vcc, 0, v57, vcc
	global_store_dwordx4 v[56:57], v[48:51], off offset:3088

; __device__ __forceinline__ unsigned pk2(float lo, float hi) { const f32x2 v = {lo, hi}; const bf16x2_t b = __builtin_convertvector(v, bf16x2_t); return __builtin_bit_cast(unsigned, b); }
;     __device__ __forceinline__ void operator()(const f32x4 (&acc)[2][2][4][2], const pg8::Unit& u, int wr, int wc, int fr, int fq, PG8_LAS unsigned char* xl) const {
;     ...
;                     for (int bj = 0; bj < 2; ++bj) {
;                         const f32x4 cur = acc[ai][bj][m][n]; f32x4 p1, p2;
;                         if (!sample) { const f32x4 prv = (m == 0) ? hb[bj] : acc[ai][bj][m == 0 ? 0 : m - 1][n];
; #pragma unroll
;                             for (int j = 0; j < 4; ++j) { const float s1 = fr == 15 ? prv[j] : cur[j], s2 = fr >= 14 ? prv[j] : cur[j]; p1[j] = dpp_ror<1>(s1); p2[j] = dpp_ror<2>(s2); }
;                         } else { const int t = fr & 3, b = (row - MP) >> 2;
; #pragma unroll
;                             for (int j = 0; j < 4; ++j) { p1[j] = dpp_ror<1>(cur[j]); p2[j] = dpp_ror<2>(cur[j]); }
;                             const f32x4 c1 = *(const f32x4*)(ctx_s + (size_t)(b * 2 + 1) * FF2 + bj * FF + jc0 + 4 * n), c0 = *(const f32x4*)(ctx_s + (size_t)(b * 2) * FF2 + bj * FF + jc0 + 4 * n);
; #pragma unroll
;                             for (int j = 0; j < 4; ++j) { p2[j] = t == 0 ? c0[j] : (t == 1 ? c1[j] : p2[j]); p1[j] = t == 0 ? c1[j] : p1[j]; }
;                         }
;                         cc[bj] = bb[bj] + w0[bj] * p2 + w1[bj] * p1 + w2[bj] * cur;
;                     }
;                     const f32x4 gv = gelu_mul4(cc[0], cc[1]);
;                     u32x2 w; w.x = pk2(gv[0], gv[1]); w.y = pk2(gv[2], gv[3]);
;                     *(u32x2*)(G + (size_t)row * FF + jc0 + 4 * n) = w;
;                     if (!sample && ai == 0 && wr == 0 && m == 0 && fr < 2 && (pm & 7) != 0) {
; #pragma unroll
;                         for (int bj = 0; bj < 2; ++bj) *(f32x4*)(PH + (size_t)(pm * 2 + fr) * FF2 + bj * FF + jc0 + 4 * n) = cc[bj];
;                     }
;                     if (sample && (fr & 3) >= 2) { const int b = (row - MP) >> 2, t = fr & 3;
; #pragma unroll
;                         for (int bj = 0; bj < 2; ++bj) *(f32x4*)(nf_s + (size_t)(b * 2 + t - 2) * FF2 + bj * FF + jc0 + 4 * n) = acc[ai][bj][m][n];
.LBB0_683:
	v_pk_fma_f32 v[48:49], v[94:95], v[62:63], v[102:103]
	v_pk_fma_f32 v[50:51], v[92:93], v[60:61], v[100:101]
	v_pk_fma_f32 v[48:49], v[90:91], v[58:59], v[48:49]
	v_pk_fma_f32 v[50:51], v[88:89], v[56:57], v[50:51]
	v_pk_fma_f32 v[48:49], v[46:47], v[82:83], v[48:49]
	v_pk_fma_f32 v[50:51], v[44:45], v[80:81], v[50:51]
	v_pk_fma_f32 v[56:57], v[86:87], v[66:67], v[98:99]
	v_pk_fma_f32 v[58:59], v[84:85], v[64:65], v[96:97]
	v_pk_fma_f32 v[54:55], v[78:79], v[54:55], v[56:57]
	v_pk_fma_f32 v[52:53], v[76:77], v[52:53], v[58:59]
	v_pk_mul_f32 v[56:57], v[48:49], v[48:49]
	v_pk_mul_f32 v[58:59], v[50:51], v[50:51]
	v_mov_b64_e32 v[60:61], s[82:83]
	v_pk_fma_f32 v[56:57], v[56:57], s[84:85], v[60:61] op_sel_hi:[1,0,0]
	v_pk_fma_f32 v[58:59], v[58:59], s[84:85], v[60:61] op_sel_hi:[1,0,0]
	v_pk_mul_f32 v[56:57], v[48:49], v[56:57]
	v_pk_mul_f32 v[58:59], v[50:51], v[58:59]
	v_exp_f32_e32 v56, v56
	v_exp_f32_e32 v58, v58
	v_exp_f32_e32 v57, v57
	v_exp_f32_e32 v59, v59
	v_pk_fma_f32 v[54:55], v[42:43], v[74:75], v[54:55]
	v_pk_fma_f32 v[52:53], v[40:41], v[72:73], v[52:53]
	v_pk_add_f32 v[56:57], v[56:57], 1.0 op_sel_hi:[1,0]
	v_pk_add_f32 v[58:59], v[58:59], 1.0 op_sel_hi:[1,0]
	v_rcp_f32_e32 v56, v56
	v_rcp_f32_e32 v58, v58
	v_rcp_f32_e32 v57, v57
	v_rcp_f32_e32 v59, v59
	v_pk_mul_f32 v[48:49], v[48:49], v[54:55]
	v_pk_mul_f32 v[50:51], v[50:51], v[52:53]
	v_pk_mul_f32 v[48:49], v[48:49], v[56:57]
	v_pk_mul_f32 v[50:51], v[50:51], v[58:59]
	s_nop 0
	v_cvt_pk_bf16_f32 v50, v50, v51
	v_cvt_pk_bf16_f32 v51, v48, v49
	ds_bpermute_b32 v236, v244, v152
	ds_bpermute_b32 v237, v244, v153
	ds_bpermute_b32 v238, v244, v50
	ds_bpermute_b32 v239, v244, v51
	s_waitcnt lgkmcnt(0)
	global_store_dwordx2 v[236:237], v[238:239], off offset:8
	s_and_saveexec_b64 s[6:7], s[34:35]
	s_cbranch_execz .LBB0_685
	v_mov_b64_e32 v[48:49], s[24:25]
	v_mad_i64_i32 v[48:49], s[58:59], v154, s36, v[48:49]
	v_lshl_add_u64 v[48:49], v[196:197], 2, v[48:49]
	global_store_dwordx4 v[48:49], v[44:47], off offset:16
	s_nop 1
	v_add_co_u32_e32 v44, vcc, 0x2000, v48
	s_nop 1
	v_addc_co_u32_e32 v45, vcc, 0, v49, vcc
	global_store_dwordx4 v[44:45], v[40:43], off offset:3088

; __device__ __forceinline__ unsigned pk2(float lo, float hi) { const f32x2 v = {lo, hi}; const bf16x2_t b = __builtin_convertvector(v, bf16x2_t); return __builtin_bit_cast(unsigned, b); }
;     __device__ __forceinline__ void operator()(const f32x4 (&acc)[2][2][4][2], const pg8::Unit& u, int wr, int wc, int fr, int fq, PG8_LAS unsigned char* xl) const {
;     ...
;                     for (int bj = 0; bj < 2; ++bj) {
;                         const f32x4 cur = acc[ai][bj][m][n]; f32x4 p1, p2;
;                         if (!sample) { const f32x4 prv = (m == 0) ? hb[bj] : acc[ai][bj][m == 0 ? 0 : m - 1][n];
; #pragma unroll
;                             for (int j = 0; j < 4; ++j) { const float s1 = fr == 15 ? prv[j] : cur[j], s2 = fr >= 14 ? prv[j] : cur[j]; p1[j] = dpp_ror<1>(s1); p2[j] = dpp_ror<2>(s2); }
;                         } else { const int t = fr & 3, b = (row - MP) >> 2;
; #pragma unroll
;                             for (int j = 0; j < 4; ++j) { p1[j] = dpp_ror<1>(cur[j]); p2[j] = dpp_ror<2>(cur[j]); }
;                             const f32x4 c1 = *(const f32x4*)(ctx_s + (size_t)(b * 2 + 1) * FF2 + bj * FF + jc0 + 4 * n), c0 = *(const f32x4*)(ctx_s + (size_t)(b * 2) * FF2 + bj * FF + jc0 + 4 * n);
; #pragma unroll
;                             for (int j = 0; j < 4; ++j) { p2[j] = t == 0 ? c0[j] : (t == 1 ? c1[j] : p2[j]); p1[j] = t == 0 ? c1[j] : p1[j]; }
;                         }
;                         cc[bj] = bb[bj] + w0[bj] * p2 + w1[bj] * p1 + w2[bj] * cur;
;                     }
;                     const f32x4 gv = gelu_mul4(cc[0], cc[1]);
;                     u32x2 w; w.x = pk2(gv[0], gv[1]); w.y = pk2(gv[2], gv[3]);
;                     *(u32x2*)(G + (size_t)row * FF + jc0 + 4 * n) = w;
;                     if (!sample && ai == 0 && wr == 0 && m == 0 && fr < 2 && (pm & 7) != 0) {
; #pragma unroll
;                         for (int bj = 0; bj < 2; ++bj) *(f32x4*)(PH + (size_t)(pm * 2 + fr) * FF2 + bj * FF + jc0 + 4 * n) = cc[bj];
;                     }
;                     if (sample && (fr & 3) >= 2) { const int b = (row - MP) >> 2, t = fr & 3;
; #pragma unroll
;                         for (int bj = 0; bj < 2; ++bj) *(f32x4*)(nf_s + (size_t)(b * 2 + t - 2) * FF2 + bj * FF + jc0 + 4 * n) = acc[ai][bj][m][n];
.LBB0_695:
	s_waitcnt lgkmcnt(0)
	v_pk_fma_f32 v[40:41], v[94:95], v[50:51], v[102:103]
	v_pk_fma_f32 v[42:43], v[92:93], v[48:49], v[100:101]
	v_pk_fma_f32 v[40:41], v[90:91], v[46:47], v[40:41]
	v_pk_fma_f32 v[42:43], v[88:89], v[44:45], v[42:43]
	v_pk_fma_f32 v[40:41], v[38:39], v[82:83], v[40:41]
	v_pk_fma_f32 v[42:43], v[36:37], v[80:81], v[42:43]
	v_pk_fma_f32 v[46:47], v[84:85], v[56:57], v[96:97]
	v_pk_mul_f32 v[48:49], v[40:41], v[40:41]
	v_pk_fma_f32 v[46:47], v[76:77], v[52:53], v[46:47]
	v_pk_mul_f32 v[50:51], v[42:43], v[42:43]
	v_mov_b64_e32 v[52:53], s[82:83]
	v_pk_fma_f32 v[48:49], v[48:49], s[84:85], v[52:53] op_sel_hi:[1,0,0]
	v_pk_fma_f32 v[50:51], v[50:51], s[84:85], v[52:53] op_sel_hi:[1,0,0]
	v_pk_mul_f32 v[48:49], v[40:41], v[48:49]
	v_pk_mul_f32 v[50:51], v[42:43], v[50:51]
	v_exp_f32_e32 v48, v48
	v_exp_f32_e32 v50, v50
	v_exp_f32_e32 v49, v49
	v_exp_f32_e32 v51, v51
	v_pk_fma_f32 v[44:45], v[86:87], v[58:59], v[98:99]
	v_pk_fma_f32 v[46:47], v[32:33], v[72:73], v[46:47]
	v_pk_add_f32 v[48:49], v[48:49], 1.0 op_sel_hi:[1,0]
	v_pk_add_f32 v[50:51], v[50:51], 1.0 op_sel_hi:[1,0]
	v_rcp_f32_e32 v48, v48
	v_rcp_f32_e32 v50, v50
	v_rcp_f32_e32 v49, v49
	v_rcp_f32_e32 v51, v51
	v_pk_fma_f32 v[44:45], v[78:79], v[54:55], v[44:45]
	v_pk_mul_f32 v[42:43], v[42:43], v[46:47]
	v_pk_fma_f32 v[44:45], v[34:35], v[74:75], v[44:45]
	v_pk_mul_f32 v[42:43], v[42:43], v[50:51]
	v_pk_mul_f32 v[40:41], v[40:41], v[44:45]
	v_cvt_pk_bf16_f32 v42, v42, v43
	v_pk_mul_f32 v[40:41], v[40:41], v[48:49]
	s_nop 0
	v_cvt_pk_bf16_f32 v43, v40, v41
	ds_bpermute_b32 v236, v244, v144
	ds_bpermute_b32 v237, v244, v145
	ds_bpermute_b32 v238, v244, v42
	ds_bpermute_b32 v239, v244, v43
	s_waitcnt lgkmcnt(0)
	global_store_dwordx2 v[236:237], v[238:239], off offset:8
	s_and_saveexec_b64 s[6:7], s[34:35]
	s_cbranch_execz .LBB0_697
	v_mov_b64_e32 v[40:41], s[24:25]
	v_mad_i64_i32 v[40:41], s[10:11], v146, s36, v[40:41]
	v_lshl_add_u64 v[40:41], v[196:197], 2, v[40:41]
	global_store_dwordx4 v[40:41], v[36:39], off offset:16
	v_add_co_u32_e32 v40, vcc, 0x2000, v40
	s_nop 1
	v_addc_co_u32_e32 v41, vcc, 0, v41, vcc
	global_store_dwordx4 v[40:41], v[32:35], off offset:3088

; __device__ __forceinline__ unsigned pk2(float lo, float hi) { const f32x2 v = {lo, hi}; const bf16x2_t b = __builtin_convertvector(v, bf16x2_t); return __builtin_bit_cast(unsigned, b); }
;     __device__ __forceinline__ void operator()(const f32x4 (&acc)[2][2][4][2], const pg8::Unit& u, int wr, int wc, int fr, int fq, PG8_LAS unsigned char* xl) const {
;     ...
;                     for (int bj = 0; bj < 2; ++bj) {
;                         const f32x4 cur = acc[ai][bj][m][n]; f32x4 p1, p2;
;                         if (!sample) { const f32x4 prv = (m == 0) ? hb[bj] : acc[ai][bj][m == 0 ? 0 : m - 1][n];
; #pragma unroll
;                             for (int j = 0; j < 4; ++j) { const float s1 = fr == 15 ? prv[j] : cur[j], s2 = fr >= 14 ? prv[j] : cur[j]; p1[j] = dpp_ror<1>(s1); p2[j] = dpp_ror<2>(s2); }
;                         } else { const int t = fr & 3, b = (row - MP) >> 2;
; #pragma unroll
;                             for (int j = 0; j < 4; ++j) { p1[j] = dpp_ror<1>(cur[j]); p2[j] = dpp_ror<2>(cur[j]); }
;                             const f32x4 c1 = *(const f32x4*)(ctx_s + (size_t)(b * 2 + 1) * FF2 + bj * FF + jc0 + 4 * n), c0 = *(const f32x4*)(ctx_s + (size_t)(b * 2) * FF2 + bj * FF + jc0 + 4 * n);
; #pragma unroll
;                             for (int j = 0; j < 4; ++j) { p2[j] = t == 0 ? c0[j] : (t == 1 ? c1[j] : p2[j]); p1[j] = t == 0 ? c1[j] : p1[j]; }
;                         }
;                         cc[bj] = bb[bj] + w0[bj] * p2 + w1[bj] * p1 + w2[bj] * cur;
;                     }
;                     const f32x4 gv = gelu_mul4(cc[0], cc[1]);
;                     u32x2 w; w.x = pk2(gv[0], gv[1]); w.y = pk2(gv[2], gv[3]);
;                     *(u32x2*)(G + (size_t)row * FF + jc0 + 4 * n) = w;
;                     if (!sample && ai == 0 && wr == 0 && m == 0 && fr < 2 && (pm & 7) != 0) {
; #pragma unroll
;                         for (int bj = 0; bj < 2; ++bj) *(f32x4*)(PH + (size_t)(pm * 2 + fr) * FF2 + bj * FF + jc0 + 4 * n) = cc[bj];
;                     }
;                     if (sample && (fr & 3) >= 2) { const int b = (row - MP) >> 2, t = fr & 3;
; #pragma unroll
;                         for (int bj = 0; bj < 2; ++bj) *(f32x4*)(nf_s + (size_t)(b * 2 + t - 2) * FF2 + bj * FF + jc0 + 4 * n) = acc[ai][bj][m][n];
.LBB0_705:
	v_pk_fma_f32 v[32:33], v[94:95], v[46:47], v[102:103]
	v_pk_fma_f32 v[34:35], v[92:93], v[44:45], v[100:101]
	v_pk_fma_f32 v[32:33], v[90:91], v[42:43], v[32:33]
	v_pk_fma_f32 v[34:35], v[88:89], v[40:41], v[34:35]
	v_pk_fma_f32 v[32:33], v[30:31], v[82:83], v[32:33]
	v_pk_fma_f32 v[34:35], v[28:29], v[80:81], v[34:35]
	v_pk_fma_f32 v[40:41], v[86:87], v[50:51], v[98:99]
	v_pk_fma_f32 v[42:43], v[84:85], v[48:49], v[96:97]
	v_pk_fma_f32 v[38:39], v[78:79], v[38:39], v[40:41]
	v_pk_fma_f32 v[36:37], v[76:77], v[36:37], v[42:43]
	v_pk_mul_f32 v[40:41], v[32:33], v[32:33]
	v_pk_mul_f32 v[42:43], v[34:35], v[34:35]
	v_mov_b64_e32 v[44:45], s[82:83]
	v_pk_fma_f32 v[40:41], v[40:41], s[84:85], v[44:45] op_sel_hi:[1,0,0]
	v_pk_fma_f32 v[42:43], v[42:43], s[84:85], v[44:45] op_sel_hi:[1,0,0]
	v_pk_mul_f32 v[40:41], v[32:33], v[40:41]
	v_pk_mul_f32 v[42:43], v[34:35], v[42:43]
	v_exp_f32_e32 v40, v40
	v_exp_f32_e32 v42, v42
	v_exp_f32_e32 v41, v41
	v_exp_f32_e32 v43, v43
	v_pk_fma_f32 v[38:39], v[26:27], v[74:75], v[38:39]
	v_pk_fma_f32 v[36:37], v[24:25], v[72:73], v[36:37]
	v_pk_add_f32 v[40:41], v[40:41], 1.0 op_sel_hi:[1,0]
	v_pk_add_f32 v[42:43], v[42:43], 1.0 op_sel_hi:[1,0]
	v_rcp_f32_e32 v40, v40
	v_rcp_f32_e32 v42, v42
	v_rcp_f32_e32 v41, v41
	v_rcp_f32_e32 v43, v43
	v_pk_mul_f32 v[32:33], v[32:33], v[38:39]
	v_pk_mul_f32 v[34:35], v[34:35], v[36:37]
	v_pk_mul_f32 v[32:33], v[32:33], v[40:41]
	v_pk_mul_f32 v[34:35], v[34:35], v[42:43]
	s_nop 0
	v_cvt_pk_bf16_f32 v34, v34, v35
	v_cvt_pk_bf16_f32 v35, v32, v33
	ds_bpermute_b32 v236, v244, v136
	ds_bpermute_b32 v237, v244, v137
	ds_bpermute_b32 v238, v244, v34
	ds_bpermute_b32 v239, v244, v35
	s_waitcnt lgkmcnt(0)
	global_store_dwordx2 v[236:237], v[238:239], off offset:8
	s_and_saveexec_b64 s[6:7], s[34:35]
	s_cbranch_execz .LBB0_707
	v_mov_b64_e32 v[32:33], s[24:25]
	v_mad_i64_i32 v[32:33], s[10:11], v138, s36, v[32:33]
	v_lshl_add_u64 v[32:33], v[196:197], 2, v[32:33]
	global_store_dwordx4 v[32:33], v[28:31], off offset:16
	v_add_co_u32_e32 v32, vcc, 0x2000, v32
	s_nop 1
	v_addc_co_u32_e32 v33, vcc, 0, v33, vcc
	global_store_dwordx4 v[32:33], v[24:27], off offset:3088

; __device__ __forceinline__ unsigned pk2(float lo, float hi) { const f32x2 v = {lo, hi}; const bf16x2_t b = __builtin_convertvector(v, bf16x2_t); return __builtin_bit_cast(unsigned, b); }
;     __device__ __forceinline__ void operator()(const f32x4 (&acc)[2][2][4][2], const pg8::Unit& u, int wr, int wc, int fr, int fq, PG8_LAS unsigned char* xl) const {
;     ...
;                     for (int bj = 0; bj < 2; ++bj) {
;                         const f32x4 cur = acc[ai][bj][m][n]; f32x4 p1, p2;
;                         if (!sample) { const f32x4 prv = (m == 0) ? hb[bj] : acc[ai][bj][m == 0 ? 0 : m - 1][n];
; #pragma unroll
;                             for (int j = 0; j < 4; ++j) { const float s1 = fr == 15 ? prv[j] : cur[j], s2 = fr >= 14 ? prv[j] : cur[j]; p1[j] = dpp_ror<1>(s1); p2[j] = dpp_ror<2>(s2); }
;                         } else { const int t = fr & 3, b = (row - MP) >> 2;
; #pragma unroll
;                             for (int j = 0; j < 4; ++j) { p1[j] = dpp_ror<1>(cur[j]); p2[j] = dpp_ror<2>(cur[j]); }
;                             const f32x4 c1 = *(const f32x4*)(ctx_s + (size_t)(b * 2 + 1) * FF2 + bj * FF + jc0 + 4 * n), c0 = *(const f32x4*)(ctx_s + (size_t)(b * 2) * FF2 + bj * FF + jc0 + 4 * n);
; #pragma unroll
;                             for (int j = 0; j < 4; ++j) { p2[j] = t == 0 ? c0[j] : (t == 1 ? c1[j] : p2[j]); p1[j] = t == 0 ? c1[j] : p1[j]; }
;                         }
;                         cc[bj] = bb[bj] + w0[bj] * p2 + w1[bj] * p1 + w2[bj] * cur;
;                     }
;                     const f32x4 gv = gelu_mul4(cc[0], cc[1]);
;                     u32x2 w; w.x = pk2(gv[0], gv[1]); w.y = pk2(gv[2], gv[3]);
;                     *(u32x2*)(G + (size_t)row * FF + jc0 + 4 * n) = w;
;                     if (!sample && ai == 0 && wr == 0 && m == 0 && fr < 2 && (pm & 7) != 0) {
; #pragma unroll
;                         for (int bj = 0; bj < 2; ++bj) *(f32x4*)(PH + (size_t)(pm * 2 + fr) * FF2 + bj * FF + jc0 + 4 * n) = cc[bj];
;                     }
;                     if (sample && (fr & 3) >= 2) { const int b = (row - MP) >> 2, t = fr & 3;
; #pragma unroll
;                         for (int bj = 0; bj < 2; ++bj) *(f32x4*)(nf_s + (size_t)(b * 2 + t - 2) * FF2 + bj * FF + jc0 + 4 * n) = acc[ai][bj][m][n];
.LBB0_715:
	v_pk_fma_f32 v[24:25], v[94:95], v[38:39], v[102:103]
	v_pk_fma_f32 v[26:27], v[92:93], v[36:37], v[100:101]
	v_pk_fma_f32 v[24:25], v[90:91], v[34:35], v[24:25]
	v_pk_fma_f32 v[26:27], v[88:89], v[32:33], v[26:27]
	v_pk_fma_f32 v[24:25], v[22:23], v[82:83], v[24:25]
	v_pk_fma_f32 v[26:27], v[20:21], v[80:81], v[26:27]
	v_pk_fma_f32 v[32:33], v[86:87], v[42:43], v[98:99]
	v_pk_fma_f32 v[34:35], v[84:85], v[40:41], v[96:97]
	v_pk_fma_f32 v[30:31], v[78:79], v[30:31], v[32:33]
	v_pk_fma_f32 v[28:29], v[76:77], v[28:29], v[34:35]
	v_pk_mul_f32 v[32:33], v[24:25], v[24:25]
	v_pk_mul_f32 v[34:35], v[26:27], v[26:27]
	v_mov_b64_e32 v[36:37], s[82:83]
	v_pk_fma_f32 v[32:33], v[32:33], s[84:85], v[36:37] op_sel_hi:[1,0,0]
	v_pk_fma_f32 v[34:35], v[34:35], s[84:85], v[36:37] op_sel_hi:[1,0,0]
	v_pk_mul_f32 v[32:33], v[24:25], v[32:33]
	v_pk_mul_f32 v[34:35], v[26:27], v[34:35]
	v_exp_f32_e32 v32, v32
	v_exp_f32_e32 v34, v34
	v_exp_f32_e32 v33, v33
	v_exp_f32_e32 v35, v35
	v_pk_fma_f32 v[30:31], v[18:19], v[74:75], v[30:31]
	v_pk_fma_f32 v[28:29], v[16:17], v[72:73], v[28:29]
	v_pk_add_f32 v[32:33], v[32:33], 1.0 op_sel_hi:[1,0]
	v_pk_add_f32 v[34:35], v[34:35], 1.0 op_sel_hi:[1,0]
	v_rcp_f32_e32 v32, v32
	v_rcp_f32_e32 v34, v34
	v_rcp_f32_e32 v33, v33
	v_rcp_f32_e32 v35, v35
	v_pk_mul_f32 v[24:25], v[24:25], v[30:31]
	v_pk_mul_f32 v[26:27], v[26:27], v[28:29]
	v_pk_mul_f32 v[24:25], v[24:25], v[32:33]
	v_pk_mul_f32 v[26:27], v[26:27], v[34:35]
	s_nop 0
	v_cvt_pk_bf16_f32 v26, v26, v27
	v_cvt_pk_bf16_f32 v27, v24, v25
	ds_bpermute_b32 v236, v244, v128
	ds_bpermute_b32 v237, v244, v129
	ds_bpermute_b32 v238, v244, v26
	ds_bpermute_b32 v239, v244, v27
	s_waitcnt lgkmcnt(0)
	global_store_dwordx2 v[236:237], v[238:239], off offset:8
	s_and_saveexec_b64 s[6:7], s[34:35]
	s_cbranch_execz .LBB0_717
	v_mov_b64_e32 v[24:25], s[24:25]
	v_mad_i64_i32 v[24:25], s[10:11], v139, s36, v[24:25]
	v_lshl_add_u64 v[24:25], v[196:197], 2, v[24:25]
	global_store_dwordx4 v[24:25], v[20:23], off offset:16
	v_add_co_u32_e32 v24, vcc, 0x2000, v24
	s_nop 1
	v_addc_co_u32_e32 v25, vcc, 0, v25, vcc
	global_store_dwordx4 v[24:25], v[16:19], off offset:3088

; __device__ __forceinline__ unsigned pk2(float lo, float hi) { const f32x2 v = {lo, hi}; const bf16x2_t b = __builtin_convertvector(v, bf16x2_t); return __builtin_bit_cast(unsigned, b); }
;     __device__ __forceinline__ void operator()(const f32x4 (&acc)[2][2][4][2], const pg8::Unit& u, int wr, int wc, int fr, int fq, PG8_LAS unsigned char* xl) const {
;     ...
;                     for (int bj = 0; bj < 2; ++bj) {
;                         const f32x4 cur = acc[ai][bj][m][n]; f32x4 p1, p2;
;                         if (!sample) { const f32x4 prv = (m == 0) ? hb[bj] : acc[ai][bj][m == 0 ? 0 : m - 1][n];
; #pragma unroll
;                             for (int j = 0; j < 4; ++j) { const float s1 = fr == 15 ? prv[j] : cur[j], s2 = fr >= 14 ? prv[j] : cur[j]; p1[j] = dpp_ror<1>(s1); p2[j] = dpp_ror<2>(s2); }
;                         } else { const int t = fr & 3, b = (row - MP) >> 2;
; #pragma unroll
;                             for (int j = 0; j < 4; ++j) { p1[j] = dpp_ror<1>(cur[j]); p2[j] = dpp_ror<2>(cur[j]); }
;                             const f32x4 c1 = *(const f32x4*)(ctx_s + (size_t)(b * 2 + 1) * FF2 + bj * FF + jc0 + 4 * n), c0 = *(const f32x4*)(ctx_s + (size_t)(b * 2) * FF2 + bj * FF + jc0 + 4 * n);
; #pragma unroll
;                             for (int j = 0; j < 4; ++j) { p2[j] = t == 0 ? c0[j] : (t == 1 ? c1[j] : p2[j]); p1[j] = t == 0 ? c1[j] : p1[j]; }
;                         }
;                         cc[bj] = bb[bj] + w0[bj] * p2 + w1[bj] * p1 + w2[bj] * cur;
;                     }
;                     const f32x4 gv = gelu_mul4(cc[0], cc[1]);
;                     u32x2 w; w.x = pk2(gv[0], gv[1]); w.y = pk2(gv[2], gv[3]);
;                     *(u32x2*)(G + (size_t)row * FF + jc0 + 4 * n) = w;
;                     if (!sample && ai == 0 && wr == 0 && m == 0 && fr < 2 && (pm & 7) != 0) {
; #pragma unroll
;                         for (int bj = 0; bj < 2; ++bj) *(f32x4*)(PH + (size_t)(pm * 2 + fr) * FF2 + bj * FF + jc0 + 4 * n) = cc[bj];
;                     }
;                     if (sample && (fr & 3) >= 2) { const int b = (row - MP) >> 2, t = fr & 3;
; #pragma unroll
;                         for (int bj = 0; bj < 2; ++bj) *(f32x4*)(nf_s + (size_t)(b * 2 + t - 2) * FF2 + bj * FF + jc0 + 4 * n) = acc[ai][bj][m][n];
.LBB0_725:
	v_pk_fma_f32 v[16:17], v[94:95], v[30:31], v[102:103]
	v_pk_fma_f32 v[18:19], v[92:93], v[28:29], v[100:101]
	v_pk_fma_f32 v[16:17], v[90:91], v[26:27], v[16:17]
	v_pk_fma_f32 v[18:19], v[88:89], v[24:25], v[18:19]
	v_pk_fma_f32 v[16:17], v[10:11], v[82:83], v[16:17]
	v_pk_fma_f32 v[18:19], v[8:9], v[80:81], v[18:19]
	v_pk_fma_f32 v[24:25], v[86:87], v[34:35], v[98:99]
	v_pk_fma_f32 v[26:27], v[84:85], v[32:33], v[96:97]
	v_pk_fma_f32 v[22:23], v[78:79], v[22:23], v[24:25]
	v_pk_fma_f32 v[20:21], v[76:77], v[20:21], v[26:27]
	v_pk_mul_f32 v[24:25], v[16:17], v[16:17]
	v_pk_mul_f32 v[26:27], v[18:19], v[18:19]
	v_mov_b64_e32 v[28:29], s[82:83]
	v_pk_fma_f32 v[24:25], v[24:25], s[84:85], v[28:29] op_sel_hi:[1,0,0]
	v_pk_fma_f32 v[26:27], v[26:27], s[84:85], v[28:29] op_sel_hi:[1,0,0]
	v_pk_mul_f32 v[24:25], v[16:17], v[24:25]
	v_pk_mul_f32 v[26:27], v[18:19], v[26:27]
	v_exp_f32_e32 v24, v24
	v_exp_f32_e32 v26, v26
	v_exp_f32_e32 v25, v25
	v_exp_f32_e32 v27, v27
	v_pk_fma_f32 v[22:23], v[2:3], v[74:75], v[22:23]
	v_pk_fma_f32 v[20:21], v[0:1], v[72:73], v[20:21]
	v_pk_add_f32 v[24:25], v[24:25], 1.0 op_sel_hi:[1,0]
	v_pk_add_f32 v[26:27], v[26:27], 1.0 op_sel_hi:[1,0]
	v_rcp_f32_e32 v24, v24
	v_rcp_f32_e32 v26, v26
	v_rcp_f32_e32 v25, v25
	v_rcp_f32_e32 v27, v27
	v_pk_mul_f32 v[16:17], v[16:17], v[22:23]
	v_pk_mul_f32 v[18:19], v[18:19], v[20:21]
	v_pk_mul_f32 v[16:17], v[16:17], v[24:25]
	v_pk_mul_f32 v[18:19], v[18:19], v[26:27]
	s_nop 0
	v_cvt_pk_bf16_f32 v18, v18, v19
	v_cvt_pk_bf16_f32 v19, v16, v17
	ds_bpermute_b32 v236, v244, v130
	ds_bpermute_b32 v237, v244, v131
	ds_bpermute_b32 v238, v244, v18
	ds_bpermute_b32 v239, v244, v19
	s_waitcnt lgkmcnt(0)
	global_store_dwordx2 v[236:237], v[238:239], off offset:8
	s_and_saveexec_b64 s[6:7], s[34:35]
	s_cbranch_execz .LBB0_727
	v_mov_b64_e32 v[16:17], s[24:25]
	v_mad_i64_i32 v[16:17], s[10:11], v147, s36, v[16:17]
	v_lshl_add_u64 v[16:17], v[196:197], 2, v[16:17]
	global_store_dwordx4 v[16:17], v[8:11], off offset:16
	v_add_co_u32_e32 v16, vcc, 0x2000, v16
	s_nop 1
	v_addc_co_u32_e32 v17, vcc, 0, v17, vcc
	global_store_dwordx4 v[16:17], v[0:3], off offset:3088

; #define LAS __attribute__((address_space(3)))
; template <class F>
; __device__ __forceinline__ void small_gemm_ks(LAS unsigned char* lds, const bf16_t* A, int lda, const bf16_t* Bt, int ldb, int K, int N, int a_grp_cols, int bx, int G, int tid, const F& f) {
;     const int lane = tid & 63, w = __builtin_amdgcn_readfirstlane(tid >> 6), c = lane & 15, g = lane >> 4, kh = w >> 2, wq = w & 3, wm = wq >> 1, wn = wq & 1;
;     const int ntn = N / 64, ntiles = (MS / 32) * ntn, KH = K / 2;
;     for (int t = bx; t < ntiles; t += G) {
;         const int row0 = MP + (t / ntn) * 32 + wm * 16, n0 = (t % ntn) * 64 + wn * 32;
;         const bf16_t* ap = A + (size_t)(row0 + c) * lda + (n0 >> 8) * a_grp_cols + kh * KH + 8 * g;
;         const bf16_t* bp = Bt + (size_t)(n0 + c) * ldb + kh * KH + 8 * g;
;         f32x4 acc[2] = {(f32x4){0.f, 0.f, 0.f, 0.f}, (f32x4){0.f, 0.f, 0.f, 0.f}};
; #pragma unroll 8
;         for (int k0 = 0; k0 < KH; k0 += 32) { const bf16x8 av = *(const bf16x8*)(ap + k0);
.LBB0_1491:
	s_or_b64 exec, exec, s[6:7]
	v_readlane_b32 s0, v235, 5
	v_mov_b32_e32 v20, v208
	v_readlane_b32 s1, v235, 6
	s_waitcnt lgkmcnt(0)
	s_barrier
	s_load_dwordx2 s[8:9], s[0:1], 0xa0
	v_readfirstlane_b32 s3, v20
	v_and_b32_e32 v21, 15, v20
	s_waitcnt lgkmcnt(0)
	s_add_u32 s6, s8, 0x5700000
	s_addc_u32 s7, s9, 0
	s_and_b64 vcc, exec, s[88:89]
	s_cbranch_vccnz .LBB0_1500
	v_readfirstlane_b32 s68, v208
	v_and_b32_e32 v86, 63, v208
	s_nop 3
	s_lshr_b32 s68, s68, 6
	v_lshrrev_b32_e32 v87, 3, v86
	v_and_b32_e32 v88, 7, v86
	v_and_b32_e32 v94, 6, v87
	v_xor_b32_e32 v88, v88, v94
	s_mov_b32 s69, 2048
	v_mul_lo_u32 v90, v87, s69
	v_lshl_add_u32 v90, v88, 4, v90
	v_mov_b32_e32 v91, 0
	s_mov_b32 s69, 2048
	v_mul_lo_u32 v92, v87, s69
	v_lshl_add_u32 v92, v88, 4, v92
	v_mov_b32_e32 v93, 0
	v_and_b32_e32 v87, 15, v86
	v_lshrrev_b32_e32 v88, 4, v86
	v_lshrrev_b32_e32 v89, 3, v87
	v_lshlrev_b32_e32 v89, 10, v89
	v_and_b32_e32 v94, 6, v87
	v_xor_b32_e32 v94, v88, v94
	v_lshl_add_u32 v89, v94, 4, v89
	v_and_b32_e32 v94, 7, v87
	v_lshl_add_u32 v89, v94, 7, v89
	s_lshr_b32 s70, s68, 2
	s_bfe_u32 s71, s68, 0x10001
	s_and_b32 s72, s68, 1
	s_lshl_b32 s73, s70, 12
	s_lshl_b32 s74, s71, 11
	s_add_i32 s73, s73, s74
	s_lshl_b32 s74, s70, 13
	s_lshl_b32 s75, s72, 12
	s_add_i32 s74, s74, s75
	s_add_i32 s74, s74, 0x2000
	v_add_u32_e32 v96, s73, v89
	v_add_u32_e32 v101, s74, v89
	v_add_u32_e32 v97, s73, v89
	v_add_u32_e32 v102, s74, v89
	v_add_u32_e32 v98, s73, v89
	v_add_u32_e32 v103, s74, v89
	v_add_u32_e32 v99, s73, v89
	v_add_u32_e32 v104, s74, v89
	v_add_u32_e32 v100, s73, v89
	v_add_u32_e32 v105, s74, v89
	v_add_u32_e32 v97, 24576, v97
	v_add_u32_e32 v102, 24576, v102
	v_add_u32_e32 v98, 49152, v98
	v_add_u32_e32 v103, 49152, v103
	v_add_u32_e32 v99, 73728, v99
	v_add_u32_e32 v104, 73728, v104
	v_add_u32_e32 v100, 98304, v100
	v_add_u32_e32 v105, 98304, v105
	v_xor_b32_e32 v188, 64, v96
	v_xor_b32_e32 v193, 64, v101
	v_xor_b32_e32 v189, 64, v97
	v_xor_b32_e32 v194, 64, v102
	v_xor_b32_e32 v190, 64, v98
	v_xor_b32_e32 v195, 64, v103
	v_xor_b32_e32 v191, 64, v99
	v_xor_b32_e32 v196, 64, v104
	v_xor_b32_e32 v192, 64, v100
	v_xor_b32_e32 v197, 64, v105
	s_lshl_b32 s75, s71, 4
	v_lshl_add_u32 v106, v88, 2, s75
	v_lshlrev_b32_e32 v106, 11, v106
	s_lshl_b32 s75, s72, 5
	v_add_u32_e32 v107, s75, v87
	v_lshl_add_u32 v106, v107, 1, v106
	v_lshlrev_b32_e32 v108, 2, v107
	v_mov_b32_e32 v107, 0
	s_and_b32 s75, s68, 3
	s_lshl_b32 s75, s75, 11
	v_lshl_add_u32 v109, v86, 4, s75
	s_lshl_b32 s76, s68, 10
	s_lshl_b32 s77, s68, 11
	s_add_i32 s77, s77, 0x2000
	s_mov_b32 s78, 0x80
	s_mov_b32 s79, 0
	s_and_b32 s80, s68, 3
	s_mov_b32 s81, s2
.Lsg_hout_tile:
	s_lshr_b32 s82, s81, 4
	s_and_b32 s83, s81, 15
	s_lshl_b32 s82, s82, 5
	s_add_i32 s82, s82, 0x4000
	s_lshl_b32 s83, s83, 6
	s_lshl_b32 s59, s80, 3
	s_add_i32 s59, s59, s82
	s_mul_i32 s60, s59, 2048
	s_mul_hi_u32 s61, s59, 2048
	s_mul_i32 s62, s70, 1024
	s_add_u32 s60, s60, s62
	s_addc_u32 s61, s61, 0
	s_add_u32 s60, s60, s54
	s_addc_u32 s61, s61, s55
	s_add_u32 s60, s60, 0x3600000
	s_addc_u32 s61, s61, 0
	v_lshl_add_u64 v[110:111], s[60:61], 0, v[90:91]
	s_lshl_b32 s59, s80, 4
	s_add_i32 s59, s59, s83
	s_mul_i32 s60, s59, 2048
	s_mul_i32 s62, s70, 1024
	s_add_u32 s60, s60, s62
	s_add_u32 s60, s60, s54
	s_addc_u32 s61, s55, 0
	s_add_u32 s60, s60, 0x2a80000
	s_addc_u32 s61, s61, 0
	v_lshl_add_u64 v[112:113], s[60:61], 0, v[92:93]
	s_add_u32 s60, s60, 16384
	s_addc_u32 s61, s61, 0
	v_lshl_add_u64 v[114:115], s[60:61], 0, v[92:93]
	s_waitcnt vmcnt(0)
	v_mov_b32_e32 v120, 0
	v_mov_b32_e32 v121, 0
	v_mov_b32_e32 v122, 0
	v_mov_b32_e32 v123, 0
	v_mov_b32_e32 v124, 0
	v_mov_b32_e32 v125, 0
	v_mov_b32_e32 v126, 0
	v_mov_b32_e32 v127, 0
	s_add_i32 m0, s76, 0
	s_nop 0
	global_load_lds_dwordx4 v[110:111], off
	v_lshl_add_u64 v[110:111], v[110:111], 0, s[78:79]
	s_add_i32 m0, s77, 0
	s_nop 0
	global_load_lds_dwordx4 v[112:113], off
	v_lshl_add_u64 v[112:113], v[112:113], 0, s[78:79]
	s_add_i32 m0, s77, 1024
	s_nop 0
	global_load_lds_dwordx4 v[114:115], off
	v_lshl_add_u64 v[114:115], v[114:115], 0, s[78:79]
	s_add_i32 m0, s76, 24576
	s_nop 0
	global_load_lds_dwordx4 v[110:111], off
	v_lshl_add_u64 v[110:111], v[110:111], 0, s[78:79]
	s_add_i32 m0, s77, 24576
	s_nop 0
	global_load_lds_dwordx4 v[112:113], off
	v_lshl_add_u64 v[112:113], v[112:113], 0, s[78:79]
	s_add_i32 m0, s77, 25600
	s_nop 0
	global_load_lds_dwordx4 v[114:115], off
	v_lshl_add_u64 v[114:115], v[114:115], 0, s[78:79]
	s_add_i32 m0, s76, 49152
	s_nop 0
	global_load_lds_dwordx4 v[110:111], off
	v_lshl_add_u64 v[110:111], v[110:111], 0, s[78:79]
	s_add_i32 m0, s77, 49152
	s_nop 0
	global_load_lds_dwordx4 v[112:113], off
	v_lshl_add_u64 v[112:113], v[112:113], 0, s[78:79]
	s_add_i32 m0, s77, 50176
	s_nop 0
	global_load_lds_dwordx4 v[114:115], off
	v_lshl_add_u64 v[114:115], v[114:115], 0, s[78:79]
	s_add_i32 m0, s76, 73728
	s_nop 0
	global_load_lds_dwordx4 v[110:111], off
	v_lshl_add_u64 v[110:111], v[110:111], 0, s[78:79]
	s_add_i32 m0, s77, 73728
	s_nop 0
	global_load_lds_dwordx4 v[112:113], off
	v_lshl_add_u64 v[112:113], v[112:113], 0, s[78:79]
	s_add_i32 m0, s77, 74752
	s_nop 0
	global_load_lds_dwordx4 v[114:115], off
	v_lshl_add_u64 v[114:115], v[114:115], 0, s[78:79]
	s_waitcnt vmcnt(9)
	s_barrier
; #define LAS __attribute__((address_space(3)))
; #define LDS_SYNC() do { asm volatile("s_waitcnt lgkmcnt(0)" ::: "memory"); __builtin_amdgcn_s_barrier(); asm volatile("" ::: "memory"); } while (0)
; template <class F>
; __device__ __forceinline__ void small_gemm_ks(LAS unsigned char* lds, const bf16_t* A, int lda, const bf16_t* Bt, int ldb, int K, int N, int a_grp_cols, int bx, int G, int tid, const F& f) {
;     ...
;     for (int t = bx; t < ntiles; t += G) {
;         const int row0 = MP + (t / ntn) * 32 + wm * 16, n0 = (t % ntn) * 64 + wn * 32;
;         const bf16_t* ap = A + (size_t)(row0 + c) * lda + (n0 >> 8) * a_grp_cols + kh * KH + 8 * g;
;         const bf16_t* bp = Bt + (size_t)(n0 + c) * ldb + kh * KH + 8 * g;
;         f32x4 acc[2] = {(f32x4){0.f, 0.f, 0.f, 0.f}, (f32x4){0.f, 0.f, 0.f, 0.f}};
; #pragma unroll 8
;         for (int k0 = 0; k0 < KH; k0 += 32) { const bf16x8 av = *(const bf16x8*)(ap + k0);
; #pragma unroll
;             for (int nt = 0; nt < 2; ++nt) { const bf16x8 bv = *(const bf16x8*)(bp + (size_t)nt * 16 * ldb + k0); acc[nt] = __builtin_amdgcn_mfma_f32_16x16x32_bf16(av, bv, acc[nt], 0, 0, 0); } }
;         if (kh == 1) { *(LAS f32x4*)(lds + ((wq * 2 + 0) * 64 + lane) * 16) = acc[0]; *(LAS f32x4*)(lds + ((wq * 2 + 1) * 64 + lane) * 16) = acc[1]; }
;         LDS_SYNC();
	ds_read_b128 v[128:131], v96
	ds_read_b128 v[136:139], v101 offset:0
	ds_read_b128 v[144:147], v101 offset:2048
	ds_read_b128 v[132:135], v188
	ds_read_b128 v[140:143], v193 offset:0
	ds_read_b128 v[148:151], v193 offset:2048
	s_add_i32 m0, s76, 98304
	s_nop 0
	global_load_lds_dwordx4 v[110:111], off
	v_lshl_add_u64 v[110:111], v[110:111], 0, s[78:79]
	s_add_i32 m0, s77, 98304
	s_nop 0
	global_load_lds_dwordx4 v[112:113], off
	v_lshl_add_u64 v[112:113], v[112:113], 0, s[78:79]
	s_add_i32 m0, s77, 99328
	s_nop 0
	global_load_lds_dwordx4 v[114:115], off
	v_lshl_add_u64 v[114:115], v[114:115], 0, s[78:79]
	s_waitcnt lgkmcnt(3)
	v_mfma_f32_16x16x32_bf16 v[120:123], v[128:131], v[136:139], v[120:123]
	v_mfma_f32_16x16x32_bf16 v[124:127], v[128:131], v[144:147], v[124:127]
	s_waitcnt lgkmcnt(0)
	v_mfma_f32_16x16x32_bf16 v[120:123], v[132:135], v[140:143], v[120:123]
	v_mfma_f32_16x16x32_bf16 v[124:127], v[132:135], v[148:151], v[124:127]
	s_waitcnt vmcnt(9)
	s_barrier
	ds_read_b128 v[152:155], v97
	ds_read_b128 v[160:163], v102 offset:0
	ds_read_b128 v[168:171], v102 offset:2048
	ds_read_b128 v[156:159], v189
	ds_read_b128 v[164:167], v194 offset:0
	ds_read_b128 v[172:175], v194 offset:2048
	s_add_i32 m0, s76, 0
	s_nop 0
	global_load_lds_dwordx4 v[110:111], off
	v_lshl_add_u64 v[110:111], v[110:111], 0, s[78:79]
	s_add_i32 m0, s77, 0
	s_nop 0
	global_load_lds_dwordx4 v[112:113], off
	v_lshl_add_u64 v[112:113], v[112:113], 0, s[78:79]
	s_add_i32 m0, s77, 1024
	s_nop 0
	global_load_lds_dwordx4 v[114:115], off
	v_lshl_add_u64 v[114:115], v[114:115], 0, s[78:79]
	s_waitcnt lgkmcnt(3)
	v_mfma_f32_16x16x32_bf16 v[120:123], v[152:155], v[160:163], v[120:123]
	v_mfma_f32_16x16x32_bf16 v[124:127], v[152:155], v[168:171], v[124:127]
	s_waitcnt lgkmcnt(0)
	v_mfma_f32_16x16x32_bf16 v[120:123], v[156:159], v[164:167], v[120:123]
	v_mfma_f32_16x16x32_bf16 v[124:127], v[156:159], v[172:175], v[124:127]
	s_waitcnt vmcnt(9)
	s_barrier
	ds_read_b128 v[128:131], v98
	ds_read_b128 v[136:139], v103 offset:0
	ds_read_b128 v[144:147], v103 offset:2048
	ds_read_b128 v[132:135], v190
	ds_read_b128 v[140:143], v195 offset:0
	ds_read_b128 v[148:151], v195 offset:2048
	s_add_i32 m0, s76, 24576
	s_nop 0
	global_load_lds_dwordx4 v[110:111], off
	v_lshl_add_u64 v[110:111], v[110:111], 0, s[78:79]
	s_add_i32 m0, s77, 24576
	s_nop 0
	global_load_lds_dwordx4 v[112:113], off
	v_lshl_add_u64 v[112:113], v[112:113], 0, s[78:79]
	s_add_i32 m0, s77, 25600
	s_nop 0
	global_load_lds_dwordx4 v[114:115], off
	v_lshl_add_u64 v[114:115], v[114:115], 0, s[78:79]
	s_waitcnt lgkmcnt(3)
	v_mfma_f32_16x16x32_bf16 v[120:123], v[128:131], v[136:139], v[120:123]
	v_mfma_f32_16x16x32_bf16 v[124:127], v[128:131], v[144:147], v[124:127]
	s_waitcnt lgkmcnt(0)
	v_mfma_f32_16x16x32_bf16 v[120:123], v[132:135], v[140:143], v[120:123]
	v_mfma_f32_16x16x32_bf16 v[124:127], v[132:135], v[148:151], v[124:127]
	s_waitcnt vmcnt(9)
	s_barrier
	ds_read_b128 v[152:155], v99
	ds_read_b128 v[160:163], v104 offset:0
	ds_read_b128 v[168:171], v104 offset:2048
	ds_read_b128 v[156:159], v191
	ds_read_b128 v[164:167], v196 offset:0
	ds_read_b128 v[172:175], v196 offset:2048
	s_add_i32 m0, s76, 49152
	s_nop 0
	global_load_lds_dwordx4 v[110:111], off
	v_lshl_add_u64 v[110:111], v[110:111], 0, s[78:79]
	s_add_i32 m0, s77, 49152
	s_nop 0
	global_load_lds_dwordx4 v[112:113], off
	v_lshl_add_u64 v[112:113], v[112:113], 0, s[78:79]
	s_add_i32 m0, s77, 50176
	s_nop 0
	global_load_lds_dwordx4 v[114:115], off
	v_lshl_add_u64 v[114:115], v[114:115], 0, s[78:79]
	s_waitcnt lgkmcnt(3)
	v_mfma_f32_16x16x32_bf16 v[120:123], v[152:155], v[160:163], v[120:123]
	v_mfma_f32_16x16x32_bf16 v[124:127], v[152:155], v[168:171], v[124:127]
	s_waitcnt lgkmcnt(0)
	v_mfma_f32_16x16x32_bf16 v[120:123], v[156:159], v[164:167], v[120:123]
	v_mfma_f32_16x16x32_bf16 v[124:127], v[156:159], v[172:175], v[124:127]
	s_waitcnt vmcnt(9)
	s_barrier
	ds_read_b128 v[128:131], v100
	ds_read_b128 v[136:139], v105 offset:0
	ds_read_b128 v[144:147], v105 offset:2048
	ds_read_b128 v[132:135], v192
	ds_read_b128 v[140:143], v197 offset:0
	ds_read_b128 v[148:151], v197 offset:2048
	s_waitcnt lgkmcnt(3)
	v_mfma_f32_16x16x32_bf16 v[120:123], v[128:131], v[136:139], v[120:123]
	v_mfma_f32_16x16x32_bf16 v[124:127], v[128:131], v[144:147], v[124:127]
	s_waitcnt lgkmcnt(0)
	v_mfma_f32_16x16x32_bf16 v[120:123], v[132:135], v[140:143], v[120:123]
	v_mfma_f32_16x16x32_bf16 v[124:127], v[132:135], v[148:151], v[124:127]
	s_waitcnt vmcnt(6)
	s_barrier
	ds_read_b128 v[152:155], v96
	ds_read_b128 v[160:163], v101 offset:0
	ds_read_b128 v[168:171], v101 offset:2048
	ds_read_b128 v[156:159], v188
	ds_read_b128 v[164:167], v193 offset:0
	ds_read_b128 v[172:175], v193 offset:2048
	s_waitcnt lgkmcnt(3)
	v_mfma_f32_16x16x32_bf16 v[120:123], v[152:155], v[160:163], v[120:123]
	v_mfma_f32_16x16x32_bf16 v[124:127], v[152:155], v[168:171], v[124:127]
	s_waitcnt lgkmcnt(0)
	v_mfma_f32_16x16x32_bf16 v[120:123], v[156:159], v[164:167], v[120:123]
	v_mfma_f32_16x16x32_bf16 v[124:127], v[156:159], v[172:175], v[124:127]
	s_waitcnt vmcnt(3)
	s_barrier
	ds_read_b128 v[128:131], v97
	ds_read_b128 v[136:139], v102 offset:0
	ds_read_b128 v[144:147], v102 offset:2048
	ds_read_b128 v[132:135], v189
	ds_read_b128 v[140:143], v194 offset:0
	ds_read_b128 v[148:151], v194 offset:2048
	s_waitcnt lgkmcnt(3)
	v_mfma_f32_16x16x32_bf16 v[120:123], v[128:131], v[136:139], v[120:123]
	v_mfma_f32_16x16x32_bf16 v[124:127], v[128:131], v[144:147], v[124:127]
	s_waitcnt lgkmcnt(0)
	v_mfma_f32_16x16x32_bf16 v[120:123], v[132:135], v[140:143], v[120:123]
	v_mfma_f32_16x16x32_bf16 v[124:127], v[132:135], v[148:151], v[124:127]
	s_waitcnt vmcnt(0)
	s_barrier
	ds_read_b128 v[152:155], v98
	ds_read_b128 v[160:163], v103 offset:0
	ds_read_b128 v[168:171], v103 offset:2048
	ds_read_b128 v[156:159], v190
	ds_read_b128 v[164:167], v195 offset:0
	ds_read_b128 v[172:175], v195 offset:2048
	s_waitcnt lgkmcnt(3)
	v_mfma_f32_16x16x32_bf16 v[120:123], v[152:155], v[160:163], v[120:123]
	v_mfma_f32_16x16x32_bf16 v[124:127], v[152:155], v[168:171], v[124:127]
	s_waitcnt lgkmcnt(0)
	v_mfma_f32_16x16x32_bf16 v[120:123], v[156:159], v[164:167], v[120:123]
	v_mfma_f32_16x16x32_bf16 v[124:127], v[156:159], v[172:175], v[124:127]
	s_barrier
	s_lshl_b32 s59, s82, 11
	s_lshl_b32 s62, s83, 1
	s_add_i32 s59, s59, s62
	s_add_u32 s60, s54, s59
	s_addc_u32 s61, s55, 0
	s_add_u32 s60, s60, 0x5700000
	s_addc_u32 s61, s61, 0
	v_lshl_add_u64 v[176:177], s[60:61], 0, v[106:107]
	s_mov_b32 s62, 0x1000
	s_mov_b32 s63, 0
	v_lshl_add_u64 v[178:179], v[176:177], 0, s[62:63]
	s_cmp_eq_u32 s70, 0
	s_cbranch_scc1 .Lsg_hout_lo
	s_nop 4
	ds_write_b128 v109, v[120:123]
	ds_write_b128 v109, v[124:127] offset:1024
	s_waitcnt lgkmcnt(0)
	s_barrier
	s_branch .Lsg_hout_done

; #define LDS_SYNC() do { asm volatile("s_waitcnt lgkmcnt(0)" ::: "memory"); __builtin_amdgcn_s_barrier(); asm volatile("" ::: "memory"); } while (0)
;     __host__ __device__ bool next(int i, Unit& u) const {
;         const long L = (long)i * G + c; if (L >= nwg) return false;
;         int wgid = (int)L; { const int q = nwg / NXCD, r = nwg % NXCD, xcd = wgid % NXCD, off = wgid / NXCD; wgid = (xcd < r ? xcd * (q + 1) : r * (q + 1) + (xcd - r) * q) + off; }
; template <class F>
; __device__ __forceinline__ void small_gemm_ks(LAS unsigned char* lds, const bf16_t* A, int lda, const bf16_t* Bt, int ldb, int K, int N, int a_grp_cols, int bx, int G, int tid, const F& f) {
;     ...
;         LDS_SYNC();
;     }
.Lsg_hout_done:
	s_waitcnt lgkmcnt(0)
	s_barrier
	s_add_i32 s81, s81, s56
	s_cmpk_lt_i32 s81, 0x100
	s_cbranch_scc1 .Lsg_hout_tile
.LBB0_1500:
	s_and_b64 vcc, exec, s[88:89]
	v_readfirstlane_b32 s13, v20
	s_cbranch_vccnz .LBB0_1524
	s_ashr_i32 s0, s2, 31
	s_lshr_b32 s1, s0, 29
	s_add_i32 s1, s2, s1
	s_and_b32 s3, s1, -8
	s_sub_i32 s3, s2, s3
	s_cmp_gt_i32 s3, -1
	s_cbranch_scc0 .LBB0_1503
	s_lshl_b32 s12, s3, 5
	s_cbranch_execz .LBB0_1504
	s_branch .LBB0_1505

; __device__ __forceinline__ unsigned pk2(float lo, float hi) { const f32x2 v = {lo, hi}; const bf16x2_t b = __builtin_convertvector(v, bf16x2_t); return __builtin_bit_cast(unsigned, b); }
; __device__ __forceinline__ f32x4 gelu_mul4(f32x4 x, f32x4 v) {
;     const f32x4 t = x * x;
;     const f32x4 u = t * (-2.0f * 0.7978845608028654f * 0.044715f * 1.4426950408889634f) + (-2.0f * 0.7978845608028654f * 1.4426950408889634f);
;     const f32x4 z = x * u;
;     f32x4 d; d[0] = __builtin_amdgcn_exp2f(z[0]); d[1] = __builtin_amdgcn_exp2f(z[1]); d[2] = __builtin_amdgcn_exp2f(z[2]); d[3] = __builtin_amdgcn_exp2f(z[3]);
;     d = d + 1.0f;
;     f32x4 r; r[0] = __builtin_amdgcn_rcpf(d[0]); r[1] = __builtin_amdgcn_rcpf(d[1]); r[2] = __builtin_amdgcn_rcpf(d[2]); r[3] = __builtin_amdgcn_rcpf(d[3]);
;     return (x * v) * r;
;     __device__ __forceinline__ void operator()(const f32x4 (&acc)[2][2][4][2], const pg8::Unit& u, int wr, int wc, int fr, int fq, PG8_LAS unsigned char* xl) const {
;     ...
;                         cc[bj] = bb[bj] + w0[bj] * p2 + w1[bj] * p1 + w2[bj] * cur;
;                     }
;                     const f32x4 gv = gelu_mul4(cc[0], cc[1]);
;                     u32x2 w; w.x = pk2(gv[0], gv[1]); w.y = pk2(gv[2], gv[3]);
;                     *(u32x2*)(G + (size_t)row * FF + jc0 + 4 * n) = w;
;                     if (!sample && ai == 0 && wr == 0 && m == 0 && fr < 2 && (pm & 7) != 0) {
; #pragma unroll
;                         for (int bj = 0; bj < 2; ++bj) *(f32x4*)(PH + (size_t)(pm * 2 + fr) * FF2 + bj * FF + jc0 + 4 * n) = cc[bj];
;                     }
;                     if (sample && (fr & 3) >= 2) { const int b = (row - MP) >> 2, t = fr & 3;
; #pragma unroll
;                         for (int bj = 0; bj < 2; ++bj) *(f32x4*)(nf_s + (size_t)(b * 2 + t - 2) * FF2 + bj * FF + jc0 + 4 * n) = acc[ai][bj][m][n];
;                     }
.LBB0_1683:
	s_and_b32 s73, s36, 7
	s_waitcnt vmcnt(0)
	v_pk_fma_f32 v[160:161], v[114:115], v[170:171], v[118:119]
	v_pk_fma_f32 v[162:163], v[112:113], v[168:169], v[116:117]
	s_cmp_lg_u32 s73, 0
	v_pk_fma_f32 v[160:161], v[106:107], v[166:167], v[160:161]
	v_pk_fma_f32 v[164:165], v[104:105], v[164:165], v[162:163]
	s_cselect_b64 s[6:7], -1, 0
	s_lshl_b32 s85, s36, 1
	v_pk_fma_f32 v[162:163], v[158:159], v[98:99], v[160:161]
	v_pk_fma_f32 v[160:161], v[156:157], v[96:97], v[164:165]
	v_add_u32_e32 v164, s85, v205
	v_mad_i64_i32 v[168:169], s[58:59], v164, s76, 0
	v_pk_fma_f32 v[164:165], v[110:111], v[178:179], v[122:123]
	v_pk_fma_f32 v[166:167], v[108:109], v[176:177], v[120:121]
	v_pk_fma_f32 v[164:165], v[102:103], v[174:175], v[164:165]
	v_pk_fma_f32 v[170:171], v[100:101], v[172:173], v[166:167]
	v_pk_mul_f32 v[166:167], v[162:163], v[162:163]
	v_pk_mul_f32 v[172:173], v[160:161], v[160:161]
	v_mov_b64_e32 v[174:175], s[80:81]
	v_pk_fma_f32 v[166:167], v[166:167], s[82:83], v[174:175] op_sel_hi:[1,0,0]
	v_pk_fma_f32 v[172:173], v[172:173], s[82:83], v[174:175] op_sel_hi:[1,0,0]
	v_pk_mul_f32 v[166:167], v[162:163], v[166:167]
	v_pk_mul_f32 v[172:173], v[160:161], v[172:173]
	v_exp_f32_e32 v174, v166
	v_exp_f32_e32 v172, v172
	v_exp_f32_e32 v175, v167
	v_exp_f32_e32 v173, v173
	v_pk_fma_f32 v[166:167], v[154:155], v[94:95], v[164:165]
	v_pk_fma_f32 v[164:165], v[152:153], v[92:93], v[170:171]
	v_pk_add_f32 v[170:171], v[174:175], 1.0 op_sel_hi:[1,0]
	v_pk_add_f32 v[172:173], v[172:173], 1.0 op_sel_hi:[1,0]
	v_rcp_f32_e32 v170, v170
	v_rcp_f32_e32 v172, v172
	v_rcp_f32_e32 v171, v171
	v_rcp_f32_e32 v173, v173
	v_pk_mul_f32 v[174:175], v[162:163], v[166:167]
	v_pk_mul_f32 v[176:177], v[160:161], v[164:165]
	v_pk_mul_f32 v[170:171], v[174:175], v[170:171]
	v_pk_mul_f32 v[172:173], v[176:177], v[172:173]
	v_lshl_add_u64 v[168:169], s[44:45], 0, v[168:169]
	v_cvt_pk_bf16_f32 v172, v172, v173
	v_cvt_pk_bf16_f32 v173, v170, v171
	v_mov_b64_e32 v[170:171], s[40:41]
	v_mad_i64_i32 v[170:171], s[58:59], v221, s77, v[170:171]
	s_and_b64 s[58:59], s[66:67], s[94:95]
	s_xor_b64 s[58:59], s[58:59], -1
	s_nor_b64 s[58:59], s[58:59], s[18:19]
	v_lshl_add_u64 v[178:179], v[196:197], 1, v[170:171]
	s_and_b64 s[58:59], s[6:7], s[58:59]
	v_lshl_add_u64 v[176:177], v[196:197], 2, v[168:169]
	ds_bpermute_b32 v236, v244, v178
	ds_bpermute_b32 v237, v244, v179
	ds_bpermute_b32 v238, v244, v172
	ds_bpermute_b32 v239, v244, v173
	s_waitcnt lgkmcnt(0)
	global_store_dwordx2 v[236:237], v[238:239], off
	s_and_saveexec_b64 s[6:7], s[58:59]
	s_cbranch_execz .LBB0_1685
	global_store_dwordx4 v[176:177], v[160:163], off
	s_nop 1
	v_add_co_u32_e32 v160, vcc, 0x2000, v176
	s_nop 1
	v_addc_co_u32_e32 v161, vcc, 0, v177, vcc
	global_store_dwordx4 v[160:161], v[164:167], off offset:3072

; __device__ __forceinline__ unsigned pk2(float lo, float hi) { const f32x2 v = {lo, hi}; const bf16x2_t b = __builtin_convertvector(v, bf16x2_t); return __builtin_bit_cast(unsigned, b); }
; __device__ __forceinline__ f32x4 gelu_mul4(f32x4 x, f32x4 v) {
;     const f32x4 t = x * x;
;     const f32x4 u = t * (-2.0f * 0.7978845608028654f * 0.044715f * 1.4426950408889634f) + (-2.0f * 0.7978845608028654f * 1.4426950408889634f);
;     const f32x4 z = x * u;
;     f32x4 d; d[0] = __builtin_amdgcn_exp2f(z[0]); d[1] = __builtin_amdgcn_exp2f(z[1]); d[2] = __builtin_amdgcn_exp2f(z[2]); d[3] = __builtin_amdgcn_exp2f(z[3]);
;     d = d + 1.0f;
;     f32x4 r; r[0] = __builtin_amdgcn_rcpf(d[0]); r[1] = __builtin_amdgcn_rcpf(d[1]); r[2] = __builtin_amdgcn_rcpf(d[2]); r[3] = __builtin_amdgcn_rcpf(d[3]);
;     return (x * v) * r;
;     __device__ __forceinline__ void operator()(const f32x4 (&acc)[2][2][4][2], const pg8::Unit& u, int wr, int wc, int fr, int fq, PG8_LAS unsigned char* xl) const {
;     ...
;                         cc[bj] = bb[bj] + w0[bj] * p2 + w1[bj] * p1 + w2[bj] * cur;
;                     }
;                     const f32x4 gv = gelu_mul4(cc[0], cc[1]);
;                     u32x2 w; w.x = pk2(gv[0], gv[1]); w.y = pk2(gv[2], gv[3]);
;                     *(u32x2*)(G + (size_t)row * FF + jc0 + 4 * n) = w;
;                     if (!sample && ai == 0 && wr == 0 && m == 0 && fr < 2 && (pm & 7) != 0) {
; #pragma unroll
;                         for (int bj = 0; bj < 2; ++bj) *(f32x4*)(PH + (size_t)(pm * 2 + fr) * FF2 + bj * FF + jc0 + 4 * n) = cc[bj];
;                     }
;                     if (sample && (fr & 3) >= 2) { const int b = (row - MP) >> 2, t = fr & 3;
; #pragma unroll
;                         for (int bj = 0; bj < 2; ++bj) *(f32x4*)(nf_s + (size_t)(b * 2 + t - 2) * FF2 + bj * FF + jc0 + 4 * n) = acc[ai][bj][m][n];
;                     }
.LBB0_1695:
	v_pk_fma_f32 v[152:153], v[114:115], v[166:167], v[118:119]
	v_pk_fma_f32 v[154:155], v[112:113], v[164:165], v[116:117]
	v_pk_fma_f32 v[152:153], v[106:107], v[162:163], v[152:153]
	v_pk_fma_f32 v[154:155], v[104:105], v[160:161], v[154:155]
	v_pk_fma_f32 v[152:153], v[150:151], v[98:99], v[152:153]
	v_pk_fma_f32 v[154:155], v[148:149], v[96:97], v[154:155]
	v_pk_fma_f32 v[160:161], v[110:111], v[170:171], v[122:123]
	v_pk_fma_f32 v[162:163], v[108:109], v[168:169], v[120:121]
	v_pk_fma_f32 v[158:159], v[102:103], v[158:159], v[160:161]
	v_pk_fma_f32 v[156:157], v[100:101], v[156:157], v[162:163]
	v_pk_mul_f32 v[160:161], v[152:153], v[152:153]
	v_pk_mul_f32 v[162:163], v[154:155], v[154:155]
	v_mov_b64_e32 v[164:165], s[80:81]
	v_pk_fma_f32 v[160:161], v[160:161], s[82:83], v[164:165] op_sel_hi:[1,0,0]
	v_pk_fma_f32 v[162:163], v[162:163], s[82:83], v[164:165] op_sel_hi:[1,0,0]
	v_pk_mul_f32 v[160:161], v[152:153], v[160:161]
	v_pk_mul_f32 v[162:163], v[154:155], v[162:163]
	v_exp_f32_e32 v160, v160
	v_exp_f32_e32 v162, v162
	v_exp_f32_e32 v161, v161
	v_exp_f32_e32 v163, v163
	v_pk_fma_f32 v[158:159], v[146:147], v[94:95], v[158:159]
	v_pk_fma_f32 v[156:157], v[144:145], v[92:93], v[156:157]
	v_pk_add_f32 v[160:161], v[160:161], 1.0 op_sel_hi:[1,0]
	v_pk_add_f32 v[162:163], v[162:163], 1.0 op_sel_hi:[1,0]
	v_rcp_f32_e32 v160, v160
	v_rcp_f32_e32 v162, v162
	v_rcp_f32_e32 v161, v161
	v_rcp_f32_e32 v163, v163
	v_pk_mul_f32 v[152:153], v[152:153], v[158:159]
	v_pk_mul_f32 v[154:155], v[154:155], v[156:157]
	v_pk_mul_f32 v[152:153], v[152:153], v[160:161]
	v_pk_mul_f32 v[154:155], v[154:155], v[162:163]
	v_or_b32_e32 v166, 16, v221
	v_cvt_pk_bf16_f32 v154, v154, v155
	v_cvt_pk_bf16_f32 v155, v152, v153
	v_mov_b64_e32 v[152:153], s[40:41]
	v_mad_i64_i32 v[152:153], s[6:7], v166, s77, v[152:153]
	v_lshl_add_u64 v[168:169], v[196:197], 1, v[152:153]
	v_add_u32_e32 v170, v222, v211
	ds_bpermute_b32 v236, v244, v168
	ds_bpermute_b32 v237, v244, v169
	ds_bpermute_b32 v238, v244, v154
	ds_bpermute_b32 v239, v244, v155
	s_waitcnt lgkmcnt(0)
	global_store_dwordx2 v[236:237], v[238:239], off
	s_and_saveexec_b64 s[6:7], s[96:97]
	s_cbranch_execz .LBB0_1697
	v_mov_b64_e32 v[152:153], s[24:25]
	v_mad_i64_i32 v[152:153], vcc, v170, s76, v[152:153]
	v_lshl_add_u64 v[152:153], v[196:197], 2, v[152:153]
	global_store_dwordx4 v[152:153], v[148:151], off
	v_add_co_u32_e32 v152, vcc, 0x2000, v152
	s_nop 1
	v_addc_co_u32_e32 v153, vcc, 0, v153, vcc
	global_store_dwordx4 v[152:153], v[144:147], off offset:3072

; __device__ __forceinline__ unsigned pk2(float lo, float hi) { const f32x2 v = {lo, hi}; const bf16x2_t b = __builtin_convertvector(v, bf16x2_t); return __builtin_bit_cast(unsigned, b); }
; __device__ __forceinline__ f32x4 gelu_mul4(f32x4 x, f32x4 v) {
;     const f32x4 t = x * x;
;     const f32x4 u = t * (-2.0f * 0.7978845608028654f * 0.044715f * 1.4426950408889634f) + (-2.0f * 0.7978845608028654f * 1.4426950408889634f);
;     const f32x4 z = x * u;
;     f32x4 d; d[0] = __builtin_amdgcn_exp2f(z[0]); d[1] = __builtin_amdgcn_exp2f(z[1]); d[2] = __builtin_amdgcn_exp2f(z[2]); d[3] = __builtin_amdgcn_exp2f(z[3]);
;     d = d + 1.0f;
;     f32x4 r; r[0] = __builtin_amdgcn_rcpf(d[0]); r[1] = __builtin_amdgcn_rcpf(d[1]); r[2] = __builtin_amdgcn_rcpf(d[2]); r[3] = __builtin_amdgcn_rcpf(d[3]);
;     return (x * v) * r;
;     __device__ __forceinline__ void operator()(const f32x4 (&acc)[2][2][4][2], const pg8::Unit& u, int wr, int wc, int fr, int fq, PG8_LAS unsigned char* xl) const {
;     ...
;                         cc[bj] = bb[bj] + w0[bj] * p2 + w1[bj] * p1 + w2[bj] * cur;
;                     }
;                     const f32x4 gv = gelu_mul4(cc[0], cc[1]);
;                     u32x2 w; w.x = pk2(gv[0], gv[1]); w.y = pk2(gv[2], gv[3]);
;                     *(u32x2*)(G + (size_t)row * FF + jc0 + 4 * n) = w;
;                     if (!sample && ai == 0 && wr == 0 && m == 0 && fr < 2 && (pm & 7) != 0) {
; #pragma unroll
;                         for (int bj = 0; bj < 2; ++bj) *(f32x4*)(PH + (size_t)(pm * 2 + fr) * FF2 + bj * FF + jc0 + 4 * n) = cc[bj];
;                     }
;                     if (sample && (fr & 3) >= 2) { const int b = (row - MP) >> 2, t = fr & 3;
; #pragma unroll
;                         for (int bj = 0; bj < 2; ++bj) *(f32x4*)(nf_s + (size_t)(b * 2 + t - 2) * FF2 + bj * FF + jc0 + 4 * n) = acc[ai][bj][m][n];
;                     }
.LBB0_1705:
	v_pk_fma_f32 v[144:145], v[114:115], v[158:159], v[118:119]
	v_pk_fma_f32 v[146:147], v[112:113], v[156:157], v[116:117]
	v_pk_fma_f32 v[144:145], v[106:107], v[154:155], v[144:145]
	v_pk_fma_f32 v[146:147], v[104:105], v[152:153], v[146:147]
	v_pk_fma_f32 v[144:145], v[142:143], v[98:99], v[144:145]
	v_pk_fma_f32 v[146:147], v[140:141], v[96:97], v[146:147]
	v_pk_fma_f32 v[152:153], v[110:111], v[162:163], v[122:123]
	v_pk_fma_f32 v[154:155], v[108:109], v[160:161], v[120:121]
	v_pk_fma_f32 v[150:151], v[102:103], v[150:151], v[152:153]
	v_pk_fma_f32 v[148:149], v[100:101], v[148:149], v[154:155]
	v_pk_mul_f32 v[152:153], v[144:145], v[144:145]
	v_pk_mul_f32 v[154:155], v[146:147], v[146:147]
	v_mov_b64_e32 v[156:157], s[80:81]
	v_pk_fma_f32 v[152:153], v[152:153], s[82:83], v[156:157] op_sel_hi:[1,0,0]
	v_pk_fma_f32 v[154:155], v[154:155], s[82:83], v[156:157] op_sel_hi:[1,0,0]
	v_pk_mul_f32 v[152:153], v[144:145], v[152:153]
	v_pk_mul_f32 v[154:155], v[146:147], v[154:155]
	v_exp_f32_e32 v152, v152
	v_exp_f32_e32 v154, v154
	v_exp_f32_e32 v153, v153
	v_exp_f32_e32 v155, v155
	v_pk_fma_f32 v[150:151], v[138:139], v[94:95], v[150:151]
	v_pk_fma_f32 v[148:149], v[136:137], v[92:93], v[148:149]
	v_pk_add_f32 v[152:153], v[152:153], 1.0 op_sel_hi:[1,0]
	v_pk_add_f32 v[154:155], v[154:155], 1.0 op_sel_hi:[1,0]
	v_rcp_f32_e32 v152, v152
	v_rcp_f32_e32 v154, v154
	v_rcp_f32_e32 v153, v153
	v_rcp_f32_e32 v155, v155
	v_pk_mul_f32 v[144:145], v[144:145], v[150:151]
	v_pk_mul_f32 v[146:147], v[146:147], v[148:149]
	v_pk_mul_f32 v[144:145], v[144:145], v[152:153]
	v_pk_mul_f32 v[146:147], v[146:147], v[154:155]
	v_or_b32_e32 v158, 32, v221
	v_cvt_pk_bf16_f32 v146, v146, v147
	v_cvt_pk_bf16_f32 v147, v144, v145
	v_mov_b64_e32 v[144:145], s[40:41]
	v_mad_i64_i32 v[144:145], s[6:7], v158, s77, v[144:145]
	v_lshl_add_u64 v[160:161], v[196:197], 1, v[144:145]
	v_add_u32_e32 v162, v171, v211
	ds_bpermute_b32 v236, v244, v160
	ds_bpermute_b32 v237, v244, v161
	ds_bpermute_b32 v238, v244, v146
	ds_bpermute_b32 v239, v244, v147
	s_waitcnt lgkmcnt(0)
	global_store_dwordx2 v[236:237], v[238:239], off
	s_and_saveexec_b64 s[6:7], s[96:97]
	s_cbranch_execz .LBB0_1707
	v_mov_b64_e32 v[144:145], s[24:25]
	v_mad_i64_i32 v[144:145], vcc, v162, s76, v[144:145]
	v_lshl_add_u64 v[144:145], v[196:197], 2, v[144:145]
	global_store_dwordx4 v[144:145], v[140:143], off
	v_add_co_u32_e32 v144, vcc, 0x2000, v144
	s_nop 1
	v_addc_co_u32_e32 v145, vcc, 0, v145, vcc
	global_store_dwordx4 v[144:145], v[136:139], off offset:3072

; __device__ __forceinline__ unsigned pk2(float lo, float hi) { const f32x2 v = {lo, hi}; const bf16x2_t b = __builtin_convertvector(v, bf16x2_t); return __builtin_bit_cast(unsigned, b); }
; __device__ __forceinline__ f32x4 gelu_mul4(f32x4 x, f32x4 v) {
;     const f32x4 t = x * x;
;     const f32x4 u = t * (-2.0f * 0.7978845608028654f * 0.044715f * 1.4426950408889634f) + (-2.0f * 0.7978845608028654f * 1.4426950408889634f);
;     const f32x4 z = x * u;
;     f32x4 d; d[0] = __builtin_amdgcn_exp2f(z[0]); d[1] = __builtin_amdgcn_exp2f(z[1]); d[2] = __builtin_amdgcn_exp2f(z[2]); d[3] = __builtin_amdgcn_exp2f(z[3]);
;     d = d + 1.0f;
;     f32x4 r; r[0] = __builtin_amdgcn_rcpf(d[0]); r[1] = __builtin_amdgcn_rcpf(d[1]); r[2] = __builtin_amdgcn_rcpf(d[2]); r[3] = __builtin_amdgcn_rcpf(d[3]);
;     return (x * v) * r;
;     __device__ __forceinline__ void operator()(const f32x4 (&acc)[2][2][4][2], const pg8::Unit& u, int wr, int wc, int fr, int fq, PG8_LAS unsigned char* xl) const {
;     ...
;                         cc[bj] = bb[bj] + w0[bj] * p2 + w1[bj] * p1 + w2[bj] * cur;
;                     }
;                     const f32x4 gv = gelu_mul4(cc[0], cc[1]);
;                     u32x2 w; w.x = pk2(gv[0], gv[1]); w.y = pk2(gv[2], gv[3]);
;                     *(u32x2*)(G + (size_t)row * FF + jc0 + 4 * n) = w;
;                     if (!sample && ai == 0 && wr == 0 && m == 0 && fr < 2 && (pm & 7) != 0) {
; #pragma unroll
;                         for (int bj = 0; bj < 2; ++bj) *(f32x4*)(PH + (size_t)(pm * 2 + fr) * FF2 + bj * FF + jc0 + 4 * n) = cc[bj];
;                     }
;                     if (sample && (fr & 3) >= 2) { const int b = (row - MP) >> 2, t = fr & 3;
; #pragma unroll
;                         for (int bj = 0; bj < 2; ++bj) *(f32x4*)(nf_s + (size_t)(b * 2 + t - 2) * FF2 + bj * FF + jc0 + 4 * n) = acc[ai][bj][m][n];
;                     }
.LBB0_1715:
	v_pk_fma_f32 v[136:137], v[114:115], v[150:151], v[118:119]
	v_pk_fma_f32 v[138:139], v[112:113], v[148:149], v[116:117]
	v_pk_fma_f32 v[136:137], v[106:107], v[146:147], v[136:137]
	v_pk_fma_f32 v[138:139], v[104:105], v[144:145], v[138:139]
	v_pk_fma_f32 v[136:137], v[134:135], v[98:99], v[136:137]
	v_pk_fma_f32 v[138:139], v[132:133], v[96:97], v[138:139]
	v_pk_fma_f32 v[144:145], v[110:111], v[154:155], v[122:123]
	v_pk_fma_f32 v[146:147], v[108:109], v[152:153], v[120:121]
	v_pk_fma_f32 v[142:143], v[102:103], v[142:143], v[144:145]
	v_pk_fma_f32 v[140:141], v[100:101], v[140:141], v[146:147]
	v_pk_mul_f32 v[144:145], v[136:137], v[136:137]
	v_pk_mul_f32 v[146:147], v[138:139], v[138:139]
	v_mov_b64_e32 v[148:149], s[80:81]
	v_pk_fma_f32 v[144:145], v[144:145], s[82:83], v[148:149] op_sel_hi:[1,0,0]
	v_pk_fma_f32 v[146:147], v[146:147], s[82:83], v[148:149] op_sel_hi:[1,0,0]
	v_pk_mul_f32 v[144:145], v[136:137], v[144:145]
	v_pk_mul_f32 v[146:147], v[138:139], v[146:147]
	v_exp_f32_e32 v144, v144
	v_exp_f32_e32 v146, v146
	v_exp_f32_e32 v145, v145
	v_exp_f32_e32 v147, v147
	v_pk_fma_f32 v[142:143], v[130:131], v[94:95], v[142:143]
	v_pk_fma_f32 v[140:141], v[128:129], v[92:93], v[140:141]
	v_pk_add_f32 v[144:145], v[144:145], 1.0 op_sel_hi:[1,0]
	v_pk_add_f32 v[146:147], v[146:147], 1.0 op_sel_hi:[1,0]
	v_rcp_f32_e32 v144, v144
	v_rcp_f32_e32 v146, v146
	v_rcp_f32_e32 v145, v145
	v_rcp_f32_e32 v147, v147
	v_pk_mul_f32 v[136:137], v[136:137], v[142:143]
	v_pk_mul_f32 v[138:139], v[138:139], v[140:141]
	v_pk_mul_f32 v[136:137], v[136:137], v[144:145]
	v_pk_mul_f32 v[138:139], v[138:139], v[146:147]
	v_or_b32_e32 v150, 48, v221
	v_cvt_pk_bf16_f32 v138, v138, v139
	v_cvt_pk_bf16_f32 v139, v136, v137
	v_mov_b64_e32 v[136:137], s[40:41]
	v_mad_i64_i32 v[136:137], s[6:7], v150, s77, v[136:137]
	v_lshl_add_u64 v[152:153], v[196:197], 1, v[136:137]
	v_add_u32_e32 v154, v163, v211
	ds_bpermute_b32 v236, v244, v152
	ds_bpermute_b32 v237, v244, v153
	ds_bpermute_b32 v238, v244, v138
	ds_bpermute_b32 v239, v244, v139
	s_waitcnt lgkmcnt(0)
	global_store_dwordx2 v[236:237], v[238:239], off
	s_and_saveexec_b64 s[6:7], s[96:97]
	s_cbranch_execz .LBB0_1717
	v_mov_b64_e32 v[136:137], s[24:25]
	v_mad_i64_i32 v[136:137], vcc, v154, s76, v[136:137]
	v_lshl_add_u64 v[136:137], v[196:197], 2, v[136:137]
	global_store_dwordx4 v[136:137], v[132:135], off
	s_nop 1
	v_add_co_u32_e32 v132, vcc, 0x2000, v136
	s_nop 1
	v_addc_co_u32_e32 v133, vcc, 0, v137, vcc
	global_store_dwordx4 v[132:133], v[128:131], off offset:3072

; __device__ __forceinline__ unsigned pk2(float lo, float hi) { const f32x2 v = {lo, hi}; const bf16x2_t b = __builtin_convertvector(v, bf16x2_t); return __builtin_bit_cast(unsigned, b); }
; __device__ __forceinline__ f32x4 gelu_mul4(f32x4 x, f32x4 v) {
;     const f32x4 t = x * x;
;     const f32x4 u = t * (-2.0f * 0.7978845608028654f * 0.044715f * 1.4426950408889634f) + (-2.0f * 0.7978845608028654f * 1.4426950408889634f);
;     const f32x4 z = x * u;
;     f32x4 d; d[0] = __builtin_amdgcn_exp2f(z[0]); d[1] = __builtin_amdgcn_exp2f(z[1]); d[2] = __builtin_amdgcn_exp2f(z[2]); d[3] = __builtin_amdgcn_exp2f(z[3]);
;     d = d + 1.0f;
;     f32x4 r; r[0] = __builtin_amdgcn_rcpf(d[0]); r[1] = __builtin_amdgcn_rcpf(d[1]); r[2] = __builtin_amdgcn_rcpf(d[2]); r[3] = __builtin_amdgcn_rcpf(d[3]);
;     return (x * v) * r;
;     __device__ __forceinline__ void operator()(const f32x4 (&acc)[2][2][4][2], const pg8::Unit& u, int wr, int wc, int fr, int fq, PG8_LAS unsigned char* xl) const {
;     ...
;                         cc[bj] = bb[bj] + w0[bj] * p2 + w1[bj] * p1 + w2[bj] * cur;
;                     }
;                     const f32x4 gv = gelu_mul4(cc[0], cc[1]);
;                     u32x2 w; w.x = pk2(gv[0], gv[1]); w.y = pk2(gv[2], gv[3]);
;                     *(u32x2*)(G + (size_t)row * FF + jc0 + 4 * n) = w;
;                     if (!sample && ai == 0 && wr == 0 && m == 0 && fr < 2 && (pm & 7) != 0) {
; #pragma unroll
;                         for (int bj = 0; bj < 2; ++bj) *(f32x4*)(PH + (size_t)(pm * 2 + fr) * FF2 + bj * FF + jc0 + 4 * n) = cc[bj];
;                     }
;                     if (sample && (fr & 3) >= 2) { const int b = (row - MP) >> 2, t = fr & 3;
; #pragma unroll
;                         for (int bj = 0; bj < 2; ++bj) *(f32x4*)(nf_s + (size_t)(b * 2 + t - 2) * FF2 + bj * FF + jc0 + 4 * n) = acc[ai][bj][m][n];
;                     }
.LBB0_1727:
	s_waitcnt lgkmcnt(0)
	v_pk_fma_f32 v[128:129], v[114:115], v[138:139], v[118:119]
	v_pk_fma_f32 v[130:131], v[112:113], v[136:137], v[116:117]
	v_pk_fma_f32 v[128:129], v[106:107], v[134:135], v[128:129]
	v_pk_fma_f32 v[130:131], v[104:105], v[132:133], v[130:131]
	v_pk_fma_f32 v[128:129], v[126:127], v[98:99], v[128:129]
	v_pk_fma_f32 v[130:131], v[124:125], v[96:97], v[130:131]
	v_pk_fma_f32 v[134:135], v[108:109], v[144:145], v[120:121]
	v_pk_mul_f32 v[136:137], v[128:129], v[128:129]
	v_pk_fma_f32 v[134:135], v[100:101], v[140:141], v[134:135]
	v_pk_mul_f32 v[138:139], v[130:131], v[130:131]
	v_mov_b64_e32 v[140:141], s[80:81]
	v_pk_fma_f32 v[136:137], v[136:137], s[82:83], v[140:141] op_sel_hi:[1,0,0]
	v_pk_fma_f32 v[138:139], v[138:139], s[82:83], v[140:141] op_sel_hi:[1,0,0]
	v_pk_mul_f32 v[136:137], v[128:129], v[136:137]
	v_pk_mul_f32 v[138:139], v[130:131], v[138:139]
	v_exp_f32_e32 v136, v136
	v_exp_f32_e32 v138, v138
	v_exp_f32_e32 v137, v137
	v_exp_f32_e32 v139, v139
	v_pk_fma_f32 v[132:133], v[110:111], v[146:147], v[122:123]
	v_pk_fma_f32 v[134:135], v[88:89], v[92:93], v[134:135]
	v_pk_add_f32 v[136:137], v[136:137], 1.0 op_sel_hi:[1,0]
	v_pk_add_f32 v[138:139], v[138:139], 1.0 op_sel_hi:[1,0]
	v_rcp_f32_e32 v136, v136
	v_rcp_f32_e32 v138, v138
	v_rcp_f32_e32 v137, v137
	v_rcp_f32_e32 v139, v139
	v_pk_fma_f32 v[132:133], v[102:103], v[142:143], v[132:133]
	v_pk_mul_f32 v[130:131], v[130:131], v[134:135]
	v_pk_fma_f32 v[132:133], v[90:91], v[94:95], v[132:133]
	v_pk_mul_f32 v[130:131], v[130:131], v[138:139]
	v_pk_mul_f32 v[128:129], v[128:129], v[132:133]
	v_add_u32_e32 v163, 0x80, v221
	v_pk_mul_f32 v[128:129], v[128:129], v[136:137]
	v_cvt_pk_bf16_f32 v130, v130, v131
	v_cvt_pk_bf16_f32 v131, v128, v129
	v_mov_b64_e32 v[128:129], s[40:41]
	v_mad_i64_i32 v[128:129], s[6:7], v163, s77, v[128:129]
	v_lshl_add_u64 v[144:145], v[196:197], 1, v[128:129]
	v_add_u32_e32 v146, v155, v211
	ds_bpermute_b32 v236, v244, v144
	ds_bpermute_b32 v237, v244, v145
	ds_bpermute_b32 v238, v244, v130
	ds_bpermute_b32 v239, v244, v131
	s_waitcnt lgkmcnt(0)
	global_store_dwordx2 v[236:237], v[238:239], off
	s_and_saveexec_b64 s[6:7], s[96:97]
	s_cbranch_execz .LBB0_1729
	v_mov_b64_e32 v[128:129], s[24:25]
	v_mad_i64_i32 v[128:129], vcc, v146, s76, v[128:129]
	v_lshl_add_u64 v[128:129], v[196:197], 2, v[128:129]
	global_store_dwordx4 v[128:129], v[124:127], off
	v_add_co_u32_e32 v128, vcc, 0x2000, v128
	s_nop 1
	v_addc_co_u32_e32 v129, vcc, 0, v129, vcc
	global_store_dwordx4 v[128:129], v[88:91], off offset:3072

; __device__ __forceinline__ unsigned pk2(float lo, float hi) { const f32x2 v = {lo, hi}; const bf16x2_t b = __builtin_convertvector(v, bf16x2_t); return __builtin_bit_cast(unsigned, b); }
; __device__ __forceinline__ f32x4 gelu_mul4(f32x4 x, f32x4 v) {
;     const f32x4 t = x * x;
;     const f32x4 u = t * (-2.0f * 0.7978845608028654f * 0.044715f * 1.4426950408889634f) + (-2.0f * 0.7978845608028654f * 1.4426950408889634f);
;     const f32x4 z = x * u;
;     f32x4 d; d[0] = __builtin_amdgcn_exp2f(z[0]); d[1] = __builtin_amdgcn_exp2f(z[1]); d[2] = __builtin_amdgcn_exp2f(z[2]); d[3] = __builtin_amdgcn_exp2f(z[3]);
;     d = d + 1.0f;
;     f32x4 r; r[0] = __builtin_amdgcn_rcpf(d[0]); r[1] = __builtin_amdgcn_rcpf(d[1]); r[2] = __builtin_amdgcn_rcpf(d[2]); r[3] = __builtin_amdgcn_rcpf(d[3]);
;     return (x * v) * r;
;     __device__ __forceinline__ void operator()(const f32x4 (&acc)[2][2][4][2], const pg8::Unit& u, int wr, int wc, int fr, int fq, PG8_LAS unsigned char* xl) const {
;     ...
;                         cc[bj] = bb[bj] + w0[bj] * p2 + w1[bj] * p1 + w2[bj] * cur;
;                     }
;                     const f32x4 gv = gelu_mul4(cc[0], cc[1]);
;                     u32x2 w; w.x = pk2(gv[0], gv[1]); w.y = pk2(gv[2], gv[3]);
;                     *(u32x2*)(G + (size_t)row * FF + jc0 + 4 * n) = w;
;                     if (!sample && ai == 0 && wr == 0 && m == 0 && fr < 2 && (pm & 7) != 0) {
; #pragma unroll
;                         for (int bj = 0; bj < 2; ++bj) *(f32x4*)(PH + (size_t)(pm * 2 + fr) * FF2 + bj * FF + jc0 + 4 * n) = cc[bj];
;                     }
;                     if (sample && (fr & 3) >= 2) { const int b = (row - MP) >> 2, t = fr & 3;
; #pragma unroll
;                         for (int bj = 0; bj < 2; ++bj) *(f32x4*)(nf_s + (size_t)(b * 2 + t - 2) * FF2 + bj * FF + jc0 + 4 * n) = acc[ai][bj][m][n];
;                     }
.LBB0_1737:
	v_pk_fma_f32 v[88:89], v[114:115], v[134:135], v[118:119]
	v_pk_fma_f32 v[90:91], v[112:113], v[132:133], v[116:117]
	v_pk_fma_f32 v[88:89], v[106:107], v[130:131], v[88:89]
	v_pk_fma_f32 v[90:91], v[104:105], v[128:129], v[90:91]
	v_pk_fma_f32 v[88:89], v[86:87], v[98:99], v[88:89]
	v_pk_fma_f32 v[90:91], v[84:85], v[96:97], v[90:91]
	v_pk_fma_f32 v[128:129], v[110:111], v[138:139], v[122:123]
	v_pk_fma_f32 v[130:131], v[108:109], v[136:137], v[120:121]
	v_pk_fma_f32 v[126:127], v[102:103], v[126:127], v[128:129]
	v_pk_fma_f32 v[124:125], v[100:101], v[124:125], v[130:131]
	v_pk_mul_f32 v[128:129], v[88:89], v[88:89]
	v_pk_mul_f32 v[130:131], v[90:91], v[90:91]
	v_mov_b64_e32 v[132:133], s[80:81]
	v_pk_fma_f32 v[128:129], v[128:129], s[82:83], v[132:133] op_sel_hi:[1,0,0]
	v_pk_fma_f32 v[130:131], v[130:131], s[82:83], v[132:133] op_sel_hi:[1,0,0]
	v_pk_mul_f32 v[128:129], v[88:89], v[128:129]
	v_pk_mul_f32 v[130:131], v[90:91], v[130:131]
	v_exp_f32_e32 v128, v128
	v_exp_f32_e32 v130, v130
	v_exp_f32_e32 v129, v129
	v_exp_f32_e32 v131, v131
	v_pk_fma_f32 v[126:127], v[82:83], v[94:95], v[126:127]
	v_pk_fma_f32 v[124:125], v[80:81], v[92:93], v[124:125]
	v_pk_add_f32 v[128:129], v[128:129], 1.0 op_sel_hi:[1,0]
	v_pk_add_f32 v[130:131], v[130:131], 1.0 op_sel_hi:[1,0]
	v_rcp_f32_e32 v128, v128
	v_rcp_f32_e32 v130, v130
	v_rcp_f32_e32 v129, v129
	v_rcp_f32_e32 v131, v131
	v_pk_mul_f32 v[88:89], v[88:89], v[126:127]
	v_pk_mul_f32 v[90:91], v[90:91], v[124:125]
	v_pk_mul_f32 v[88:89], v[88:89], v[128:129]
	v_pk_mul_f32 v[90:91], v[90:91], v[130:131]
	v_add_u32_e32 v134, 0x90, v221
	v_cvt_pk_bf16_f32 v90, v90, v91
	v_cvt_pk_bf16_f32 v91, v88, v89
	v_mov_b64_e32 v[88:89], s[40:41]
	v_mad_i64_i32 v[88:89], s[6:7], v134, s77, v[88:89]
	v_lshl_add_u64 v[136:137], v[196:197], 1, v[88:89]
	v_add_u32_e32 v138, v147, v211
	ds_bpermute_b32 v236, v244, v136
	ds_bpermute_b32 v237, v244, v137
	ds_bpermute_b32 v238, v244, v90
	ds_bpermute_b32 v239, v244, v91
	s_waitcnt lgkmcnt(0)
	global_store_dwordx2 v[236:237], v[238:239], off
	s_and_saveexec_b64 s[6:7], s[96:97]
	s_cbranch_execz .LBB0_1739
	v_mov_b64_e32 v[88:89], s[24:25]
	v_mad_i64_i32 v[88:89], vcc, v138, s76, v[88:89]
	v_lshl_add_u64 v[88:89], v[196:197], 2, v[88:89]
	global_store_dwordx4 v[88:89], v[84:87], off
	v_add_co_u32_e32 v88, vcc, 0x2000, v88
	s_nop 1
	v_addc_co_u32_e32 v89, vcc, 0, v89, vcc
	global_store_dwordx4 v[88:89], v[80:83], off offset:3072

; __device__ __forceinline__ unsigned pk2(float lo, float hi) { const f32x2 v = {lo, hi}; const bf16x2_t b = __builtin_convertvector(v, bf16x2_t); return __builtin_bit_cast(unsigned, b); }
; __device__ __forceinline__ f32x4 gelu_mul4(f32x4 x, f32x4 v) {
;     const f32x4 t = x * x;
;     const f32x4 u = t * (-2.0f * 0.7978845608028654f * 0.044715f * 1.4426950408889634f) + (-2.0f * 0.7978845608028654f * 1.4426950408889634f);
;     const f32x4 z = x * u;
;     f32x4 d; d[0] = __builtin_amdgcn_exp2f(z[0]); d[1] = __builtin_amdgcn_exp2f(z[1]); d[2] = __builtin_amdgcn_exp2f(z[2]); d[3] = __builtin_amdgcn_exp2f(z[3]);
;     d = d + 1.0f;
;     f32x4 r; r[0] = __builtin_amdgcn_rcpf(d[0]); r[1] = __builtin_amdgcn_rcpf(d[1]); r[2] = __builtin_amdgcn_rcpf(d[2]); r[3] = __builtin_amdgcn_rcpf(d[3]);
;     return (x * v) * r;
;     __device__ __forceinline__ void operator()(const f32x4 (&acc)[2][2][4][2], const pg8::Unit& u, int wr, int wc, int fr, int fq, PG8_LAS unsigned char* xl) const {
;     ...
;                         cc[bj] = bb[bj] + w0[bj] * p2 + w1[bj] * p1 + w2[bj] * cur;
;                     }
;                     const f32x4 gv = gelu_mul4(cc[0], cc[1]);
;                     u32x2 w; w.x = pk2(gv[0], gv[1]); w.y = pk2(gv[2], gv[3]);
;                     *(u32x2*)(G + (size_t)row * FF + jc0 + 4 * n) = w;
;                     if (!sample && ai == 0 && wr == 0 && m == 0 && fr < 2 && (pm & 7) != 0) {
; #pragma unroll
;                         for (int bj = 0; bj < 2; ++bj) *(f32x4*)(PH + (size_t)(pm * 2 + fr) * FF2 + bj * FF + jc0 + 4 * n) = cc[bj];
;                     }
;                     if (sample && (fr & 3) >= 2) { const int b = (row - MP) >> 2, t = fr & 3;
; #pragma unroll
;                         for (int bj = 0; bj < 2; ++bj) *(f32x4*)(nf_s + (size_t)(b * 2 + t - 2) * FF2 + bj * FF + jc0 + 4 * n) = acc[ai][bj][m][n];
;                     }
.LBB0_1747:
	v_pk_fma_f32 v[80:81], v[114:115], v[126:127], v[118:119]
	v_pk_fma_f32 v[82:83], v[112:113], v[124:125], v[116:117]
	v_pk_fma_f32 v[80:81], v[106:107], v[90:91], v[80:81]
	v_pk_fma_f32 v[82:83], v[104:105], v[88:89], v[82:83]
	v_pk_fma_f32 v[80:81], v[78:79], v[98:99], v[80:81]
	v_pk_fma_f32 v[82:83], v[76:77], v[96:97], v[82:83]
	v_pk_fma_f32 v[88:89], v[110:111], v[130:131], v[122:123]
	v_pk_fma_f32 v[90:91], v[108:109], v[128:129], v[120:121]
	v_pk_fma_f32 v[86:87], v[102:103], v[86:87], v[88:89]
	v_pk_fma_f32 v[84:85], v[100:101], v[84:85], v[90:91]
	v_pk_mul_f32 v[88:89], v[80:81], v[80:81]
	v_pk_mul_f32 v[90:91], v[82:83], v[82:83]
	v_mov_b64_e32 v[124:125], s[80:81]
	v_pk_fma_f32 v[88:89], v[88:89], s[82:83], v[124:125] op_sel_hi:[1,0,0]
	v_pk_fma_f32 v[90:91], v[90:91], s[82:83], v[124:125] op_sel_hi:[1,0,0]
	v_pk_mul_f32 v[88:89], v[80:81], v[88:89]
	v_pk_mul_f32 v[90:91], v[82:83], v[90:91]
	v_exp_f32_e32 v88, v88
	v_exp_f32_e32 v90, v90
	v_exp_f32_e32 v89, v89
	v_exp_f32_e32 v91, v91
	v_pk_fma_f32 v[86:87], v[74:75], v[94:95], v[86:87]
	v_pk_fma_f32 v[84:85], v[72:73], v[92:93], v[84:85]
	v_pk_add_f32 v[88:89], v[88:89], 1.0 op_sel_hi:[1,0]
	v_pk_add_f32 v[90:91], v[90:91], 1.0 op_sel_hi:[1,0]
	v_rcp_f32_e32 v88, v88
	v_rcp_f32_e32 v90, v90
	v_rcp_f32_e32 v89, v89
	v_rcp_f32_e32 v91, v91
	v_pk_mul_f32 v[80:81], v[80:81], v[86:87]
	v_pk_mul_f32 v[82:83], v[82:83], v[84:85]
	v_pk_mul_f32 v[80:81], v[80:81], v[88:89]
	v_pk_mul_f32 v[82:83], v[82:83], v[90:91]
	v_add_u32_e32 v126, 0xa0, v221
	v_cvt_pk_bf16_f32 v82, v82, v83
	v_cvt_pk_bf16_f32 v83, v80, v81
	v_mov_b64_e32 v[80:81], s[40:41]
	v_mad_i64_i32 v[80:81], s[6:7], v126, s77, v[80:81]
	v_lshl_add_u64 v[128:129], v[196:197], 1, v[80:81]
	v_add_u32_e32 v139, v139, v211
	ds_bpermute_b32 v236, v244, v128
	ds_bpermute_b32 v237, v244, v129
	ds_bpermute_b32 v238, v244, v82
	ds_bpermute_b32 v239, v244, v83
	s_waitcnt lgkmcnt(0)
	global_store_dwordx2 v[236:237], v[238:239], off
	s_and_saveexec_b64 s[6:7], s[96:97]
	s_cbranch_execz .LBB0_1749
	v_mov_b64_e32 v[80:81], s[24:25]
	v_mad_i64_i32 v[80:81], vcc, v139, s76, v[80:81]
	v_lshl_add_u64 v[80:81], v[196:197], 2, v[80:81]
	global_store_dwordx4 v[80:81], v[76:79], off
	v_add_co_u32_e32 v80, vcc, 0x2000, v80
	s_nop 1
	v_addc_co_u32_e32 v81, vcc, 0, v81, vcc
	global_store_dwordx4 v[80:81], v[72:75], off offset:3072

; __device__ __forceinline__ unsigned pk2(float lo, float hi) { const f32x2 v = {lo, hi}; const bf16x2_t b = __builtin_convertvector(v, bf16x2_t); return __builtin_bit_cast(unsigned, b); }
; __device__ __forceinline__ f32x4 gelu_mul4(f32x4 x, f32x4 v) {
;     const f32x4 t = x * x;
;     const f32x4 u = t * (-2.0f * 0.7978845608028654f * 0.044715f * 1.4426950408889634f) + (-2.0f * 0.7978845608028654f * 1.4426950408889634f);
;     const f32x4 z = x * u;
;     f32x4 d; d[0] = __builtin_amdgcn_exp2f(z[0]); d[1] = __builtin_amdgcn_exp2f(z[1]); d[2] = __builtin_amdgcn_exp2f(z[2]); d[3] = __builtin_amdgcn_exp2f(z[3]);
;     d = d + 1.0f;
;     f32x4 r; r[0] = __builtin_amdgcn_rcpf(d[0]); r[1] = __builtin_amdgcn_rcpf(d[1]); r[2] = __builtin_amdgcn_rcpf(d[2]); r[3] = __builtin_amdgcn_rcpf(d[3]);
;     return (x * v) * r;
;     __device__ __forceinline__ void operator()(const f32x4 (&acc)[2][2][4][2], const pg8::Unit& u, int wr, int wc, int fr, int fq, PG8_LAS unsigned char* xl) const {
;     ...
;                         cc[bj] = bb[bj] + w0[bj] * p2 + w1[bj] * p1 + w2[bj] * cur;
;                     }
;                     const f32x4 gv = gelu_mul4(cc[0], cc[1]);
;                     u32x2 w; w.x = pk2(gv[0], gv[1]); w.y = pk2(gv[2], gv[3]);
;                     *(u32x2*)(G + (size_t)row * FF + jc0 + 4 * n) = w;
;                     if (!sample && ai == 0 && wr == 0 && m == 0 && fr < 2 && (pm & 7) != 0) {
; #pragma unroll
;                         for (int bj = 0; bj < 2; ++bj) *(f32x4*)(PH + (size_t)(pm * 2 + fr) * FF2 + bj * FF + jc0 + 4 * n) = cc[bj];
;                     }
;                     if (sample && (fr & 3) >= 2) { const int b = (row - MP) >> 2, t = fr & 3;
; #pragma unroll
;                         for (int bj = 0; bj < 2; ++bj) *(f32x4*)(nf_s + (size_t)(b * 2 + t - 2) * FF2 + bj * FF + jc0 + 4 * n) = acc[ai][bj][m][n];
;                     }
.LBB0_1757:
	v_pk_fma_f32 v[72:73], v[114:115], v[86:87], v[118:119]
	v_pk_fma_f32 v[74:75], v[112:113], v[84:85], v[116:117]
	v_pk_fma_f32 v[72:73], v[106:107], v[82:83], v[72:73]
	v_pk_fma_f32 v[74:75], v[104:105], v[80:81], v[74:75]
	v_pk_fma_f32 v[72:73], v[14:15], v[98:99], v[72:73]
	v_pk_fma_f32 v[74:75], v[12:13], v[96:97], v[74:75]
	v_pk_fma_f32 v[80:81], v[110:111], v[90:91], v[122:123]
	v_pk_fma_f32 v[82:83], v[108:109], v[88:89], v[120:121]
	v_pk_fma_f32 v[78:79], v[102:103], v[78:79], v[80:81]
	v_pk_fma_f32 v[76:77], v[100:101], v[76:77], v[82:83]
	v_pk_mul_f32 v[80:81], v[72:73], v[72:73]
	v_pk_mul_f32 v[82:83], v[74:75], v[74:75]
	v_mov_b64_e32 v[84:85], s[80:81]
	v_pk_fma_f32 v[80:81], v[80:81], s[82:83], v[84:85] op_sel_hi:[1,0,0]
	v_pk_fma_f32 v[82:83], v[82:83], s[82:83], v[84:85] op_sel_hi:[1,0,0]
	v_pk_mul_f32 v[80:81], v[72:73], v[80:81]
	v_pk_mul_f32 v[82:83], v[74:75], v[82:83]
	v_exp_f32_e32 v80, v80
	v_exp_f32_e32 v82, v82
	v_exp_f32_e32 v81, v81
	v_exp_f32_e32 v83, v83
	v_pk_fma_f32 v[78:79], v[6:7], v[94:95], v[78:79]
	v_pk_fma_f32 v[76:77], v[4:5], v[92:93], v[76:77]
	v_pk_add_f32 v[80:81], v[80:81], 1.0 op_sel_hi:[1,0]
	v_pk_add_f32 v[82:83], v[82:83], 1.0 op_sel_hi:[1,0]
	v_rcp_f32_e32 v80, v80
	v_rcp_f32_e32 v82, v82
	v_rcp_f32_e32 v81, v81
	v_rcp_f32_e32 v83, v83
	v_pk_mul_f32 v[72:73], v[72:73], v[78:79]
	v_pk_mul_f32 v[74:75], v[74:75], v[76:77]
	v_pk_mul_f32 v[72:73], v[72:73], v[80:81]
	v_pk_mul_f32 v[74:75], v[74:75], v[82:83]
	v_add_u32_e32 v86, 0xb0, v221
	v_cvt_pk_bf16_f32 v74, v74, v75
	v_cvt_pk_bf16_f32 v75, v72, v73
	v_mov_b64_e32 v[72:73], s[40:41]
	v_mad_i64_i32 v[72:73], s[6:7], v86, s77, v[72:73]
	v_lshl_add_u64 v[130:131], v[196:197], 1, v[72:73]
	v_add_u32_e32 v147, v147, v211
	ds_bpermute_b32 v236, v244, v130
	ds_bpermute_b32 v237, v244, v131
	ds_bpermute_b32 v238, v244, v74
	ds_bpermute_b32 v239, v244, v75
	s_waitcnt lgkmcnt(0)
	global_store_dwordx2 v[236:237], v[238:239], off
	s_and_saveexec_b64 s[6:7], s[96:97]
	s_cbranch_execz .LBB0_1759
	v_mov_b64_e32 v[72:73], s[24:25]
	v_mad_i64_i32 v[72:73], vcc, v147, s76, v[72:73]
	v_lshl_add_u64 v[72:73], v[196:197], 2, v[72:73]
	global_store_dwordx4 v[72:73], v[12:15], off
	v_add_co_u32_e32 v72, vcc, 0x2000, v72
	s_nop 1
	v_addc_co_u32_e32 v73, vcc, 0, v73, vcc
	global_store_dwordx4 v[72:73], v[4:7], off offset:3072

; __device__ __forceinline__ unsigned pk2(float lo, float hi) { const f32x2 v = {lo, hi}; const bf16x2_t b = __builtin_convertvector(v, bf16x2_t); return __builtin_bit_cast(unsigned, b); }
; __device__ __forceinline__ f32x4 gelu_mul4(f32x4 x, f32x4 v) {
;     const f32x4 t = x * x;
;     const f32x4 u = t * (-2.0f * 0.7978845608028654f * 0.044715f * 1.4426950408889634f) + (-2.0f * 0.7978845608028654f * 1.4426950408889634f);
;     const f32x4 z = x * u;
;     f32x4 d; d[0] = __builtin_amdgcn_exp2f(z[0]); d[1] = __builtin_amdgcn_exp2f(z[1]); d[2] = __builtin_amdgcn_exp2f(z[2]); d[3] = __builtin_amdgcn_exp2f(z[3]);
;     d = d + 1.0f;
;     f32x4 r; r[0] = __builtin_amdgcn_rcpf(d[0]); r[1] = __builtin_amdgcn_rcpf(d[1]); r[2] = __builtin_amdgcn_rcpf(d[2]); r[3] = __builtin_amdgcn_rcpf(d[3]);
;     return (x * v) * r;
;     __device__ __forceinline__ void operator()(const f32x4 (&acc)[2][2][4][2], const pg8::Unit& u, int wr, int wc, int fr, int fq, PG8_LAS unsigned char* xl) const {
;     ...
;                         cc[bj] = bb[bj] + w0[bj] * p2 + w1[bj] * p1 + w2[bj] * cur;
;                     }
;                     const f32x4 gv = gelu_mul4(cc[0], cc[1]);
;                     u32x2 w; w.x = pk2(gv[0], gv[1]); w.y = pk2(gv[2], gv[3]);
;                     *(u32x2*)(G + (size_t)row * FF + jc0 + 4 * n) = w;
;                     if (!sample && ai == 0 && wr == 0 && m == 0 && fr < 2 && (pm & 7) != 0) {
; #pragma unroll
;                         for (int bj = 0; bj < 2; ++bj) *(f32x4*)(PH + (size_t)(pm * 2 + fr) * FF2 + bj * FF + jc0 + 4 * n) = cc[bj];
;                     }
;                     if (sample && (fr & 3) >= 2) { const int b = (row - MP) >> 2, t = fr & 3;
; #pragma unroll
;                         for (int bj = 0; bj < 2; ++bj) *(f32x4*)(nf_s + (size_t)(b * 2 + t - 2) * FF2 + bj * FF + jc0 + 4 * n) = acc[ai][bj][m][n];
;                     }
.LBB0_1769:
	s_waitcnt vmcnt(5) lgkmcnt(0)
	v_pk_fma_f32 v[104:105], v[98:99], v[114:115], v[102:103]
	v_pk_fma_f32 v[106:107], v[96:97], v[112:113], v[100:101]
	v_pk_fma_f32 v[104:105], v[90:91], v[110:111], v[104:105]
	v_pk_fma_f32 v[108:109], v[88:89], v[108:109], v[106:107]
	s_waitcnt vmcnt(4)
	v_pk_fma_f32 v[106:107], v[70:71], v[82:83], v[104:105]
	v_pk_fma_f32 v[104:105], v[68:69], v[80:81], v[108:109]
	s_waitcnt vmcnt(0)
	v_pk_fma_f32 v[110:111], v[84:85], v[120:121], v[92:93]
	v_pk_mul_f32 v[114:115], v[104:105], v[104:105]
	v_pk_fma_f32 v[112:113], v[76:77], v[116:117], v[110:111]
	v_pk_mul_f32 v[110:111], v[106:107], v[106:107]
	v_mov_b64_e32 v[116:117], s[80:81]
	v_pk_fma_f32 v[110:111], v[110:111], s[82:83], v[116:117] op_sel_hi:[1,0,0]
	v_pk_fma_f32 v[114:115], v[114:115], s[82:83], v[116:117] op_sel_hi:[1,0,0]
	v_pk_mul_f32 v[110:111], v[106:107], v[110:111]
	v_pk_mul_f32 v[114:115], v[104:105], v[114:115]
	v_exp_f32_e32 v116, v110
	v_exp_f32_e32 v114, v114
	v_exp_f32_e32 v117, v111
	v_exp_f32_e32 v115, v115
	v_pk_fma_f32 v[108:109], v[86:87], v[122:123], v[94:95]
	v_pk_add_f32 v[114:115], v[114:115], 1.0 op_sel_hi:[1,0]
	v_pk_fma_f32 v[108:109], v[78:79], v[118:119], v[108:109]
	v_rcp_f32_e32 v114, v114
	v_pk_fma_f32 v[110:111], v[66:67], v[74:75], v[108:109]
	v_pk_fma_f32 v[108:109], v[64:65], v[72:73], v[112:113]
	v_pk_add_f32 v[112:113], v[116:117], 1.0 op_sel_hi:[1,0]
	v_rcp_f32_e32 v115, v115
	v_rcp_f32_e32 v112, v112
	v_rcp_f32_e32 v113, v113
	v_pk_mul_f32 v[116:117], v[106:107], v[110:111]
	v_pk_mul_f32 v[118:119], v[104:105], v[108:109]
	v_pk_mul_f32 v[112:113], v[116:117], v[112:113]
	v_pk_mul_f32 v[114:115], v[118:119], v[114:115]
	s_nop 0
	v_cvt_pk_bf16_f32 v114, v114, v115
	v_cvt_pk_bf16_f32 v115, v112, v113
	ds_bpermute_b32 v236, v244, v178
	ds_bpermute_b32 v237, v244, v179
	ds_bpermute_b32 v238, v244, v114
	ds_bpermute_b32 v239, v244, v115
	s_waitcnt lgkmcnt(0)
	global_store_dwordx2 v[236:237], v[238:239], off offset:8
	s_and_saveexec_b64 s[6:7], s[58:59]
	s_cbranch_execz .LBB0_1771
	global_store_dwordx4 v[176:177], v[104:107], off offset:16
	s_nop 1
	v_add_co_u32_e32 v104, vcc, 0x2000, v176
	s_nop 1
	v_addc_co_u32_e32 v105, vcc, 0, v177, vcc
	global_store_dwordx4 v[104:105], v[108:111], off offset:3088
	s_or_b64 exec, exec, s[6:7]
	s_and_saveexec_b64 s[6:7], s[96:97]
	s_cbranch_execz .LBB0_1773
	s_branch .LBB0_1772

; __device__ __forceinline__ unsigned pk2(float lo, float hi) { const f32x2 v = {lo, hi}; const bf16x2_t b = __builtin_convertvector(v, bf16x2_t); return __builtin_bit_cast(unsigned, b); }
; __device__ __forceinline__ f32x4 gelu_mul4(f32x4 x, f32x4 v) {
;     const f32x4 t = x * x;
;     const f32x4 u = t * (-2.0f * 0.7978845608028654f * 0.044715f * 1.4426950408889634f) + (-2.0f * 0.7978845608028654f * 1.4426950408889634f);
;     const f32x4 z = x * u;
;     f32x4 d; d[0] = __builtin_amdgcn_exp2f(z[0]); d[1] = __builtin_amdgcn_exp2f(z[1]); d[2] = __builtin_amdgcn_exp2f(z[2]); d[3] = __builtin_amdgcn_exp2f(z[3]);
;     d = d + 1.0f;
;     f32x4 r; r[0] = __builtin_amdgcn_rcpf(d[0]); r[1] = __builtin_amdgcn_rcpf(d[1]); r[2] = __builtin_amdgcn_rcpf(d[2]); r[3] = __builtin_amdgcn_rcpf(d[3]);
;     return (x * v) * r;
;     __device__ __forceinline__ void operator()(const f32x4 (&acc)[2][2][4][2], const pg8::Unit& u, int wr, int wc, int fr, int fq, PG8_LAS unsigned char* xl) const {
;     ...
;                         cc[bj] = bb[bj] + w0[bj] * p2 + w1[bj] * p1 + w2[bj] * cur;
;                     }
;                     const f32x4 gv = gelu_mul4(cc[0], cc[1]);
;                     u32x2 w; w.x = pk2(gv[0], gv[1]); w.y = pk2(gv[2], gv[3]);
;                     *(u32x2*)(G + (size_t)row * FF + jc0 + 4 * n) = w;
;                     if (!sample && ai == 0 && wr == 0 && m == 0 && fr < 2 && (pm & 7) != 0) {
; #pragma unroll
;                         for (int bj = 0; bj < 2; ++bj) *(f32x4*)(PH + (size_t)(pm * 2 + fr) * FF2 + bj * FF + jc0 + 4 * n) = cc[bj];
;                     }
;                     if (sample && (fr & 3) >= 2) { const int b = (row - MP) >> 2, t = fr & 3;
; #pragma unroll
;                         for (int bj = 0; bj < 2; ++bj) *(f32x4*)(nf_s + (size_t)(b * 2 + t - 2) * FF2 + bj * FF + jc0 + 4 * n) = acc[ai][bj][m][n];
;                     }
.LBB0_1781:
	v_pk_fma_f32 v[64:65], v[98:99], v[110:111], v[102:103]
	v_pk_fma_f32 v[66:67], v[96:97], v[108:109], v[100:101]
	v_pk_fma_f32 v[64:65], v[90:91], v[106:107], v[64:65]
	v_pk_fma_f32 v[66:67], v[88:89], v[104:105], v[66:67]
	v_pk_fma_f32 v[64:65], v[62:63], v[82:83], v[64:65]
	v_pk_fma_f32 v[66:67], v[60:61], v[80:81], v[66:67]
	v_pk_fma_f32 v[104:105], v[86:87], v[114:115], v[94:95]
	v_pk_fma_f32 v[106:107], v[84:85], v[112:113], v[92:93]
	v_pk_fma_f32 v[70:71], v[78:79], v[70:71], v[104:105]
	v_pk_fma_f32 v[68:69], v[76:77], v[68:69], v[106:107]
	v_pk_mul_f32 v[104:105], v[64:65], v[64:65]
	v_pk_mul_f32 v[106:107], v[66:67], v[66:67]
	v_mov_b64_e32 v[108:109], s[80:81]
	v_pk_fma_f32 v[104:105], v[104:105], s[82:83], v[108:109] op_sel_hi:[1,0,0]
	v_pk_fma_f32 v[106:107], v[106:107], s[82:83], v[108:109] op_sel_hi:[1,0,0]
	v_pk_mul_f32 v[104:105], v[64:65], v[104:105]
	v_pk_mul_f32 v[106:107], v[66:67], v[106:107]
	v_exp_f32_e32 v104, v104
	v_exp_f32_e32 v106, v106
	v_exp_f32_e32 v105, v105
	v_exp_f32_e32 v107, v107
	v_pk_fma_f32 v[70:71], v[58:59], v[74:75], v[70:71]
	v_pk_fma_f32 v[68:69], v[56:57], v[72:73], v[68:69]
	v_pk_add_f32 v[104:105], v[104:105], 1.0 op_sel_hi:[1,0]
	v_pk_add_f32 v[106:107], v[106:107], 1.0 op_sel_hi:[1,0]
	v_rcp_f32_e32 v104, v104
	v_rcp_f32_e32 v106, v106
	v_rcp_f32_e32 v105, v105
	v_rcp_f32_e32 v107, v107
	v_pk_mul_f32 v[64:65], v[64:65], v[70:71]
	v_pk_mul_f32 v[66:67], v[66:67], v[68:69]
	v_pk_mul_f32 v[64:65], v[64:65], v[104:105]
	v_pk_mul_f32 v[66:67], v[66:67], v[106:107]
	s_nop 0
	v_cvt_pk_bf16_f32 v66, v66, v67
	v_cvt_pk_bf16_f32 v67, v64, v65
	ds_bpermute_b32 v236, v244, v168
	ds_bpermute_b32 v237, v244, v169
	ds_bpermute_b32 v238, v244, v66
	ds_bpermute_b32 v239, v244, v67
	s_waitcnt lgkmcnt(0)
	global_store_dwordx2 v[236:237], v[238:239], off offset:8
	s_and_saveexec_b64 s[6:7], s[96:97]
	s_cbranch_execz .LBB0_1783
	v_mov_b64_e32 v[64:65], s[24:25]
	v_mad_i64_i32 v[64:65], s[58:59], v170, s76, v[64:65]
	v_lshl_add_u64 v[64:65], v[196:197], 2, v[64:65]
	global_store_dwordx4 v[64:65], v[60:63], off offset:16
	v_add_co_u32_e32 v64, vcc, 0x2000, v64
	s_nop 1
	v_addc_co_u32_e32 v65, vcc, 0, v65, vcc
	global_store_dwordx4 v[64:65], v[56:59], off offset:3088

; __device__ __forceinline__ unsigned pk2(float lo, float hi) { const f32x2 v = {lo, hi}; const bf16x2_t b = __builtin_convertvector(v, bf16x2_t); return __builtin_bit_cast(unsigned, b); }
; __device__ __forceinline__ f32x4 gelu_mul4(f32x4 x, f32x4 v) {
;     const f32x4 t = x * x;
;     const f32x4 u = t * (-2.0f * 0.7978845608028654f * 0.044715f * 1.4426950408889634f) + (-2.0f * 0.7978845608028654f * 1.4426950408889634f);
;     const f32x4 z = x * u;
;     f32x4 d; d[0] = __builtin_amdgcn_exp2f(z[0]); d[1] = __builtin_amdgcn_exp2f(z[1]); d[2] = __builtin_amdgcn_exp2f(z[2]); d[3] = __builtin_amdgcn_exp2f(z[3]);
;     d = d + 1.0f;
;     f32x4 r; r[0] = __builtin_amdgcn_rcpf(d[0]); r[1] = __builtin_amdgcn_rcpf(d[1]); r[2] = __builtin_amdgcn_rcpf(d[2]); r[3] = __builtin_amdgcn_rcpf(d[3]);
;     return (x * v) * r;
;     __device__ __forceinline__ void operator()(const f32x4 (&acc)[2][2][4][2], const pg8::Unit& u, int wr, int wc, int fr, int fq, PG8_LAS unsigned char* xl) const {
;     ...
;                         cc[bj] = bb[bj] + w0[bj] * p2 + w1[bj] * p1 + w2[bj] * cur;
;                     }
;                     const f32x4 gv = gelu_mul4(cc[0], cc[1]);
;                     u32x2 w; w.x = pk2(gv[0], gv[1]); w.y = pk2(gv[2], gv[3]);
;                     *(u32x2*)(G + (size_t)row * FF + jc0 + 4 * n) = w;
;                     if (!sample && ai == 0 && wr == 0 && m == 0 && fr < 2 && (pm & 7) != 0) {
; #pragma unroll
;                         for (int bj = 0; bj < 2; ++bj) *(f32x4*)(PH + (size_t)(pm * 2 + fr) * FF2 + bj * FF + jc0 + 4 * n) = cc[bj];
;                     }
;                     if (sample && (fr & 3) >= 2) { const int b = (row - MP) >> 2, t = fr & 3;
; #pragma unroll
;                         for (int bj = 0; bj < 2; ++bj) *(f32x4*)(nf_s + (size_t)(b * 2 + t - 2) * FF2 + bj * FF + jc0 + 4 * n) = acc[ai][bj][m][n];
;                     }
.LBB0_1791:
	v_pk_fma_f32 v[56:57], v[98:99], v[70:71], v[102:103]
	v_pk_fma_f32 v[58:59], v[96:97], v[68:69], v[100:101]
	v_pk_fma_f32 v[56:57], v[90:91], v[66:67], v[56:57]
	v_pk_fma_f32 v[58:59], v[88:89], v[64:65], v[58:59]
	v_pk_fma_f32 v[56:57], v[54:55], v[82:83], v[56:57]
	v_pk_fma_f32 v[58:59], v[52:53], v[80:81], v[58:59]
	v_pk_fma_f32 v[64:65], v[86:87], v[106:107], v[94:95]
	v_pk_fma_f32 v[66:67], v[84:85], v[104:105], v[92:93]
	v_pk_fma_f32 v[62:63], v[78:79], v[62:63], v[64:65]
	v_pk_fma_f32 v[60:61], v[76:77], v[60:61], v[66:67]
	v_pk_mul_f32 v[64:65], v[56:57], v[56:57]
	v_pk_mul_f32 v[66:67], v[58:59], v[58:59]
	v_mov_b64_e32 v[68:69], s[80:81]
	v_pk_fma_f32 v[64:65], v[64:65], s[82:83], v[68:69] op_sel_hi:[1,0,0]
	v_pk_fma_f32 v[66:67], v[66:67], s[82:83], v[68:69] op_sel_hi:[1,0,0]
	v_pk_mul_f32 v[64:65], v[56:57], v[64:65]
	v_pk_mul_f32 v[66:67], v[58:59], v[66:67]
	v_exp_f32_e32 v64, v64
	v_exp_f32_e32 v66, v66
	v_exp_f32_e32 v65, v65
	v_exp_f32_e32 v67, v67
	v_pk_fma_f32 v[62:63], v[50:51], v[74:75], v[62:63]
	v_pk_fma_f32 v[60:61], v[48:49], v[72:73], v[60:61]
	v_pk_add_f32 v[64:65], v[64:65], 1.0 op_sel_hi:[1,0]
	v_pk_add_f32 v[66:67], v[66:67], 1.0 op_sel_hi:[1,0]
	v_rcp_f32_e32 v64, v64
	v_rcp_f32_e32 v66, v66
	v_rcp_f32_e32 v65, v65
	v_rcp_f32_e32 v67, v67
	v_pk_mul_f32 v[56:57], v[56:57], v[62:63]
	v_pk_mul_f32 v[58:59], v[58:59], v[60:61]
	v_pk_mul_f32 v[56:57], v[56:57], v[64:65]
	v_pk_mul_f32 v[58:59], v[58:59], v[66:67]
	s_nop 0
	v_cvt_pk_bf16_f32 v58, v58, v59
	v_cvt_pk_bf16_f32 v59, v56, v57
	ds_bpermute_b32 v236, v244, v160
	ds_bpermute_b32 v237, v244, v161
	ds_bpermute_b32 v238, v244, v58
	ds_bpermute_b32 v239, v244, v59
	s_waitcnt lgkmcnt(0)
	global_store_dwordx2 v[236:237], v[238:239], off offset:8
	s_and_saveexec_b64 s[6:7], s[96:97]
	s_cbranch_execz .LBB0_1793
	v_mov_b64_e32 v[56:57], s[24:25]
	v_mad_i64_i32 v[56:57], s[58:59], v162, s76, v[56:57]
	v_lshl_add_u64 v[56:57], v[196:197], 2, v[56:57]
	global_store_dwordx4 v[56:57], v[52:55], off offset:16
	v_add_co_u32_e32 v56, vcc, 0x2000, v56
	s_nop 1
	v_addc_co_u32_e32 v57, vcc, 0, v57, vcc
	global_store_dwordx4 v[56:57], v[48:51], off offset:3088

; __device__ __forceinline__ unsigned pk2(float lo, float hi) { const f32x2 v = {lo, hi}; const bf16x2_t b = __builtin_convertvector(v, bf16x2_t); return __builtin_bit_cast(unsigned, b); }
; __device__ __forceinline__ f32x4 gelu_mul4(f32x4 x, f32x4 v) {
;     const f32x4 t = x * x;
;     const f32x4 u = t * (-2.0f * 0.7978845608028654f * 0.044715f * 1.4426950408889634f) + (-2.0f * 0.7978845608028654f * 1.4426950408889634f);
;     const f32x4 z = x * u;
;     f32x4 d; d[0] = __builtin_amdgcn_exp2f(z[0]); d[1] = __builtin_amdgcn_exp2f(z[1]); d[2] = __builtin_amdgcn_exp2f(z[2]); d[3] = __builtin_amdgcn_exp2f(z[3]);
;     d = d + 1.0f;
;     f32x4 r; r[0] = __builtin_amdgcn_rcpf(d[0]); r[1] = __builtin_amdgcn_rcpf(d[1]); r[2] = __builtin_amdgcn_rcpf(d[2]); r[3] = __builtin_amdgcn_rcpf(d[3]);
;     return (x * v) * r;
;     __device__ __forceinline__ void operator()(const f32x4 (&acc)[2][2][4][2], const pg8::Unit& u, int wr, int wc, int fr, int fq, PG8_LAS unsigned char* xl) const {
;     ...
;                         cc[bj] = bb[bj] + w0[bj] * p2 + w1[bj] * p1 + w2[bj] * cur;
;                     }
;                     const f32x4 gv = gelu_mul4(cc[0], cc[1]);
;                     u32x2 w; w.x = pk2(gv[0], gv[1]); w.y = pk2(gv[2], gv[3]);
;                     *(u32x2*)(G + (size_t)row * FF + jc0 + 4 * n) = w;
;                     if (!sample && ai == 0 && wr == 0 && m == 0 && fr < 2 && (pm & 7) != 0) {
; #pragma unroll
;                         for (int bj = 0; bj < 2; ++bj) *(f32x4*)(PH + (size_t)(pm * 2 + fr) * FF2 + bj * FF + jc0 + 4 * n) = cc[bj];
;                     }
;                     if (sample && (fr & 3) >= 2) { const int b = (row - MP) >> 2, t = fr & 3;
; #pragma unroll
;                         for (int bj = 0; bj < 2; ++bj) *(f32x4*)(nf_s + (size_t)(b * 2 + t - 2) * FF2 + bj * FF + jc0 + 4 * n) = acc[ai][bj][m][n];
;                     }
.LBB0_1801:
	v_pk_fma_f32 v[48:49], v[98:99], v[62:63], v[102:103]
	v_pk_fma_f32 v[50:51], v[96:97], v[60:61], v[100:101]
	v_pk_fma_f32 v[48:49], v[90:91], v[58:59], v[48:49]
	v_pk_fma_f32 v[50:51], v[88:89], v[56:57], v[50:51]
	v_pk_fma_f32 v[48:49], v[46:47], v[82:83], v[48:49]
	v_pk_fma_f32 v[50:51], v[44:45], v[80:81], v[50:51]
	v_pk_fma_f32 v[56:57], v[86:87], v[66:67], v[94:95]
	v_pk_fma_f32 v[58:59], v[84:85], v[64:65], v[92:93]
	v_pk_fma_f32 v[54:55], v[78:79], v[54:55], v[56:57]
	v_pk_fma_f32 v[52:53], v[76:77], v[52:53], v[58:59]
	v_pk_mul_f32 v[56:57], v[48:49], v[48:49]
	v_pk_mul_f32 v[58:59], v[50:51], v[50:51]
	v_mov_b64_e32 v[60:61], s[80:81]
	v_pk_fma_f32 v[56:57], v[56:57], s[82:83], v[60:61] op_sel_hi:[1,0,0]
	v_pk_fma_f32 v[58:59], v[58:59], s[82:83], v[60:61] op_sel_hi:[1,0,0]
	v_pk_mul_f32 v[56:57], v[48:49], v[56:57]
	v_pk_mul_f32 v[58:59], v[50:51], v[58:59]
	v_exp_f32_e32 v56, v56
	v_exp_f32_e32 v58, v58
	v_exp_f32_e32 v57, v57
	v_exp_f32_e32 v59, v59
	v_pk_fma_f32 v[54:55], v[42:43], v[74:75], v[54:55]
	v_pk_fma_f32 v[52:53], v[40:41], v[72:73], v[52:53]
	v_pk_add_f32 v[56:57], v[56:57], 1.0 op_sel_hi:[1,0]
	v_pk_add_f32 v[58:59], v[58:59], 1.0 op_sel_hi:[1,0]
	v_rcp_f32_e32 v56, v56
	v_rcp_f32_e32 v58, v58
	v_rcp_f32_e32 v57, v57
	v_rcp_f32_e32 v59, v59
	v_pk_mul_f32 v[48:49], v[48:49], v[54:55]
	v_pk_mul_f32 v[50:51], v[50:51], v[52:53]
	v_pk_mul_f32 v[48:49], v[48:49], v[56:57]
	v_pk_mul_f32 v[50:51], v[50:51], v[58:59]
	s_nop 0
	v_cvt_pk_bf16_f32 v50, v50, v51
	v_cvt_pk_bf16_f32 v51, v48, v49
	ds_bpermute_b32 v236, v244, v152
	ds_bpermute_b32 v237, v244, v153
	ds_bpermute_b32 v238, v244, v50
	ds_bpermute_b32 v239, v244, v51
	s_waitcnt lgkmcnt(0)
	global_store_dwordx2 v[236:237], v[238:239], off offset:8
	s_and_saveexec_b64 s[6:7], s[96:97]
	s_cbranch_execz .LBB0_1803
	v_mov_b64_e32 v[48:49], s[24:25]
	v_mad_i64_i32 v[48:49], s[58:59], v154, s76, v[48:49]
	v_lshl_add_u64 v[48:49], v[196:197], 2, v[48:49]
	global_store_dwordx4 v[48:49], v[44:47], off offset:16
	s_nop 1
	v_add_co_u32_e32 v44, vcc, 0x2000, v48
	s_nop 1
	v_addc_co_u32_e32 v45, vcc, 0, v49, vcc
	global_store_dwordx4 v[44:45], v[40:43], off offset:3088

; __device__ __forceinline__ unsigned pk2(float lo, float hi) { const f32x2 v = {lo, hi}; const bf16x2_t b = __builtin_convertvector(v, bf16x2_t); return __builtin_bit_cast(unsigned, b); }
; __device__ __forceinline__ f32x4 gelu_mul4(f32x4 x, f32x4 v) {
;     const f32x4 t = x * x;
;     const f32x4 u = t * (-2.0f * 0.7978845608028654f * 0.044715f * 1.4426950408889634f) + (-2.0f * 0.7978845608028654f * 1.4426950408889634f);
;     const f32x4 z = x * u;
;     f32x4 d; d[0] = __builtin_amdgcn_exp2f(z[0]); d[1] = __builtin_amdgcn_exp2f(z[1]); d[2] = __builtin_amdgcn_exp2f(z[2]); d[3] = __builtin_amdgcn_exp2f(z[3]);
;     d = d + 1.0f;
;     f32x4 r; r[0] = __builtin_amdgcn_rcpf(d[0]); r[1] = __builtin_amdgcn_rcpf(d[1]); r[2] = __builtin_amdgcn_rcpf(d[2]); r[3] = __builtin_amdgcn_rcpf(d[3]);
;     return (x * v) * r;
;     __device__ __forceinline__ void operator()(const f32x4 (&acc)[2][2][4][2], const pg8::Unit& u, int wr, int wc, int fr, int fq, PG8_LAS unsigned char* xl) const {
;     ...
;                         cc[bj] = bb[bj] + w0[bj] * p2 + w1[bj] * p1 + w2[bj] * cur;
;                     }
;                     const f32x4 gv = gelu_mul4(cc[0], cc[1]);
;                     u32x2 w; w.x = pk2(gv[0], gv[1]); w.y = pk2(gv[2], gv[3]);
;                     *(u32x2*)(G + (size_t)row * FF + jc0 + 4 * n) = w;
;                     if (!sample && ai == 0 && wr == 0 && m == 0 && fr < 2 && (pm & 7) != 0) {
; #pragma unroll
;                         for (int bj = 0; bj < 2; ++bj) *(f32x4*)(PH + (size_t)(pm * 2 + fr) * FF2 + bj * FF + jc0 + 4 * n) = cc[bj];
;                     }
;                     if (sample && (fr & 3) >= 2) { const int b = (row - MP) >> 2, t = fr & 3;
; #pragma unroll
;                         for (int bj = 0; bj < 2; ++bj) *(f32x4*)(nf_s + (size_t)(b * 2 + t - 2) * FF2 + bj * FF + jc0 + 4 * n) = acc[ai][bj][m][n];
;                     }
.LBB0_1813:
	s_waitcnt lgkmcnt(0)
	v_pk_fma_f32 v[40:41], v[98:99], v[50:51], v[102:103]
	v_pk_fma_f32 v[42:43], v[96:97], v[48:49], v[100:101]
	v_pk_fma_f32 v[40:41], v[90:91], v[46:47], v[40:41]
	v_pk_fma_f32 v[42:43], v[88:89], v[44:45], v[42:43]
	v_pk_fma_f32 v[40:41], v[38:39], v[82:83], v[40:41]
	v_pk_fma_f32 v[42:43], v[36:37], v[80:81], v[42:43]
	v_pk_fma_f32 v[46:47], v[84:85], v[56:57], v[92:93]
	v_pk_mul_f32 v[48:49], v[40:41], v[40:41]
	v_pk_fma_f32 v[46:47], v[76:77], v[52:53], v[46:47]
	v_pk_mul_f32 v[50:51], v[42:43], v[42:43]
	v_mov_b64_e32 v[52:53], s[80:81]
	v_pk_fma_f32 v[48:49], v[48:49], s[82:83], v[52:53] op_sel_hi:[1,0,0]
	v_pk_fma_f32 v[50:51], v[50:51], s[82:83], v[52:53] op_sel_hi:[1,0,0]
	v_pk_mul_f32 v[48:49], v[40:41], v[48:49]
	v_pk_mul_f32 v[50:51], v[42:43], v[50:51]
	v_exp_f32_e32 v48, v48
	v_exp_f32_e32 v50, v50
	v_exp_f32_e32 v49, v49
	v_exp_f32_e32 v51, v51
	v_pk_fma_f32 v[44:45], v[86:87], v[58:59], v[94:95]
	v_pk_fma_f32 v[46:47], v[32:33], v[72:73], v[46:47]
	v_pk_add_f32 v[48:49], v[48:49], 1.0 op_sel_hi:[1,0]
	v_pk_add_f32 v[50:51], v[50:51], 1.0 op_sel_hi:[1,0]
	v_rcp_f32_e32 v48, v48
	v_rcp_f32_e32 v50, v50
	v_rcp_f32_e32 v49, v49
	v_rcp_f32_e32 v51, v51
	v_pk_fma_f32 v[44:45], v[78:79], v[54:55], v[44:45]
	v_pk_mul_f32 v[42:43], v[42:43], v[46:47]
	v_pk_fma_f32 v[44:45], v[34:35], v[74:75], v[44:45]
	v_pk_mul_f32 v[42:43], v[42:43], v[50:51]
	v_pk_mul_f32 v[40:41], v[40:41], v[44:45]
	v_cvt_pk_bf16_f32 v42, v42, v43
	v_pk_mul_f32 v[40:41], v[40:41], v[48:49]
	s_nop 0
	v_cvt_pk_bf16_f32 v43, v40, v41
	ds_bpermute_b32 v236, v244, v144
	ds_bpermute_b32 v237, v244, v145
	ds_bpermute_b32 v238, v244, v42
	ds_bpermute_b32 v239, v244, v43
	s_waitcnt lgkmcnt(0)
	global_store_dwordx2 v[236:237], v[238:239], off offset:8
	s_and_saveexec_b64 s[6:7], s[96:97]
	s_cbranch_execz .LBB0_1815
	v_mov_b64_e32 v[40:41], s[24:25]
	v_mad_i64_i32 v[40:41], s[8:9], v146, s76, v[40:41]
	v_lshl_add_u64 v[40:41], v[196:197], 2, v[40:41]
	global_store_dwordx4 v[40:41], v[36:39], off offset:16
	v_add_co_u32_e32 v40, vcc, 0x2000, v40
	s_nop 1
	v_addc_co_u32_e32 v41, vcc, 0, v41, vcc
	global_store_dwordx4 v[40:41], v[32:35], off offset:3088

; __device__ __forceinline__ unsigned pk2(float lo, float hi) { const f32x2 v = {lo, hi}; const bf16x2_t b = __builtin_convertvector(v, bf16x2_t); return __builtin_bit_cast(unsigned, b); }
; __device__ __forceinline__ f32x4 gelu_mul4(f32x4 x, f32x4 v) {
;     const f32x4 t = x * x;
;     const f32x4 u = t * (-2.0f * 0.7978845608028654f * 0.044715f * 1.4426950408889634f) + (-2.0f * 0.7978845608028654f * 1.4426950408889634f);
;     const f32x4 z = x * u;
;     f32x4 d; d[0] = __builtin_amdgcn_exp2f(z[0]); d[1] = __builtin_amdgcn_exp2f(z[1]); d[2] = __builtin_amdgcn_exp2f(z[2]); d[3] = __builtin_amdgcn_exp2f(z[3]);
;     d = d + 1.0f;
;     f32x4 r; r[0] = __builtin_amdgcn_rcpf(d[0]); r[1] = __builtin_amdgcn_rcpf(d[1]); r[2] = __builtin_amdgcn_rcpf(d[2]); r[3] = __builtin_amdgcn_rcpf(d[3]);
;     return (x * v) * r;
;     __device__ __forceinline__ void operator()(const f32x4 (&acc)[2][2][4][2], const pg8::Unit& u, int wr, int wc, int fr, int fq, PG8_LAS unsigned char* xl) const {
;     ...
;                         cc[bj] = bb[bj] + w0[bj] * p2 + w1[bj] * p1 + w2[bj] * cur;
;                     }
;                     const f32x4 gv = gelu_mul4(cc[0], cc[1]);
;                     u32x2 w; w.x = pk2(gv[0], gv[1]); w.y = pk2(gv[2], gv[3]);
;                     *(u32x2*)(G + (size_t)row * FF + jc0 + 4 * n) = w;
;                     if (!sample && ai == 0 && wr == 0 && m == 0 && fr < 2 && (pm & 7) != 0) {
; #pragma unroll
;                         for (int bj = 0; bj < 2; ++bj) *(f32x4*)(PH + (size_t)(pm * 2 + fr) * FF2 + bj * FF + jc0 + 4 * n) = cc[bj];
;                     }
;                     if (sample && (fr & 3) >= 2) { const int b = (row - MP) >> 2, t = fr & 3;
; #pragma unroll
;                         for (int bj = 0; bj < 2; ++bj) *(f32x4*)(nf_s + (size_t)(b * 2 + t - 2) * FF2 + bj * FF + jc0 + 4 * n) = acc[ai][bj][m][n];
;                     }
.LBB0_1823:
	v_pk_fma_f32 v[32:33], v[98:99], v[46:47], v[102:103]
	v_pk_fma_f32 v[34:35], v[96:97], v[44:45], v[100:101]
	v_pk_fma_f32 v[32:33], v[90:91], v[42:43], v[32:33]
	v_pk_fma_f32 v[34:35], v[88:89], v[40:41], v[34:35]
	v_pk_fma_f32 v[32:33], v[30:31], v[82:83], v[32:33]
	v_pk_fma_f32 v[34:35], v[28:29], v[80:81], v[34:35]
	v_pk_fma_f32 v[40:41], v[86:87], v[50:51], v[94:95]
	v_pk_fma_f32 v[42:43], v[84:85], v[48:49], v[92:93]
	v_pk_fma_f32 v[38:39], v[78:79], v[38:39], v[40:41]
	v_pk_fma_f32 v[36:37], v[76:77], v[36:37], v[42:43]
	v_pk_mul_f32 v[40:41], v[32:33], v[32:33]
	v_pk_mul_f32 v[42:43], v[34:35], v[34:35]
	v_mov_b64_e32 v[44:45], s[80:81]
	v_pk_fma_f32 v[40:41], v[40:41], s[82:83], v[44:45] op_sel_hi:[1,0,0]
	v_pk_fma_f32 v[42:43], v[42:43], s[82:83], v[44:45] op_sel_hi:[1,0,0]
	v_pk_mul_f32 v[40:41], v[32:33], v[40:41]
	v_pk_mul_f32 v[42:43], v[34:35], v[42:43]
	v_exp_f32_e32 v40, v40
	v_exp_f32_e32 v42, v42
	v_exp_f32_e32 v41, v41
	v_exp_f32_e32 v43, v43
	v_pk_fma_f32 v[38:39], v[26:27], v[74:75], v[38:39]
	v_pk_fma_f32 v[36:37], v[24:25], v[72:73], v[36:37]
	v_pk_add_f32 v[40:41], v[40:41], 1.0 op_sel_hi:[1,0]
	v_pk_add_f32 v[42:43], v[42:43], 1.0 op_sel_hi:[1,0]
	v_rcp_f32_e32 v40, v40
	v_rcp_f32_e32 v42, v42
	v_rcp_f32_e32 v41, v41
	v_rcp_f32_e32 v43, v43
	v_pk_mul_f32 v[32:33], v[32:33], v[38:39]
	v_pk_mul_f32 v[34:35], v[34:35], v[36:37]
	v_pk_mul_f32 v[32:33], v[32:33], v[40:41]
	v_pk_mul_f32 v[34:35], v[34:35], v[42:43]
	s_nop 0
	v_cvt_pk_bf16_f32 v34, v34, v35
	v_cvt_pk_bf16_f32 v35, v32, v33
	ds_bpermute_b32 v236, v244, v136
	ds_bpermute_b32 v237, v244, v137
	ds_bpermute_b32 v238, v244, v34
	ds_bpermute_b32 v239, v244, v35
	s_waitcnt lgkmcnt(0)
	global_store_dwordx2 v[236:237], v[238:239], off offset:8
	s_and_saveexec_b64 s[6:7], s[96:97]
	s_cbranch_execz .LBB0_1825
	v_mov_b64_e32 v[32:33], s[24:25]
	v_mad_i64_i32 v[32:33], s[8:9], v138, s76, v[32:33]
	v_lshl_add_u64 v[32:33], v[196:197], 2, v[32:33]
	global_store_dwordx4 v[32:33], v[28:31], off offset:16
	v_add_co_u32_e32 v32, vcc, 0x2000, v32
	s_nop 1
	v_addc_co_u32_e32 v33, vcc, 0, v33, vcc
	global_store_dwordx4 v[32:33], v[24:27], off offset:3088

; __device__ __forceinline__ unsigned pk2(float lo, float hi) { const f32x2 v = {lo, hi}; const bf16x2_t b = __builtin_convertvector(v, bf16x2_t); return __builtin_bit_cast(unsigned, b); }
; __device__ __forceinline__ f32x4 gelu_mul4(f32x4 x, f32x4 v) {
;     const f32x4 t = x * x;
;     const f32x4 u = t * (-2.0f * 0.7978845608028654f * 0.044715f * 1.4426950408889634f) + (-2.0f * 0.7978845608028654f * 1.4426950408889634f);
;     const f32x4 z = x * u;
;     f32x4 d; d[0] = __builtin_amdgcn_exp2f(z[0]); d[1] = __builtin_amdgcn_exp2f(z[1]); d[2] = __builtin_amdgcn_exp2f(z[2]); d[3] = __builtin_amdgcn_exp2f(z[3]);
;     d = d + 1.0f;
;     f32x4 r; r[0] = __builtin_amdgcn_rcpf(d[0]); r[1] = __builtin_amdgcn_rcpf(d[1]); r[2] = __builtin_amdgcn_rcpf(d[2]); r[3] = __builtin_amdgcn_rcpf(d[3]);
;     return (x * v) * r;
;     __device__ __forceinline__ void operator()(const f32x4 (&acc)[2][2][4][2], const pg8::Unit& u, int wr, int wc, int fr, int fq, PG8_LAS unsigned char* xl) const {
;     ...
;                         cc[bj] = bb[bj] + w0[bj] * p2 + w1[bj] * p1 + w2[bj] * cur;
;                     }
;                     const f32x4 gv = gelu_mul4(cc[0], cc[1]);
;                     u32x2 w; w.x = pk2(gv[0], gv[1]); w.y = pk2(gv[2], gv[3]);
;                     *(u32x2*)(G + (size_t)row * FF + jc0 + 4 * n) = w;
;                     if (!sample && ai == 0 && wr == 0 && m == 0 && fr < 2 && (pm & 7) != 0) {
; #pragma unroll
;                         for (int bj = 0; bj < 2; ++bj) *(f32x4*)(PH + (size_t)(pm * 2 + fr) * FF2 + bj * FF + jc0 + 4 * n) = cc[bj];
;                     }
;                     if (sample && (fr & 3) >= 2) { const int b = (row - MP) >> 2, t = fr & 3;
; #pragma unroll
;                         for (int bj = 0; bj < 2; ++bj) *(f32x4*)(nf_s + (size_t)(b * 2 + t - 2) * FF2 + bj * FF + jc0 + 4 * n) = acc[ai][bj][m][n];
;                     }
.LBB0_1833:
	v_pk_fma_f32 v[24:25], v[98:99], v[38:39], v[102:103]
	v_pk_fma_f32 v[26:27], v[96:97], v[36:37], v[100:101]
	v_pk_fma_f32 v[24:25], v[90:91], v[34:35], v[24:25]
	v_pk_fma_f32 v[26:27], v[88:89], v[32:33], v[26:27]
	v_pk_fma_f32 v[24:25], v[22:23], v[82:83], v[24:25]
	v_pk_fma_f32 v[26:27], v[20:21], v[80:81], v[26:27]
	v_pk_fma_f32 v[32:33], v[86:87], v[42:43], v[94:95]
	v_pk_fma_f32 v[34:35], v[84:85], v[40:41], v[92:93]
	v_pk_fma_f32 v[30:31], v[78:79], v[30:31], v[32:33]
	v_pk_fma_f32 v[28:29], v[76:77], v[28:29], v[34:35]
	v_pk_mul_f32 v[32:33], v[24:25], v[24:25]
	v_pk_mul_f32 v[34:35], v[26:27], v[26:27]
	v_mov_b64_e32 v[36:37], s[80:81]
	v_pk_fma_f32 v[32:33], v[32:33], s[82:83], v[36:37] op_sel_hi:[1,0,0]
	v_pk_fma_f32 v[34:35], v[34:35], s[82:83], v[36:37] op_sel_hi:[1,0,0]
	v_pk_mul_f32 v[32:33], v[24:25], v[32:33]
	v_pk_mul_f32 v[34:35], v[26:27], v[34:35]
	v_exp_f32_e32 v32, v32
	v_exp_f32_e32 v34, v34
	v_exp_f32_e32 v33, v33
	v_exp_f32_e32 v35, v35
	v_pk_fma_f32 v[30:31], v[18:19], v[74:75], v[30:31]
	v_pk_fma_f32 v[28:29], v[16:17], v[72:73], v[28:29]
	v_pk_add_f32 v[32:33], v[32:33], 1.0 op_sel_hi:[1,0]
	v_pk_add_f32 v[34:35], v[34:35], 1.0 op_sel_hi:[1,0]
	v_rcp_f32_e32 v32, v32
	v_rcp_f32_e32 v34, v34
	v_rcp_f32_e32 v33, v33
	v_rcp_f32_e32 v35, v35
	v_pk_mul_f32 v[24:25], v[24:25], v[30:31]
	v_pk_mul_f32 v[26:27], v[26:27], v[28:29]
	v_pk_mul_f32 v[24:25], v[24:25], v[32:33]
	v_pk_mul_f32 v[26:27], v[26:27], v[34:35]
	s_nop 0
	v_cvt_pk_bf16_f32 v26, v26, v27
	v_cvt_pk_bf16_f32 v27, v24, v25
	ds_bpermute_b32 v236, v244, v128
	ds_bpermute_b32 v237, v244, v129
	ds_bpermute_b32 v238, v244, v26
	ds_bpermute_b32 v239, v244, v27
	s_waitcnt lgkmcnt(0)
	global_store_dwordx2 v[236:237], v[238:239], off offset:8
	s_and_saveexec_b64 s[6:7], s[96:97]
	s_cbranch_execz .LBB0_1835
	v_mov_b64_e32 v[24:25], s[24:25]
	v_mad_i64_i32 v[24:25], s[8:9], v139, s76, v[24:25]
	v_lshl_add_u64 v[24:25], v[196:197], 2, v[24:25]
	global_store_dwordx4 v[24:25], v[20:23], off offset:16
	v_add_co_u32_e32 v24, vcc, 0x2000, v24
	s_nop 1
	v_addc_co_u32_e32 v25, vcc, 0, v25, vcc
	global_store_dwordx4 v[24:25], v[16:19], off offset:3088

; __device__ __forceinline__ unsigned pk2(float lo, float hi) { const f32x2 v = {lo, hi}; const bf16x2_t b = __builtin_convertvector(v, bf16x2_t); return __builtin_bit_cast(unsigned, b); }
; __device__ __forceinline__ f32x4 gelu_mul4(f32x4 x, f32x4 v) {
;     const f32x4 t = x * x;
;     const f32x4 u = t * (-2.0f * 0.7978845608028654f * 0.044715f * 1.4426950408889634f) + (-2.0f * 0.7978845608028654f * 1.4426950408889634f);
;     const f32x4 z = x * u;
;     f32x4 d; d[0] = __builtin_amdgcn_exp2f(z[0]); d[1] = __builtin_amdgcn_exp2f(z[1]); d[2] = __builtin_amdgcn_exp2f(z[2]); d[3] = __builtin_amdgcn_exp2f(z[3]);
;     d = d + 1.0f;
;     f32x4 r; r[0] = __builtin_amdgcn_rcpf(d[0]); r[1] = __builtin_amdgcn_rcpf(d[1]); r[2] = __builtin_amdgcn_rcpf(d[2]); r[3] = __builtin_amdgcn_rcpf(d[3]);
;     return (x * v) * r;
;     __device__ __forceinline__ void operator()(const f32x4 (&acc)[2][2][4][2], const pg8::Unit& u, int wr, int wc, int fr, int fq, PG8_LAS unsigned char* xl) const {
;     ...
;                         cc[bj] = bb[bj] + w0[bj] * p2 + w1[bj] * p1 + w2[bj] * cur;
;                     }
;                     const f32x4 gv = gelu_mul4(cc[0], cc[1]);
;                     u32x2 w; w.x = pk2(gv[0], gv[1]); w.y = pk2(gv[2], gv[3]);
;                     *(u32x2*)(G + (size_t)row * FF + jc0 + 4 * n) = w;
;                     if (!sample && ai == 0 && wr == 0 && m == 0 && fr < 2 && (pm & 7) != 0) {
; #pragma unroll
;                         for (int bj = 0; bj < 2; ++bj) *(f32x4*)(PH + (size_t)(pm * 2 + fr) * FF2 + bj * FF + jc0 + 4 * n) = cc[bj];
;                     }
;                     if (sample && (fr & 3) >= 2) { const int b = (row - MP) >> 2, t = fr & 3;
; #pragma unroll
;                         for (int bj = 0; bj < 2; ++bj) *(f32x4*)(nf_s + (size_t)(b * 2 + t - 2) * FF2 + bj * FF + jc0 + 4 * n) = acc[ai][bj][m][n];
;                     }
.LBB0_1843:
	v_pk_fma_f32 v[16:17], v[98:99], v[30:31], v[102:103]
	v_pk_fma_f32 v[18:19], v[96:97], v[28:29], v[100:101]
	v_pk_fma_f32 v[16:17], v[90:91], v[26:27], v[16:17]
	v_pk_fma_f32 v[18:19], v[88:89], v[24:25], v[18:19]
	v_pk_fma_f32 v[16:17], v[10:11], v[82:83], v[16:17]
	v_pk_fma_f32 v[18:19], v[8:9], v[80:81], v[18:19]
	v_pk_fma_f32 v[24:25], v[86:87], v[34:35], v[94:95]
	v_pk_fma_f32 v[26:27], v[84:85], v[32:33], v[92:93]
	v_pk_fma_f32 v[22:23], v[78:79], v[22:23], v[24:25]
	v_pk_fma_f32 v[20:21], v[76:77], v[20:21], v[26:27]
	v_pk_mul_f32 v[24:25], v[16:17], v[16:17]
	v_pk_mul_f32 v[26:27], v[18:19], v[18:19]
	v_mov_b64_e32 v[28:29], s[80:81]
	v_pk_fma_f32 v[24:25], v[24:25], s[82:83], v[28:29] op_sel_hi:[1,0,0]
	v_pk_fma_f32 v[26:27], v[26:27], s[82:83], v[28:29] op_sel_hi:[1,0,0]
	v_pk_mul_f32 v[24:25], v[16:17], v[24:25]
	v_pk_mul_f32 v[26:27], v[18:19], v[26:27]
	v_exp_f32_e32 v24, v24
	v_exp_f32_e32 v26, v26
	v_exp_f32_e32 v25, v25
	v_exp_f32_e32 v27, v27
	v_pk_fma_f32 v[22:23], v[2:3], v[74:75], v[22:23]
	v_pk_fma_f32 v[20:21], v[0:1], v[72:73], v[20:21]
	v_pk_add_f32 v[24:25], v[24:25], 1.0 op_sel_hi:[1,0]
	v_pk_add_f32 v[26:27], v[26:27], 1.0 op_sel_hi:[1,0]
	v_rcp_f32_e32 v24, v24
	v_rcp_f32_e32 v26, v26
	v_rcp_f32_e32 v25, v25
	v_rcp_f32_e32 v27, v27
	v_pk_mul_f32 v[16:17], v[16:17], v[22:23]
	v_pk_mul_f32 v[18:19], v[18:19], v[20:21]
	v_pk_mul_f32 v[16:17], v[16:17], v[24:25]
	v_pk_mul_f32 v[18:19], v[18:19], v[26:27]
	s_nop 0
	v_cvt_pk_bf16_f32 v18, v18, v19
	v_cvt_pk_bf16_f32 v19, v16, v17
	ds_bpermute_b32 v236, v244, v130
	ds_bpermute_b32 v237, v244, v131
	ds_bpermute_b32 v238, v244, v18
	ds_bpermute_b32 v239, v244, v19
	s_waitcnt lgkmcnt(0)
	global_store_dwordx2 v[236:237], v[238:239], off offset:8
	s_and_saveexec_b64 s[6:7], s[96:97]
	s_cbranch_execz .LBB0_1845
	v_mov_b64_e32 v[16:17], s[24:25]
	v_mad_i64_i32 v[16:17], s[8:9], v147, s76, v[16:17]
	v_lshl_add_u64 v[16:17], v[196:197], 2, v[16:17]
	global_store_dwordx4 v[16:17], v[8:11], off offset:16
	v_add_co_u32_e32 v16, vcc, 0x2000, v16
	s_nop 1
	v_addc_co_u32_e32 v17, vcc, 0, v17, vcc
	global_store_dwordx4 v[16:17], v[0:3], off offset:3088

; __global__ void __launch_bounds__(512, 2) fwd_megakernel(Args a_unused) {
	.amdhsa_kernel _Z14fwd_megakernel4Args
		.amdhsa_group_segment_fixed_size 0
		.amdhsa_private_segment_fixed_size 0
		.amdhsa_kernarg_size 432
		.amdhsa_user_sgpr_count 2
		.amdhsa_user_sgpr_dispatch_ptr 0
		.amdhsa_user_sgpr_queue_ptr 0
		.amdhsa_user_sgpr_kernarg_segment_ptr 1
		.amdhsa_user_sgpr_dispatch_id 0
		.amdhsa_user_sgpr_kernarg_preload_length 0
		.amdhsa_user_sgpr_kernarg_preload_offset 0
		.amdhsa_user_sgpr_private_segment_size 0
		.amdhsa_uses_dynamic_stack 0
		.amdhsa_enable_private_segment 0
		.amdhsa_system_sgpr_workgroup_id_x 1
		.amdhsa_system_sgpr_workgroup_id_y 0
		.amdhsa_system_sgpr_workgroup_id_z 0
		.amdhsa_system_sgpr_workgroup_info 0
		.amdhsa_system_vgpr_workitem_id 2
		.amdhsa_next_free_vgpr 248
		.amdhsa_next_free_sgpr 98
		.amdhsa_accum_offset 248
		.amdhsa_reserve_vcc 1
		.amdhsa_float_round_mode_32 0
		.amdhsa_float_round_mode_16_64 0
		.amdhsa_float_denorm_mode_32 3
		.amdhsa_float_denorm_mode_16_64 3
		.amdhsa_dx10_clamp 1
		.amdhsa_ieee_mode 1
		.amdhsa_fp16_overflow 0
		.amdhsa_tg_split 0
		.amdhsa_exception_fp_ieee_invalid_op 0
		.amdhsa_exception_fp_denorm_src 0
		.amdhsa_exception_fp_ieee_div_zero 0
		.amdhsa_exception_fp_ieee_overflow 0
		.amdhsa_exception_fp_ieee_underflow 0
		.amdhsa_exception_fp_ieee_inexact 0
		.amdhsa_exception_int_div_zero 0
	.end_amdhsa_kernel

; __global__ void __launch_bounds__(512, 2) fwd_megakernel(Args a_unused) {
amdhsa.kernels:
  - .agpr_count:     0
    .args:
      - .offset:         0
        .size:           176
        .value_kind:     by_value
      - .offset:         176
        .size:           4
        .value_kind:     hidden_block_count_x
      - .offset:         180
        .size:           4
        .value_kind:     hidden_block_count_y
      - .offset:         184
        .size:           4
        .value_kind:     hidden_block_count_z
      - .offset:         188
        .size:           2
        .value_kind:     hidden_group_size_x
      - .offset:         190
        .size:           2
        .value_kind:     hidden_group_size_y
      - .offset:         192
        .size:           2
        .value_kind:     hidden_group_size_z
      - .offset:         194
        .size:           2
        .value_kind:     hidden_remainder_x
      - .offset:         196
        .size:           2
        .value_kind:     hidden_remainder_y
      - .offset:         198
        .size:           2
        .value_kind:     hidden_remainder_z
      - .offset:         216
        .size:           8
        .value_kind:     hidden_global_offset_x
      - .offset:         224
        .size:           8
        .value_kind:     hidden_global_offset_y
      - .offset:         232
        .size:           8
        .value_kind:     hidden_global_offset_z
      - .offset:         240
        .size:           2
        .value_kind:     hidden_grid_dims
      - .offset:         264
        .size:           8
        .value_kind:     hidden_multigrid_sync_arg
      - .offset:         296
        .size:           4
        .value_kind:     hidden_dynamic_lds_size
    .group_segment_fixed_size: 0
    .kernarg_segment_align: 8
    .kernarg_segment_size: 432
    .language:       OpenCL C
    .language_version:
      - 2
      - 0
    .max_flat_workgroup_size: 512
    .name:           _Z14fwd_megakernel4Args
    .private_segment_fixed_size: 0
    .sgpr_count:     104
    .sgpr_spill_count: 80
    .symbol:         _Z14fwd_megakernel4Args.kd
    .uniform_work_group_size: 1
    .uses_dynamic_stack: false
    .vgpr_count:     248
    .vgpr_spill_count: 0
    .wavefront_size: 64
